# v23 + per-phase s_setprio flips of the GEMM mainloops deleted (A/B per doc 6.3)
# speedup vs baseline: 1.0034x; 1.0019x over previous
; #define PG8_STAGE(bufoff, gbase, voff) do { _Pragma("unroll") for (int _i = 0; _i < 2; ++_i) \
;         __builtin_amdgcn_global_load_lds((const unsigned*)((const char*)(gbase) + (voff)[_i]), (LAS unsigned*)(lds + (bufoff) + ldsw + _i * 8192), 16, 0, 0); } while (0)
; #define PG8_LDA(dst, b, h) do { _Pragma("unroll") for (int m = 0; m < 4; ++m) _Pragma("unroll") for (int k = 0; k < 2; ++k) dst[m][k] = *(const LAS bf16x8*)(lds + PG8_SA(b, h) + aoff + m * 2048 + k * 1024); } while (0)
; #define PG8_LDB(dst, b, h) do { _Pragma("unroll") for (int n = 0; n < 2; ++n) _Pragma("unroll") for (int k = 0; k < 2; ++k) dst[n][k] = *(const LAS bf16x8*)(lds + PG8_SB(b, h) + boff + n * 2048 + k * 1024); } while (0)
; #define PG8_MMA(ai, bj, At, Bt) do { __builtin_amdgcn_s_setprio(1); _Pragma("unroll") for (int m = 0; m < 4; ++m) _Pragma("unroll") for (int n = 0; n < 2; ++n) _Pragma("unroll") for (int k = 0; k < 2; ++k) \
;         acc[ai][bj][m][n] = __builtin_amdgcn_mfma_f32_16x16x32_bf16(Bt[n][k], At[m][k], acc[ai][bj][m][n], 0, 0, 0); __builtin_amdgcn_s_setprio(0); } while (0)
; #define PG8_WAIT_V(n) asm volatile("s_waitcnt vmcnt(" #n ")" ::: "memory")
; #define PG8_WAIT_L(n) asm volatile("s_waitcnt lgkmcnt(" #n ")" ::: "memory")
; #define PG8_BAR __builtin_amdgcn_s_barrier()
; #define PG8_SCHED __builtin_amdgcn_sched_barrier(0)
; template <class GEO, class Epi>
; __device__ __forceinline__ void gemm_phase(LAS unsigned char* lds, const Gemm g, const StaticOrder& S, const Epi& E) {
;     ...
;             const bool last = (t == nt - 2);
;             const char* a1 = cA + (size_t)(t + 1) * kstep;
;             const char* a2 = last ? nA : cA + (size_t)(t + 2) * kstep; const char* b2 = last ? nB : cB + (size_t)(t + 2) * kstep;
;             const char* a3 = a2 + kstep; const char* b3 = b2 + kstep;
;             PG8_LDB(B0, 0, 0); PG8_LDB(B1, 0, 1); PG8_SCHED; PG8_LDA(At, 0, 0); PG8_STAGE(PG8_SA(1, 1), a1 + hstepA, voffA);
;             PG8_WAIT_V(8); PG8_WAIT_L(0); PG8_BAR; PG8_MMA(0, 0, At, B0); PG8_MMA(0, 1, At, B1); PG8_BAR; PG8_SCHED;
;             PG8_LDA(At, 0, 1); PG8_STAGE(PG8_SB(0, 0), b2, voffB); PG8_STAGE(PG8_SB(0, 1), b2 + hstepB, voffB); PG8_STAGE(PG8_SA(0, 0), a2, voffA);
;             PG8_WAIT_V(8); PG8_WAIT_L(0); PG8_BAR; PG8_MMA(1, 0, At, B0); PG8_MMA(1, 1, At, B1); PG8_BAR; PG8_SCHED;
.LBB0_165:
	ds_read_b128 v[120:123], v172
	ds_read_b128 v[124:127], v172 offset:1024
	ds_read_b128 v[156:159], v172 offset:2048
	ds_read_b128 v[186:189], v172 offset:3072
	ds_read_b128 v[190:193], v173
	ds_read_b128 v[194:197], v173 offset:1024
	ds_read_b128 v[198:201], v173 offset:2048
	ds_read_b128 v[202:205], v173 offset:3072
	s_add_u32 s39, s8, 0xfffc0080
	s_addc_u32 s51, s9, -1
	s_cmp_eq_u32 s38, 12
	s_cselect_b32 s93, s13, s51
	s_cselect_b32 s92, s20, s39
	s_cselect_b32 s89, s21, s35
	s_cselect_b32 s88, s22, s34
	v_lshl_add_u64 v[160:161], s[8:9], 0, v[148:149]
	s_add_i32 m0, s19, 0xc000
	ds_read_b128 v[210:213], v174
	ds_read_b128 v[214:217], v174 offset:1024
	ds_read_b128 v[218:221], v174 offset:2048
	ds_read_b128 v[222:225], v174 offset:3072
	ds_read_b128 v[226:229], v174 offset:4096
	ds_read_b128 v[230:233], v174 offset:5120
	ds_read_b128 v[234:237], v174 offset:6144
	ds_read_b128 v[238:241], v174 offset:7168
	global_load_lds_dwordx4 v[160:161], off
	v_lshl_add_u64 v[160:161], s[8:9], 0, v[150:151]
	s_add_i32 m0, s19, 0xe000
	s_nop 0
	global_load_lds_dwordx4 v[160:161], off
	s_waitcnt vmcnt(8)
	s_waitcnt lgkmcnt(0)
	s_barrier
	s_waitcnt lgkmcnt(0)
	v_mfma_f32_16x16x32_bf16 v[68:71], v[120:123], v[210:213], v[68:71]
	v_mfma_f32_16x16x32_bf16 v[64:67], v[156:159], v[210:213], v[64:67]
	v_mfma_f32_16x16x32_bf16 v[60:63], v[120:123], v[218:221], v[60:63]
	v_mfma_f32_16x16x32_bf16 v[56:59], v[156:159], v[218:221], v[56:59]
	v_mfma_f32_16x16x32_bf16 v[52:55], v[120:123], v[226:229], v[52:55]
	v_mfma_f32_16x16x32_bf16 v[48:51], v[156:159], v[226:229], v[48:51]
	v_mfma_f32_16x16x32_bf16 v[44:47], v[120:123], v[234:237], v[44:47]
	v_mfma_f32_16x16x32_bf16 v[40:43], v[156:159], v[234:237], v[40:43]
	v_mfma_f32_16x16x32_bf16 v[68:71], v[124:127], v[214:217], v[68:71]
	v_mfma_f32_16x16x32_bf16 v[64:67], v[186:189], v[214:217], v[64:67]
	v_mfma_f32_16x16x32_bf16 v[60:63], v[124:127], v[222:225], v[60:63]
	v_mfma_f32_16x16x32_bf16 v[56:59], v[186:189], v[222:225], v[56:59]
	v_mfma_f32_16x16x32_bf16 v[52:55], v[124:127], v[230:233], v[52:55]
	v_mfma_f32_16x16x32_bf16 v[48:51], v[186:189], v[230:233], v[48:51]
	v_mfma_f32_16x16x32_bf16 v[44:47], v[124:127], v[238:241], v[44:47]
	v_mfma_f32_16x16x32_bf16 v[40:43], v[186:189], v[238:241], v[40:43]
	v_mfma_f32_16x16x32_bf16 v[132:135], v[190:193], v[210:213], v[132:135]
	v_mfma_f32_16x16x32_bf16 v[128:131], v[198:201], v[210:213], v[128:131]
	v_mfma_f32_16x16x32_bf16 v[116:119], v[190:193], v[218:221], v[116:119]
	v_mfma_f32_16x16x32_bf16 v[112:115], v[198:201], v[218:221], v[112:115]
	v_mfma_f32_16x16x32_bf16 v[108:111], v[190:193], v[226:229], v[108:111]
	v_mfma_f32_16x16x32_bf16 v[104:107], v[198:201], v[226:229], v[104:107]
	v_mfma_f32_16x16x32_bf16 v[100:103], v[190:193], v[234:237], v[100:103]
	v_mfma_f32_16x16x32_bf16 v[96:99], v[198:201], v[234:237], v[96:99]
	v_mfma_f32_16x16x32_bf16 v[132:135], v[194:197], v[214:217], v[132:135]
	v_mfma_f32_16x16x32_bf16 v[128:131], v[202:205], v[214:217], v[128:131]
	v_mfma_f32_16x16x32_bf16 v[116:119], v[194:197], v[222:225], v[116:119]
	v_mfma_f32_16x16x32_bf16 v[112:115], v[202:205], v[222:225], v[112:115]
	v_mfma_f32_16x16x32_bf16 v[108:111], v[194:197], v[230:233], v[108:111]
	v_mfma_f32_16x16x32_bf16 v[104:107], v[202:205], v[230:233], v[104:107]
	v_mfma_f32_16x16x32_bf16 v[100:103], v[194:197], v[238:241], v[100:103]
	v_mfma_f32_16x16x32_bf16 v[96:99], v[202:205], v[238:241], v[96:99]
	s_barrier
	s_add_i32 s39, s87, s49
	v_lshl_add_u64 v[160:161], s[88:89], 0, v[140:141]
	s_mov_b32 m0, s39
	ds_read_b128 v[210:213], v174 offset:16384
	ds_read_b128 v[214:217], v174 offset:17408
	ds_read_b128 v[218:221], v174 offset:18432
	ds_read_b128 v[222:225], v174 offset:19456
	ds_read_b128 v[226:229], v174 offset:20480
	ds_read_b128 v[230:233], v174 offset:21504
	ds_read_b128 v[234:237], v174 offset:22528
	ds_read_b128 v[238:241], v174 offset:23552
	global_load_lds_dwordx4 v[160:161], off
	s_add_i32 m0, s39, 0x2000
	s_add_u32 s52, s88, 0x40000
	v_lshl_add_u64 v[242:243], s[88:89], 0, v[144:145]
	s_addc_u32 s53, s89, 0
	s_add_i32 s39, s90, s49
	global_load_lds_dwordx4 v[242:243], off
	v_lshl_add_u64 v[244:245], s[52:53], 0, v[140:141]
	s_mov_b32 m0, s39
	v_lshl_add_u64 v[246:247], s[92:93], 0, v[142:143]
	global_load_lds_dwordx4 v[244:245], off
	v_lshl_add_u64 v[244:245], s[52:53], 0, v[144:145]
	s_add_i32 m0, s39, 0x2000
	s_nop 0
	global_load_lds_dwordx4 v[244:245], off
	v_lshl_add_u64 v[244:245], s[92:93], 0, v[138:139]
	s_mov_b32 m0, s19
	s_nop 0
	global_load_lds_dwordx4 v[244:245], off
	s_mov_b32 m0, s55
	s_nop 0
	global_load_lds_dwordx4 v[246:247], off
	s_waitcnt vmcnt(8)
	s_waitcnt lgkmcnt(0)
	s_barrier
; #define PG8_STAGE(bufoff, gbase, voff) do { _Pragma("unroll") for (int _i = 0; _i < 2; ++_i) \
;         __builtin_amdgcn_global_load_lds((const unsigned*)((const char*)(gbase) + (voff)[_i]), (LAS unsigned*)(lds + (bufoff) + ldsw + _i * 8192), 16, 0, 0); } while (0)
; #define PG8_LDA(dst, b, h) do { _Pragma("unroll") for (int m = 0; m < 4; ++m) _Pragma("unroll") for (int k = 0; k < 2; ++k) dst[m][k] = *(const LAS bf16x8*)(lds + PG8_SA(b, h) + aoff + m * 2048 + k * 1024); } while (0)
; #define PG8_LDB(dst, b, h) do { _Pragma("unroll") for (int n = 0; n < 2; ++n) _Pragma("unroll") for (int k = 0; k < 2; ++k) dst[n][k] = *(const LAS bf16x8*)(lds + PG8_SB(b, h) + boff + n * 2048 + k * 1024); } while (0)
; #define PG8_MMA(ai, bj, At, Bt) do { __builtin_amdgcn_s_setprio(1); _Pragma("unroll") for (int m = 0; m < 4; ++m) _Pragma("unroll") for (int n = 0; n < 2; ++n) _Pragma("unroll") for (int k = 0; k < 2; ++k) \
;         acc[ai][bj][m][n] = __builtin_amdgcn_mfma_f32_16x16x32_bf16(Bt[n][k], At[m][k], acc[ai][bj][m][n], 0, 0, 0); __builtin_amdgcn_s_setprio(0); } while (0)
; #define PG8_WAIT_V(n) asm volatile("s_waitcnt vmcnt(" #n ")" ::: "memory")
; #define PG8_WAIT_L(n) asm volatile("s_waitcnt lgkmcnt(" #n ")" ::: "memory")
; #define PG8_BAR __builtin_amdgcn_s_barrier()
; #define PG8_SCHED __builtin_amdgcn_sched_barrier(0)
; template <class GEO, class Epi>
; __device__ __forceinline__ void gemm_phase(LAS unsigned char* lds, const Gemm g, const StaticOrder& S, const Epi& E) {
;     ...
;             PG8_WAIT_V(8); PG8_WAIT_L(0); PG8_BAR; PG8_MMA(1, 0, At, B0); PG8_MMA(1, 1, At, B1); PG8_BAR; PG8_SCHED;
;             PG8_LDB(B0, 1, 0); PG8_LDB(B1, 1, 1); PG8_SCHED; PG8_LDA(At, 1, 0); PG8_STAGE(PG8_SA(0, 1), a2 + hstepA, voffA);
;             PG8_WAIT_V(8); PG8_WAIT_L(0); PG8_BAR; PG8_MMA(0, 0, At, B0); PG8_MMA(0, 1, At, B1); PG8_BAR; PG8_SCHED;
	s_waitcnt lgkmcnt(0)
	v_mfma_f32_16x16x32_bf16 v[28:31], v[120:123], v[210:213], v[28:31]
	v_mfma_f32_16x16x32_bf16 v[24:27], v[156:159], v[210:213], v[24:27]
	v_mfma_f32_16x16x32_bf16 v[20:23], v[120:123], v[218:221], v[20:23]
	v_mfma_f32_16x16x32_bf16 v[16:19], v[156:159], v[218:221], v[16:19]
	v_mfma_f32_16x16x32_bf16 v[12:15], v[120:123], v[226:229], v[12:15]
	v_mfma_f32_16x16x32_bf16 v[8:11], v[156:159], v[226:229], v[8:11]
	v_mfma_f32_16x16x32_bf16 v[4:7], v[120:123], v[234:237], v[4:7]
	v_mfma_f32_16x16x32_bf16 v[0:3], v[156:159], v[234:237], v[0:3]
	v_mfma_f32_16x16x32_bf16 v[28:31], v[124:127], v[214:217], v[28:31]
	v_mfma_f32_16x16x32_bf16 v[24:27], v[186:189], v[214:217], v[24:27]
	v_mfma_f32_16x16x32_bf16 v[20:23], v[124:127], v[222:225], v[20:23]
	v_mfma_f32_16x16x32_bf16 v[16:19], v[186:189], v[222:225], v[16:19]
	v_mfma_f32_16x16x32_bf16 v[12:15], v[124:127], v[230:233], v[12:15]
	v_mfma_f32_16x16x32_bf16 v[8:11], v[186:189], v[230:233], v[8:11]
	v_mfma_f32_16x16x32_bf16 v[4:7], v[124:127], v[238:241], v[4:7]
	v_mfma_f32_16x16x32_bf16 v[0:3], v[186:189], v[238:241], v[0:3]
	v_mfma_f32_16x16x32_bf16 v[92:95], v[190:193], v[210:213], v[92:95]
	v_mfma_f32_16x16x32_bf16 v[88:91], v[198:201], v[210:213], v[88:91]
	v_mfma_f32_16x16x32_bf16 v[84:87], v[190:193], v[218:221], v[84:87]
	v_mfma_f32_16x16x32_bf16 v[80:83], v[198:201], v[218:221], v[80:83]
	v_mfma_f32_16x16x32_bf16 v[76:79], v[190:193], v[226:229], v[76:79]
	v_mfma_f32_16x16x32_bf16 v[72:75], v[198:201], v[226:229], v[72:75]
	v_mfma_f32_16x16x32_bf16 v[36:39], v[190:193], v[234:237], v[36:39]
	v_mfma_f32_16x16x32_bf16 v[32:35], v[198:201], v[234:237], v[32:35]
	v_mfma_f32_16x16x32_bf16 v[92:95], v[194:197], v[214:217], v[92:95]
	v_mfma_f32_16x16x32_bf16 v[88:91], v[202:205], v[214:217], v[88:91]
	v_mfma_f32_16x16x32_bf16 v[84:87], v[194:197], v[222:225], v[84:87]
	v_mfma_f32_16x16x32_bf16 v[80:83], v[202:205], v[222:225], v[80:83]
	v_mfma_f32_16x16x32_bf16 v[76:79], v[194:197], v[230:233], v[76:79]
	v_mfma_f32_16x16x32_bf16 v[72:75], v[202:205], v[230:233], v[72:75]
	v_mfma_f32_16x16x32_bf16 v[36:39], v[194:197], v[238:241], v[36:39]
	v_mfma_f32_16x16x32_bf16 v[32:35], v[202:205], v[238:241], v[32:35]
	s_barrier
	s_add_i32 s39, 0, 0x18000
	s_add_i32 s51, 0, 0x1c000
	v_add_u32_e32 v186, s39, v163
	v_add_u32_e32 v202, s51, v163
	ds_read_b128 v[120:123], v186
	ds_read_b128 v[124:127], v186 offset:1024
	ds_read_b128 v[156:159], v186 offset:2048
	ds_read_b128 v[186:189], v186 offset:3072
	ds_read_b128 v[190:193], v202
	ds_read_b128 v[194:197], v202 offset:1024
	ds_read_b128 v[198:201], v202 offset:2048
	ds_read_b128 v[202:205], v202 offset:3072
	s_add_u32 s52, s92, 0x40000
	s_addc_u32 s53, s93, 0
	s_mov_b32 m0, s58
	v_lshl_add_u64 v[248:249], s[52:53], 0, v[138:139]
	ds_read_b128 v[210:213], v174 offset:32768
	ds_read_b128 v[214:217], v174 offset:33792
	ds_read_b128 v[218:221], v174 offset:34816
	ds_read_b128 v[222:225], v174 offset:35840
	ds_read_b128 v[226:229], v174 offset:36864
	ds_read_b128 v[230:233], v174 offset:37888
	ds_read_b128 v[234:237], v174 offset:38912
	ds_read_b128 v[238:241], v174 offset:39936
	global_load_lds_dwordx4 v[248:249], off
	v_lshl_add_u64 v[248:249], s[52:53], 0, v[142:143]
	s_mov_b32 m0, s59
	s_nop 0
	global_load_lds_dwordx4 v[248:249], off
	s_waitcnt vmcnt(8)
	s_waitcnt lgkmcnt(0)
	s_barrier
	s_waitcnt lgkmcnt(0)
	v_mfma_f32_16x16x32_bf16 v[68:71], v[120:123], v[210:213], v[68:71]
	v_mfma_f32_16x16x32_bf16 v[64:67], v[156:159], v[210:213], v[64:67]
	v_mfma_f32_16x16x32_bf16 v[60:63], v[120:123], v[218:221], v[60:63]
	v_mfma_f32_16x16x32_bf16 v[56:59], v[156:159], v[218:221], v[56:59]
	v_mfma_f32_16x16x32_bf16 v[52:55], v[120:123], v[226:229], v[52:55]
	v_mfma_f32_16x16x32_bf16 v[48:51], v[156:159], v[226:229], v[48:51]
	v_mfma_f32_16x16x32_bf16 v[44:47], v[120:123], v[234:237], v[44:47]
	v_mfma_f32_16x16x32_bf16 v[40:43], v[156:159], v[234:237], v[40:43]
	v_mfma_f32_16x16x32_bf16 v[68:71], v[124:127], v[214:217], v[68:71]
	v_mfma_f32_16x16x32_bf16 v[64:67], v[186:189], v[214:217], v[64:67]
	v_mfma_f32_16x16x32_bf16 v[60:63], v[124:127], v[222:225], v[60:63]
	v_mfma_f32_16x16x32_bf16 v[56:59], v[186:189], v[222:225], v[56:59]
	v_mfma_f32_16x16x32_bf16 v[52:55], v[124:127], v[230:233], v[52:55]
	v_mfma_f32_16x16x32_bf16 v[48:51], v[186:189], v[230:233], v[48:51]
	v_mfma_f32_16x16x32_bf16 v[44:47], v[124:127], v[238:241], v[44:47]
	v_mfma_f32_16x16x32_bf16 v[40:43], v[186:189], v[238:241], v[40:43]
	v_mfma_f32_16x16x32_bf16 v[132:135], v[190:193], v[210:213], v[132:135]
	v_mfma_f32_16x16x32_bf16 v[128:131], v[198:201], v[210:213], v[128:131]
	v_mfma_f32_16x16x32_bf16 v[116:119], v[190:193], v[218:221], v[116:119]
	v_mfma_f32_16x16x32_bf16 v[112:115], v[198:201], v[218:221], v[112:115]
	v_mfma_f32_16x16x32_bf16 v[108:111], v[190:193], v[226:229], v[108:111]
	v_mfma_f32_16x16x32_bf16 v[104:107], v[198:201], v[226:229], v[104:107]
	v_mfma_f32_16x16x32_bf16 v[100:103], v[190:193], v[234:237], v[100:103]
	v_mfma_f32_16x16x32_bf16 v[96:99], v[198:201], v[234:237], v[96:99]
	v_mfma_f32_16x16x32_bf16 v[132:135], v[194:197], v[214:217], v[132:135]
	v_mfma_f32_16x16x32_bf16 v[128:131], v[202:205], v[214:217], v[128:131]
	v_mfma_f32_16x16x32_bf16 v[116:119], v[194:197], v[222:225], v[116:119]
	v_mfma_f32_16x16x32_bf16 v[112:115], v[202:205], v[222:225], v[112:115]
	v_mfma_f32_16x16x32_bf16 v[108:111], v[194:197], v[230:233], v[108:111]
	v_mfma_f32_16x16x32_bf16 v[104:107], v[202:205], v[230:233], v[104:107]
	v_mfma_f32_16x16x32_bf16 v[100:103], v[194:197], v[238:241], v[100:103]
	v_mfma_f32_16x16x32_bf16 v[96:99], v[202:205], v[238:241], v[96:99]
	s_barrier
; #define PG8_STAGE(bufoff, gbase, voff) do { _Pragma("unroll") for (int _i = 0; _i < 2; ++_i) \
;         __builtin_amdgcn_global_load_lds((const unsigned*)((const char*)(gbase) + (voff)[_i]), (LAS unsigned*)(lds + (bufoff) + ldsw + _i * 8192), 16, 0, 0); } while (0)
; #define PG8_LDA(dst, b, h) do { _Pragma("unroll") for (int m = 0; m < 4; ++m) _Pragma("unroll") for (int k = 0; k < 2; ++k) dst[m][k] = *(const LAS bf16x8*)(lds + PG8_SA(b, h) + aoff + m * 2048 + k * 1024); } while (0)
; #define PG8_MMA(ai, bj, At, Bt) do { __builtin_amdgcn_s_setprio(1); _Pragma("unroll") for (int m = 0; m < 4; ++m) _Pragma("unroll") for (int n = 0; n < 2; ++n) _Pragma("unroll") for (int k = 0; k < 2; ++k) \
;         acc[ai][bj][m][n] = __builtin_amdgcn_mfma_f32_16x16x32_bf16(Bt[n][k], At[m][k], acc[ai][bj][m][n], 0, 0, 0); __builtin_amdgcn_s_setprio(0); } while (0)
; #define PG8_WAIT_V(n) asm volatile("s_waitcnt vmcnt(" #n ")" ::: "memory")
; #define PG8_WAIT_L(n) asm volatile("s_waitcnt lgkmcnt(" #n ")" ::: "memory")
; #define PG8_BAR __builtin_amdgcn_s_barrier()
; #define PG8_SCHED __builtin_amdgcn_sched_barrier(0)
; template <class GEO, class Epi>
; __device__ __forceinline__ void gemm_phase(LAS unsigned char* lds, const Gemm g, const StaticOrder& S, const Epi& E) {
;     ...
;             PG8_LDA(At, 1, 1); PG8_STAGE(PG8_SB(1, 0), b3, voffB); PG8_STAGE(PG8_SB(1, 1), b3 + hstepB, voffB); PG8_STAGE(PG8_SA(1, 0), a3, voffA);
;             PG8_WAIT_V(8); PG8_WAIT_L(0); PG8_BAR; PG8_MMA(1, 0, At, B0); PG8_MMA(1, 1, At, B1); PG8_BAR; PG8_SCHED;
;         }
;         if (wr == 0) PG8_BAR;
	s_add_i32 s39, s39, s49
	v_lshl_add_u64 v[160:161], v[160:161], 0, s[42:43]
	s_mov_b32 m0, s39
	ds_read_b128 v[210:213], v174 offset:49152
	ds_read_b128 v[214:217], v174 offset:50176
	ds_read_b128 v[218:221], v174 offset:51200
	ds_read_b128 v[222:225], v174 offset:52224
	ds_read_b128 v[226:229], v174 offset:53248
	ds_read_b128 v[230:233], v174 offset:54272
	ds_read_b128 v[234:237], v174 offset:55296
	ds_read_b128 v[238:241], v174 offset:56320
	global_load_lds_dwordx4 v[160:161], off
	s_add_i32 m0, s39, 0x2000
	s_add_u32 s52, s88, 0x40080
	v_lshl_add_u64 v[160:161], v[242:243], 0, s[42:43]
	s_addc_u32 s53, s89, 0
	s_add_i32 s39, s51, s49
	global_load_lds_dwordx4 v[160:161], off
	v_lshl_add_u64 v[160:161], s[52:53], 0, v[140:141]
	s_mov_b32 m0, s39
	s_nop 0
	global_load_lds_dwordx4 v[160:161], off
	v_lshl_add_u64 v[160:161], s[52:53], 0, v[144:145]
	s_add_i32 m0, s39, 0x2000
	s_nop 0
	global_load_lds_dwordx4 v[160:161], off
	v_lshl_add_u64 v[160:161], v[244:245], 0, s[42:43]
	s_mov_b32 m0, s85
	s_nop 0
	global_load_lds_dwordx4 v[160:161], off
	v_lshl_add_u64 v[160:161], v[246:247], 0, s[42:43]
	s_mov_b32 m0, s86
	s_nop 0
	global_load_lds_dwordx4 v[160:161], off
	s_waitcnt vmcnt(8)
	s_waitcnt lgkmcnt(0)
	s_barrier
	s_waitcnt lgkmcnt(0)
	v_mfma_f32_16x16x32_bf16 v[28:31], v[120:123], v[210:213], v[28:31]
	v_mfma_f32_16x16x32_bf16 v[24:27], v[156:159], v[210:213], v[24:27]
	v_mfma_f32_16x16x32_bf16 v[20:23], v[120:123], v[218:221], v[20:23]
	v_mfma_f32_16x16x32_bf16 v[16:19], v[156:159], v[218:221], v[16:19]
	v_mfma_f32_16x16x32_bf16 v[12:15], v[120:123], v[226:229], v[12:15]
	v_mfma_f32_16x16x32_bf16 v[8:11], v[156:159], v[226:229], v[8:11]
	v_mfma_f32_16x16x32_bf16 v[4:7], v[120:123], v[234:237], v[4:7]
	v_mfma_f32_16x16x32_bf16 v[0:3], v[156:159], v[234:237], v[0:3]
	v_mfma_f32_16x16x32_bf16 v[28:31], v[124:127], v[214:217], v[28:31]
	v_mfma_f32_16x16x32_bf16 v[24:27], v[186:189], v[214:217], v[24:27]
	v_mfma_f32_16x16x32_bf16 v[20:23], v[124:127], v[222:225], v[20:23]
	v_mfma_f32_16x16x32_bf16 v[16:19], v[186:189], v[222:225], v[16:19]
	v_mfma_f32_16x16x32_bf16 v[12:15], v[124:127], v[230:233], v[12:15]
	v_mfma_f32_16x16x32_bf16 v[8:11], v[186:189], v[230:233], v[8:11]
	v_mfma_f32_16x16x32_bf16 v[4:7], v[124:127], v[238:241], v[4:7]
	v_mfma_f32_16x16x32_bf16 v[0:3], v[186:189], v[238:241], v[0:3]
	v_mfma_f32_16x16x32_bf16 v[92:95], v[190:193], v[210:213], v[92:95]
	v_mfma_f32_16x16x32_bf16 v[88:91], v[198:201], v[210:213], v[88:91]
	v_mfma_f32_16x16x32_bf16 v[84:87], v[190:193], v[218:221], v[84:87]
	v_mfma_f32_16x16x32_bf16 v[80:83], v[198:201], v[218:221], v[80:83]
	v_mfma_f32_16x16x32_bf16 v[76:79], v[190:193], v[226:229], v[76:79]
	v_mfma_f32_16x16x32_bf16 v[72:75], v[198:201], v[226:229], v[72:75]
	v_mfma_f32_16x16x32_bf16 v[36:39], v[190:193], v[234:237], v[36:39]
	v_mfma_f32_16x16x32_bf16 v[32:35], v[198:201], v[234:237], v[32:35]
	v_mfma_f32_16x16x32_bf16 v[92:95], v[194:197], v[214:217], v[92:95]
	v_mfma_f32_16x16x32_bf16 v[88:91], v[202:205], v[214:217], v[88:91]
	v_mfma_f32_16x16x32_bf16 v[84:87], v[194:197], v[222:225], v[84:87]
	v_mfma_f32_16x16x32_bf16 v[80:83], v[202:205], v[222:225], v[80:83]
	v_mfma_f32_16x16x32_bf16 v[76:79], v[194:197], v[230:233], v[76:79]
	v_mfma_f32_16x16x32_bf16 v[72:75], v[202:205], v[230:233], v[72:75]
	v_mfma_f32_16x16x32_bf16 v[36:39], v[194:197], v[238:241], v[36:39]
	v_mfma_f32_16x16x32_bf16 v[32:35], v[202:205], v[238:241], v[32:35]
	s_barrier
	s_add_i32 s38, s38, 2
	s_add_u32 s8, s8, 0x100
	s_addc_u32 s9, s9, 0
	s_add_u32 s34, s34, 0x100
	s_addc_u32 s35, s35, 0
	s_cmp_gt_u32 s38, 13
	s_cbranch_scc0 .LBB0_165
	s_and_b64 vcc, exec, s[44:45]
	s_cbranch_vccz .LBB0_168
	s_barrier

; #define PG8_STAGE(bufoff, gbase, voff) do { _Pragma("unroll") for (int _i = 0; _i < 2; ++_i) \
;         __builtin_amdgcn_global_load_lds((const unsigned*)((const char*)(gbase) + (voff)[_i]), (LAS unsigned*)(lds + (bufoff) + ldsw + _i * 8192), 16, 0, 0); } while (0)
; #define PG8_LDA(dst, b, h) do { _Pragma("unroll") for (int m = 0; m < 4; ++m) _Pragma("unroll") for (int k = 0; k < 2; ++k) dst[m][k] = *(const LAS bf16x8*)(lds + PG8_SA(b, h) + aoff + m * 2048 + k * 1024); } while (0)
; #define PG8_LDB(dst, b, h) do { _Pragma("unroll") for (int n = 0; n < 2; ++n) _Pragma("unroll") for (int k = 0; k < 2; ++k) dst[n][k] = *(const LAS bf16x8*)(lds + PG8_SB(b, h) + boff + n * 2048 + k * 1024); } while (0)
; #define PG8_MMA(ai, bj, At, Bt) do { __builtin_amdgcn_s_setprio(1); _Pragma("unroll") for (int m = 0; m < 4; ++m) _Pragma("unroll") for (int n = 0; n < 2; ++n) _Pragma("unroll") for (int k = 0; k < 2; ++k) \
;         acc[ai][bj][m][n] = __builtin_amdgcn_mfma_f32_16x16x32_bf16(Bt[n][k], At[m][k], acc[ai][bj][m][n], 0, 0, 0); __builtin_amdgcn_s_setprio(0); } while (0)
; #define PG8_WAIT_V(n) asm volatile("s_waitcnt vmcnt(" #n ")" ::: "memory")
; #define PG8_WAIT_L(n) asm volatile("s_waitcnt lgkmcnt(" #n ")" ::: "memory")
; #define PG8_BAR __builtin_amdgcn_s_barrier()
; #define PG8_SCHED __builtin_amdgcn_sched_barrier(0)
; template <class GEO, class Epi>
; __device__ __forceinline__ void gemm_phase(LAS unsigned char* lds, const Gemm g, const StaticOrder& S, const Epi& E) {
;     ...
;             const bool last = (t == nt - 2);
;             const char* a1 = cA + (size_t)(t + 1) * kstep;
;             const char* a2 = last ? nA : cA + (size_t)(t + 2) * kstep; const char* b2 = last ? nB : cB + (size_t)(t + 2) * kstep;
;             const char* a3 = a2 + kstep; const char* b3 = b2 + kstep;
;             PG8_LDB(B0, 0, 0); PG8_LDB(B1, 0, 1); PG8_SCHED; PG8_LDA(At, 0, 0); PG8_STAGE(PG8_SA(1, 1), a1 + hstepA, voffA);
;             PG8_WAIT_V(8); PG8_WAIT_L(0); PG8_BAR; PG8_MMA(0, 0, At, B0); PG8_MMA(0, 1, At, B1); PG8_BAR; PG8_SCHED;
;             PG8_LDA(At, 0, 1); PG8_STAGE(PG8_SB(0, 0), b2, voffB); PG8_STAGE(PG8_SB(0, 1), b2 + hstepB, voffB); PG8_STAGE(PG8_SA(0, 0), a2, voffA);
;             PG8_WAIT_V(8); PG8_WAIT_L(0); PG8_BAR; PG8_MMA(1, 0, At, B0); PG8_MMA(1, 1, At, B1); PG8_BAR; PG8_SCHED;
.LBB0_232:
	ds_read_b128 v[128:131], v163
	ds_read_b128 v[132:135], v163 offset:1024
	ds_read_b128 v[156:159], v163 offset:2048
	ds_read_b128 v[166:169], v163 offset:3072
	ds_read_b128 v[170:173], v164
	ds_read_b128 v[174:177], v164 offset:1024
	ds_read_b128 v[178:181], v164 offset:2048
	ds_read_b128 v[182:185], v164 offset:3072
	s_add_u32 s8, s64, 0xfffc0080
	s_addc_u32 s9, s65, -1
	s_cmp_eq_u32 vcc_hi, 12
	s_cselect_b32 s93, s47, s9
	s_cselect_b32 s92, s52, s8
	s_cselect_b32 s89, s6, vcc_lo
	s_cselect_b32 s88, s53, s57
	v_lshl_add_u64 v[222:223], s[64:65], 0, v[150:151]
	s_add_i32 m0, s79, 0xc000
	ds_read_b128 v[186:189], v165
	ds_read_b128 v[190:193], v165 offset:1024
	ds_read_b128 v[194:197], v165 offset:2048
	ds_read_b128 v[198:201], v165 offset:3072
	ds_read_b128 v[202:205], v165 offset:4096
	ds_read_b128 v[210:213], v165 offset:5120
	ds_read_b128 v[214:217], v165 offset:6144
	ds_read_b128 v[218:221], v165 offset:7168
	global_load_lds_dwordx4 v[222:223], off
	v_lshl_add_u64 v[222:223], s[64:65], 0, v[152:153]
	s_add_i32 m0, s79, 0xe000
	s_nop 0
	global_load_lds_dwordx4 v[222:223], off
	s_waitcnt vmcnt(8)
	s_waitcnt lgkmcnt(0)
	s_barrier
	s_waitcnt lgkmcnt(0)
	v_mfma_f32_16x16x32_bf16 v[124:127], v[128:131], v[186:189], v[124:127]
	v_mfma_f32_16x16x32_bf16 v[120:123], v[156:159], v[186:189], v[120:123]
	v_mfma_f32_16x16x32_bf16 v[116:119], v[128:131], v[194:197], v[116:119]
	v_mfma_f32_16x16x32_bf16 v[112:115], v[156:159], v[194:197], v[112:115]
	v_mfma_f32_16x16x32_bf16 v[100:103], v[128:131], v[202:205], v[100:103]
	v_mfma_f32_16x16x32_bf16 v[96:99], v[156:159], v[202:205], v[96:99]
	v_mfma_f32_16x16x32_bf16 v[84:87], v[128:131], v[214:217], v[84:87]
	v_mfma_f32_16x16x32_bf16 v[80:83], v[156:159], v[214:217], v[80:83]
	v_mfma_f32_16x16x32_bf16 v[124:127], v[132:135], v[190:193], v[124:127]
	v_mfma_f32_16x16x32_bf16 v[120:123], v[166:169], v[190:193], v[120:123]
	v_mfma_f32_16x16x32_bf16 v[116:119], v[132:135], v[198:201], v[116:119]
	v_mfma_f32_16x16x32_bf16 v[112:115], v[166:169], v[198:201], v[112:115]
	v_mfma_f32_16x16x32_bf16 v[100:103], v[132:135], v[210:213], v[100:103]
	v_mfma_f32_16x16x32_bf16 v[96:99], v[166:169], v[210:213], v[96:99]
	v_mfma_f32_16x16x32_bf16 v[84:87], v[132:135], v[218:221], v[84:87]
	v_mfma_f32_16x16x32_bf16 v[80:83], v[166:169], v[218:221], v[80:83]
	v_mfma_f32_16x16x32_bf16 v[108:111], v[170:173], v[186:189], v[108:111]
	v_mfma_f32_16x16x32_bf16 v[104:107], v[178:181], v[186:189], v[104:107]
	v_mfma_f32_16x16x32_bf16 v[92:95], v[170:173], v[194:197], v[92:95]
	v_mfma_f32_16x16x32_bf16 v[88:91], v[178:181], v[194:197], v[88:91]
	v_mfma_f32_16x16x32_bf16 v[76:79], v[170:173], v[202:205], v[76:79]
	v_mfma_f32_16x16x32_bf16 v[72:75], v[178:181], v[202:205], v[72:75]
	v_mfma_f32_16x16x32_bf16 v[68:71], v[170:173], v[214:217], v[68:71]
	v_mfma_f32_16x16x32_bf16 v[64:67], v[178:181], v[214:217], v[64:67]
	v_mfma_f32_16x16x32_bf16 v[108:111], v[174:177], v[190:193], v[108:111]
	v_mfma_f32_16x16x32_bf16 v[104:107], v[182:185], v[190:193], v[104:107]
	v_mfma_f32_16x16x32_bf16 v[92:95], v[174:177], v[198:201], v[92:95]
	v_mfma_f32_16x16x32_bf16 v[88:91], v[182:185], v[198:201], v[88:91]
	v_mfma_f32_16x16x32_bf16 v[76:79], v[174:177], v[210:213], v[76:79]
	v_mfma_f32_16x16x32_bf16 v[72:75], v[182:185], v[210:213], v[72:75]
	v_mfma_f32_16x16x32_bf16 v[68:71], v[174:177], v[218:221], v[68:71]
	v_mfma_f32_16x16x32_bf16 v[64:67], v[182:185], v[218:221], v[64:67]
	s_barrier
	s_add_i32 s8, s54, s55
	v_lshl_add_u64 v[222:223], s[88:89], 0, v[140:141]
	s_mov_b32 m0, s8
	ds_read_b128 v[186:189], v165 offset:16384
	ds_read_b128 v[190:193], v165 offset:17408
	ds_read_b128 v[194:197], v165 offset:18432
	ds_read_b128 v[198:201], v165 offset:19456
	ds_read_b128 v[202:205], v165 offset:20480
	ds_read_b128 v[210:213], v165 offset:21504
	ds_read_b128 v[214:217], v165 offset:22528
	ds_read_b128 v[218:221], v165 offset:23552
	global_load_lds_dwordx4 v[222:223], off
	s_add_i32 m0, s8, 0x2000
	s_add_u32 s8, s88, 0x40000
	v_lshl_add_u64 v[224:225], s[88:89], 0, v[144:145]
	s_addc_u32 s9, s89, 0
	s_add_i32 s83, s34, s55
	global_load_lds_dwordx4 v[224:225], off
	v_lshl_add_u64 v[226:227], s[8:9], 0, v[140:141]
	s_mov_b32 m0, s83
	v_lshl_add_u64 v[228:229], s[92:93], 0, v[142:143]
	global_load_lds_dwordx4 v[226:227], off
	v_lshl_add_u64 v[226:227], s[8:9], 0, v[144:145]
	s_add_i32 m0, s83, 0x2000
	s_nop 0
	global_load_lds_dwordx4 v[226:227], off
	v_lshl_add_u64 v[226:227], s[92:93], 0, v[138:139]
	s_mov_b32 m0, s79
	s_nop 0
	global_load_lds_dwordx4 v[226:227], off
	s_mov_b32 m0, s81
	s_nop 0
	global_load_lds_dwordx4 v[228:229], off
	s_waitcnt vmcnt(8)
	s_waitcnt lgkmcnt(0)
	s_barrier
; #define PG8_STAGE(bufoff, gbase, voff) do { _Pragma("unroll") for (int _i = 0; _i < 2; ++_i) \
;         __builtin_amdgcn_global_load_lds((const unsigned*)((const char*)(gbase) + (voff)[_i]), (LAS unsigned*)(lds + (bufoff) + ldsw + _i * 8192), 16, 0, 0); } while (0)
; #define PG8_LDA(dst, b, h) do { _Pragma("unroll") for (int m = 0; m < 4; ++m) _Pragma("unroll") for (int k = 0; k < 2; ++k) dst[m][k] = *(const LAS bf16x8*)(lds + PG8_SA(b, h) + aoff + m * 2048 + k * 1024); } while (0)
; #define PG8_LDB(dst, b, h) do { _Pragma("unroll") for (int n = 0; n < 2; ++n) _Pragma("unroll") for (int k = 0; k < 2; ++k) dst[n][k] = *(const LAS bf16x8*)(lds + PG8_SB(b, h) + boff + n * 2048 + k * 1024); } while (0)
; #define PG8_MMA(ai, bj, At, Bt) do { __builtin_amdgcn_s_setprio(1); _Pragma("unroll") for (int m = 0; m < 4; ++m) _Pragma("unroll") for (int n = 0; n < 2; ++n) _Pragma("unroll") for (int k = 0; k < 2; ++k) \
;         acc[ai][bj][m][n] = __builtin_amdgcn_mfma_f32_16x16x32_bf16(Bt[n][k], At[m][k], acc[ai][bj][m][n], 0, 0, 0); __builtin_amdgcn_s_setprio(0); } while (0)
; #define PG8_WAIT_V(n) asm volatile("s_waitcnt vmcnt(" #n ")" ::: "memory")
; #define PG8_WAIT_L(n) asm volatile("s_waitcnt lgkmcnt(" #n ")" ::: "memory")
; #define PG8_BAR __builtin_amdgcn_s_barrier()
; #define PG8_SCHED __builtin_amdgcn_sched_barrier(0)
; template <class GEO, class Epi>
; __device__ __forceinline__ void gemm_phase(LAS unsigned char* lds, const Gemm g, const StaticOrder& S, const Epi& E) {
;     ...
;             PG8_WAIT_V(8); PG8_WAIT_L(0); PG8_BAR; PG8_MMA(1, 0, At, B0); PG8_MMA(1, 1, At, B1); PG8_BAR; PG8_SCHED;
;             PG8_LDB(B0, 1, 0); PG8_LDB(B1, 1, 1); PG8_SCHED; PG8_LDA(At, 1, 0); PG8_STAGE(PG8_SA(0, 1), a2 + hstepA, voffA);
;             PG8_WAIT_V(8); PG8_WAIT_L(0); PG8_BAR; PG8_MMA(0, 0, At, B0); PG8_MMA(0, 1, At, B1); PG8_BAR; PG8_SCHED;
	s_waitcnt lgkmcnt(0)
	v_mfma_f32_16x16x32_bf16 v[60:63], v[128:131], v[186:189], v[60:63]
	v_mfma_f32_16x16x32_bf16 v[56:59], v[156:159], v[186:189], v[56:59]
	v_mfma_f32_16x16x32_bf16 v[52:55], v[128:131], v[194:197], v[52:55]
	v_mfma_f32_16x16x32_bf16 v[48:51], v[156:159], v[194:197], v[48:51]
	v_mfma_f32_16x16x32_bf16 v[36:39], v[128:131], v[202:205], v[36:39]
	v_mfma_f32_16x16x32_bf16 v[32:35], v[156:159], v[202:205], v[32:35]
	v_mfma_f32_16x16x32_bf16 v[20:23], v[128:131], v[214:217], v[20:23]
	v_mfma_f32_16x16x32_bf16 v[16:19], v[156:159], v[214:217], v[16:19]
	v_mfma_f32_16x16x32_bf16 v[60:63], v[132:135], v[190:193], v[60:63]
	v_mfma_f32_16x16x32_bf16 v[56:59], v[166:169], v[190:193], v[56:59]
	v_mfma_f32_16x16x32_bf16 v[52:55], v[132:135], v[198:201], v[52:55]
	v_mfma_f32_16x16x32_bf16 v[48:51], v[166:169], v[198:201], v[48:51]
	v_mfma_f32_16x16x32_bf16 v[36:39], v[132:135], v[210:213], v[36:39]
	v_mfma_f32_16x16x32_bf16 v[32:35], v[166:169], v[210:213], v[32:35]
	v_mfma_f32_16x16x32_bf16 v[20:23], v[132:135], v[218:221], v[20:23]
	v_mfma_f32_16x16x32_bf16 v[16:19], v[166:169], v[218:221], v[16:19]
	v_mfma_f32_16x16x32_bf16 v[44:47], v[170:173], v[186:189], v[44:47]
	v_mfma_f32_16x16x32_bf16 v[40:43], v[178:181], v[186:189], v[40:43]
	v_mfma_f32_16x16x32_bf16 v[28:31], v[170:173], v[194:197], v[28:31]
	v_mfma_f32_16x16x32_bf16 v[24:27], v[178:181], v[194:197], v[24:27]
	v_mfma_f32_16x16x32_bf16 v[12:15], v[170:173], v[202:205], v[12:15]
	v_mfma_f32_16x16x32_bf16 v[8:11], v[178:181], v[202:205], v[8:11]
	v_mfma_f32_16x16x32_bf16 v[4:7], v[170:173], v[214:217], v[4:7]
	v_mfma_f32_16x16x32_bf16 v[0:3], v[178:181], v[214:217], v[0:3]
	v_mfma_f32_16x16x32_bf16 v[44:47], v[174:177], v[190:193], v[44:47]
	v_mfma_f32_16x16x32_bf16 v[40:43], v[182:185], v[190:193], v[40:43]
	v_mfma_f32_16x16x32_bf16 v[28:31], v[174:177], v[198:201], v[28:31]
	v_mfma_f32_16x16x32_bf16 v[24:27], v[182:185], v[198:201], v[24:27]
	v_mfma_f32_16x16x32_bf16 v[12:15], v[174:177], v[210:213], v[12:15]
	v_mfma_f32_16x16x32_bf16 v[8:11], v[182:185], v[210:213], v[8:11]
	v_mfma_f32_16x16x32_bf16 v[4:7], v[174:177], v[218:221], v[4:7]
	v_mfma_f32_16x16x32_bf16 v[0:3], v[182:185], v[218:221], v[0:3]
	s_barrier
	s_add_i32 s83, 0, 0x18000
	v_add_u32_e32 v155, s83, v161
	s_add_i32 s0, 0, 0x1c000
	ds_read_b128 v[128:131], v155
	ds_read_b128 v[132:135], v155 offset:1024
	ds_read_b128 v[156:159], v155 offset:2048
	ds_read_b128 v[166:169], v155 offset:3072
	v_add_u32_e32 v155, s0, v161
	ds_read_b128 v[170:173], v155
	ds_read_b128 v[174:177], v155 offset:1024
	ds_read_b128 v[178:181], v155 offset:2048
	ds_read_b128 v[182:185], v155 offset:3072
	s_add_u32 s8, s92, 0x40000
	s_addc_u32 s9, s93, 0
	s_mov_b32 m0, s84
	v_lshl_add_u64 v[230:231], s[8:9], 0, v[138:139]
	ds_read_b128 v[186:189], v165 offset:32768
	ds_read_b128 v[190:193], v165 offset:33792
	ds_read_b128 v[194:197], v165 offset:34816
	ds_read_b128 v[198:201], v165 offset:35840
	ds_read_b128 v[202:205], v165 offset:36864
	ds_read_b128 v[210:213], v165 offset:37888
	ds_read_b128 v[214:217], v165 offset:38912
	ds_read_b128 v[218:221], v165 offset:39936
	global_load_lds_dwordx4 v[230:231], off
	v_lshl_add_u64 v[230:231], s[8:9], 0, v[142:143]
	s_mov_b32 m0, s85
	s_nop 0
	global_load_lds_dwordx4 v[230:231], off
	s_waitcnt vmcnt(8)
	s_waitcnt lgkmcnt(0)
	s_barrier
	s_waitcnt lgkmcnt(0)
	v_mfma_f32_16x16x32_bf16 v[124:127], v[128:131], v[186:189], v[124:127]
	v_mfma_f32_16x16x32_bf16 v[120:123], v[156:159], v[186:189], v[120:123]
	v_mfma_f32_16x16x32_bf16 v[116:119], v[128:131], v[194:197], v[116:119]
	v_mfma_f32_16x16x32_bf16 v[112:115], v[156:159], v[194:197], v[112:115]
	v_mfma_f32_16x16x32_bf16 v[100:103], v[128:131], v[202:205], v[100:103]
	v_mfma_f32_16x16x32_bf16 v[96:99], v[156:159], v[202:205], v[96:99]
	v_mfma_f32_16x16x32_bf16 v[84:87], v[128:131], v[214:217], v[84:87]
	v_mfma_f32_16x16x32_bf16 v[80:83], v[156:159], v[214:217], v[80:83]
	v_mfma_f32_16x16x32_bf16 v[124:127], v[132:135], v[190:193], v[124:127]
	v_mfma_f32_16x16x32_bf16 v[120:123], v[166:169], v[190:193], v[120:123]
	v_mfma_f32_16x16x32_bf16 v[116:119], v[132:135], v[198:201], v[116:119]
	v_mfma_f32_16x16x32_bf16 v[112:115], v[166:169], v[198:201], v[112:115]
	v_mfma_f32_16x16x32_bf16 v[100:103], v[132:135], v[210:213], v[100:103]
	v_mfma_f32_16x16x32_bf16 v[96:99], v[166:169], v[210:213], v[96:99]
	v_mfma_f32_16x16x32_bf16 v[84:87], v[132:135], v[218:221], v[84:87]
	v_mfma_f32_16x16x32_bf16 v[80:83], v[166:169], v[218:221], v[80:83]
	v_mfma_f32_16x16x32_bf16 v[108:111], v[170:173], v[186:189], v[108:111]
	v_mfma_f32_16x16x32_bf16 v[104:107], v[178:181], v[186:189], v[104:107]
	v_mfma_f32_16x16x32_bf16 v[92:95], v[170:173], v[194:197], v[92:95]
	v_mfma_f32_16x16x32_bf16 v[88:91], v[178:181], v[194:197], v[88:91]
	v_mfma_f32_16x16x32_bf16 v[76:79], v[170:173], v[202:205], v[76:79]
	v_mfma_f32_16x16x32_bf16 v[72:75], v[178:181], v[202:205], v[72:75]
	v_mfma_f32_16x16x32_bf16 v[68:71], v[170:173], v[214:217], v[68:71]
	v_mfma_f32_16x16x32_bf16 v[64:67], v[178:181], v[214:217], v[64:67]
	v_mfma_f32_16x16x32_bf16 v[108:111], v[174:177], v[190:193], v[108:111]
	v_mfma_f32_16x16x32_bf16 v[104:107], v[182:185], v[190:193], v[104:107]
	v_mfma_f32_16x16x32_bf16 v[92:95], v[174:177], v[198:201], v[92:95]
	v_mfma_f32_16x16x32_bf16 v[88:91], v[182:185], v[198:201], v[88:91]
	v_mfma_f32_16x16x32_bf16 v[76:79], v[174:177], v[210:213], v[76:79]
	v_mfma_f32_16x16x32_bf16 v[72:75], v[182:185], v[210:213], v[72:75]
	v_mfma_f32_16x16x32_bf16 v[68:71], v[174:177], v[218:221], v[68:71]
	v_mfma_f32_16x16x32_bf16 v[64:67], v[182:185], v[218:221], v[64:67]
	s_barrier
; #define PG8_STAGE(bufoff, gbase, voff) do { _Pragma("unroll") for (int _i = 0; _i < 2; ++_i) \
;         __builtin_amdgcn_global_load_lds((const unsigned*)((const char*)(gbase) + (voff)[_i]), (LAS unsigned*)(lds + (bufoff) + ldsw + _i * 8192), 16, 0, 0); } while (0)
; #define PG8_LDA(dst, b, h) do { _Pragma("unroll") for (int m = 0; m < 4; ++m) _Pragma("unroll") for (int k = 0; k < 2; ++k) dst[m][k] = *(const LAS bf16x8*)(lds + PG8_SA(b, h) + aoff + m * 2048 + k * 1024); } while (0)
; #define PG8_MMA(ai, bj, At, Bt) do { __builtin_amdgcn_s_setprio(1); _Pragma("unroll") for (int m = 0; m < 4; ++m) _Pragma("unroll") for (int n = 0; n < 2; ++n) _Pragma("unroll") for (int k = 0; k < 2; ++k) \
;         acc[ai][bj][m][n] = __builtin_amdgcn_mfma_f32_16x16x32_bf16(Bt[n][k], At[m][k], acc[ai][bj][m][n], 0, 0, 0); __builtin_amdgcn_s_setprio(0); } while (0)
; #define PG8_WAIT_V(n) asm volatile("s_waitcnt vmcnt(" #n ")" ::: "memory")
; #define PG8_WAIT_L(n) asm volatile("s_waitcnt lgkmcnt(" #n ")" ::: "memory")
; #define PG8_BAR __builtin_amdgcn_s_barrier()
; #define PG8_SCHED __builtin_amdgcn_sched_barrier(0)
; template <class GEO, class Epi>
; __device__ __forceinline__ void gemm_phase(LAS unsigned char* lds, const Gemm g, const StaticOrder& S, const Epi& E) {
;     ...
;             PG8_LDA(At, 1, 1); PG8_STAGE(PG8_SB(1, 0), b3, voffB); PG8_STAGE(PG8_SB(1, 1), b3 + hstepB, voffB); PG8_STAGE(PG8_SA(1, 0), a3, voffA);
;             PG8_WAIT_V(8); PG8_WAIT_L(0); PG8_BAR; PG8_MMA(1, 0, At, B0); PG8_MMA(1, 1, At, B1); PG8_BAR; PG8_SCHED;
;         }
;         if (wr == 0) PG8_BAR;
	s_add_i32 s1, s83, s55
	v_lshl_add_u64 v[222:223], v[222:223], 0, s[22:23]
	s_mov_b32 m0, s1
	ds_read_b128 v[186:189], v165 offset:49152
	ds_read_b128 v[190:193], v165 offset:50176
	ds_read_b128 v[194:197], v165 offset:51200
	ds_read_b128 v[198:201], v165 offset:52224
	ds_read_b128 v[202:205], v165 offset:53248
	ds_read_b128 v[210:213], v165 offset:54272
	ds_read_b128 v[214:217], v165 offset:55296
	ds_read_b128 v[218:221], v165 offset:56320
	global_load_lds_dwordx4 v[222:223], off
	s_add_i32 m0, s1, 0x2000
	s_add_u32 s8, s88, 0x40080
	v_lshl_add_u64 v[222:223], v[224:225], 0, s[22:23]
	s_addc_u32 s9, s89, 0
	s_add_i32 s0, s0, s55
	global_load_lds_dwordx4 v[222:223], off
	v_lshl_add_u64 v[222:223], s[8:9], 0, v[140:141]
	s_mov_b32 m0, s0
	s_nop 0
	global_load_lds_dwordx4 v[222:223], off
	v_lshl_add_u64 v[222:223], s[8:9], 0, v[144:145]
	s_add_i32 m0, s0, 0x2000
	s_nop 0
	global_load_lds_dwordx4 v[222:223], off
	v_lshl_add_u64 v[222:223], v[226:227], 0, s[22:23]
	s_mov_b32 m0, s86
	s_nop 0
	global_load_lds_dwordx4 v[222:223], off
	v_lshl_add_u64 v[222:223], v[228:229], 0, s[22:23]
	s_mov_b32 m0, s87
	s_nop 0
	global_load_lds_dwordx4 v[222:223], off
	s_waitcnt vmcnt(8)
	s_waitcnt lgkmcnt(0)
	s_barrier
	s_waitcnt lgkmcnt(0)
	v_mfma_f32_16x16x32_bf16 v[60:63], v[128:131], v[186:189], v[60:63]
	v_mfma_f32_16x16x32_bf16 v[56:59], v[156:159], v[186:189], v[56:59]
	v_mfma_f32_16x16x32_bf16 v[52:55], v[128:131], v[194:197], v[52:55]
	v_mfma_f32_16x16x32_bf16 v[48:51], v[156:159], v[194:197], v[48:51]
	v_mfma_f32_16x16x32_bf16 v[36:39], v[128:131], v[202:205], v[36:39]
	v_mfma_f32_16x16x32_bf16 v[32:35], v[156:159], v[202:205], v[32:35]
	v_mfma_f32_16x16x32_bf16 v[20:23], v[128:131], v[214:217], v[20:23]
	v_mfma_f32_16x16x32_bf16 v[16:19], v[156:159], v[214:217], v[16:19]
	v_mfma_f32_16x16x32_bf16 v[60:63], v[132:135], v[190:193], v[60:63]
	v_mfma_f32_16x16x32_bf16 v[56:59], v[166:169], v[190:193], v[56:59]
	v_mfma_f32_16x16x32_bf16 v[52:55], v[132:135], v[198:201], v[52:55]
	v_mfma_f32_16x16x32_bf16 v[48:51], v[166:169], v[198:201], v[48:51]
	v_mfma_f32_16x16x32_bf16 v[36:39], v[132:135], v[210:213], v[36:39]
	v_mfma_f32_16x16x32_bf16 v[32:35], v[166:169], v[210:213], v[32:35]
	v_mfma_f32_16x16x32_bf16 v[20:23], v[132:135], v[218:221], v[20:23]
	v_mfma_f32_16x16x32_bf16 v[16:19], v[166:169], v[218:221], v[16:19]
	v_mfma_f32_16x16x32_bf16 v[44:47], v[170:173], v[186:189], v[44:47]
	v_mfma_f32_16x16x32_bf16 v[40:43], v[178:181], v[186:189], v[40:43]
	v_mfma_f32_16x16x32_bf16 v[28:31], v[170:173], v[194:197], v[28:31]
	v_mfma_f32_16x16x32_bf16 v[24:27], v[178:181], v[194:197], v[24:27]
	v_mfma_f32_16x16x32_bf16 v[12:15], v[170:173], v[202:205], v[12:15]
	v_mfma_f32_16x16x32_bf16 v[8:11], v[178:181], v[202:205], v[8:11]
	v_mfma_f32_16x16x32_bf16 v[4:7], v[170:173], v[214:217], v[4:7]
	v_mfma_f32_16x16x32_bf16 v[0:3], v[178:181], v[214:217], v[0:3]
	v_mfma_f32_16x16x32_bf16 v[44:47], v[174:177], v[190:193], v[44:47]
	v_mfma_f32_16x16x32_bf16 v[40:43], v[182:185], v[190:193], v[40:43]
	v_mfma_f32_16x16x32_bf16 v[28:31], v[174:177], v[198:201], v[28:31]
	v_mfma_f32_16x16x32_bf16 v[24:27], v[182:185], v[198:201], v[24:27]
	v_mfma_f32_16x16x32_bf16 v[12:15], v[174:177], v[210:213], v[12:15]
	v_mfma_f32_16x16x32_bf16 v[8:11], v[182:185], v[210:213], v[8:11]
	v_mfma_f32_16x16x32_bf16 v[4:7], v[174:177], v[218:221], v[4:7]
	v_mfma_f32_16x16x32_bf16 v[0:3], v[182:185], v[218:221], v[0:3]
	s_barrier
	s_add_i32 vcc_hi, vcc_hi, 2
	s_add_u32 s64, s64, 0x100
	s_addc_u32 s65, s65, 0
	s_add_u32 s57, s57, 0x100
	s_addc_u32 vcc_lo, vcc_lo, 0
	s_cmp_gt_u32 vcc_hi, 13
	s_cbranch_scc0 .LBB0_232
	s_and_b64 vcc, exec, s[36:37]
	s_cbranch_vccz .LBB0_235
	s_barrier

; #define PG8_STAGE(bufoff, gbase, voff) do { _Pragma("unroll") for (int _i = 0; _i < 2; ++_i) \
;         __builtin_amdgcn_global_load_lds((const unsigned*)((const char*)(gbase) + (voff)[_i]), (LAS unsigned*)(lds + (bufoff) + ldsw + _i * 8192), 16, 0, 0); } while (0)
; #define PG8_LDA(dst, b, h) do { _Pragma("unroll") for (int m = 0; m < 4; ++m) _Pragma("unroll") for (int k = 0; k < 2; ++k) dst[m][k] = *(const LAS bf16x8*)(lds + PG8_SA(b, h) + aoff + m * 2048 + k * 1024); } while (0)
; #define PG8_LDB(dst, b, h) do { _Pragma("unroll") for (int n = 0; n < 2; ++n) _Pragma("unroll") for (int k = 0; k < 2; ++k) dst[n][k] = *(const LAS bf16x8*)(lds + PG8_SB(b, h) + boff + n * 2048 + k * 1024); } while (0)
; #define PG8_MMA(ai, bj, At, Bt) do { __builtin_amdgcn_s_setprio(1); _Pragma("unroll") for (int m = 0; m < 4; ++m) _Pragma("unroll") for (int n = 0; n < 2; ++n) _Pragma("unroll") for (int k = 0; k < 2; ++k) \
;         acc[ai][bj][m][n] = __builtin_amdgcn_mfma_f32_16x16x32_bf16(Bt[n][k], At[m][k], acc[ai][bj][m][n], 0, 0, 0); __builtin_amdgcn_s_setprio(0); } while (0)
; #define PG8_WAIT_V(n) asm volatile("s_waitcnt vmcnt(" #n ")" ::: "memory")
; #define PG8_WAIT_L(n) asm volatile("s_waitcnt lgkmcnt(" #n ")" ::: "memory")
; #define PG8_BAR __builtin_amdgcn_s_barrier()
; #define PG8_SCHED __builtin_amdgcn_sched_barrier(0)
; template <class GEO, class Epi>
; __device__ __forceinline__ void gemm_phase(LAS unsigned char* lds, const Gemm g, const StaticOrder& S, const Epi& E) {
;     ...
;         for (int t = 0; t < nt; t += 2) {
;             const bool last = (t == nt - 2);
;             const char* a1 = cA + (size_t)(t + 1) * kstep;
;             const char* a2 = last ? nA : cA + (size_t)(t + 2) * kstep; const char* b2 = last ? nB : cB + (size_t)(t + 2) * kstep;
;             const char* a3 = a2 + kstep; const char* b3 = b2 + kstep;
;             PG8_LDB(B0, 0, 0); PG8_LDB(B1, 0, 1); PG8_SCHED; PG8_LDA(At, 0, 0); PG8_STAGE(PG8_SA(1, 1), a1 + hstepA, voffA);
;             PG8_WAIT_V(8); PG8_WAIT_L(0); PG8_BAR; PG8_MMA(0, 0, At, B0); PG8_MMA(0, 1, At, B1); PG8_BAR; PG8_SCHED;
;             PG8_LDA(At, 0, 1); PG8_STAGE(PG8_SB(0, 0), b2, voffB); PG8_STAGE(PG8_SB(0, 1), b2 + hstepB, voffB); PG8_STAGE(PG8_SA(0, 0), a2, voffA);
;             PG8_WAIT_V(8); PG8_WAIT_L(0); PG8_BAR; PG8_MMA(1, 0, At, B0); PG8_MMA(1, 1, At, B1); PG8_BAR; PG8_SCHED;
.LBB0_425:
	s_add_u32 s54, s46, s64
	s_addc_u32 s55, s47, s65
	s_add_u32 s56, s54, 0x100
	s_addc_u32 s57, s55, 0
	s_and_b64 s[8:9], s[60:61], exec
	s_cselect_b32 s67, s39, s57
	s_cselect_b32 s66, s45, s56
	s_add_u32 s8, s40, s64
	s_addc_u32 s9, s41, s65
	s_add_u32 s56, s8, 0x100
	s_addc_u32 s57, s9, 0
	s_and_b64 s[8:9], s[60:61], exec
	s_cselect_b32 s69, s52, s57
	s_cselect_b32 s68, s53, s56
	s_add_u32 s72, s54, 0x40080
	ds_read_b128 v[142:145], v139
	ds_read_b128 v[146:149], v139 offset:1024
	ds_read_b128 v[150:153], v139 offset:2048
	ds_read_b128 v[154:157], v139 offset:3072
	ds_read_b128 v[158:161], v140
	ds_read_b128 v[166:169], v140 offset:1024
	ds_read_b128 v[170:173], v140 offset:2048
	ds_read_b128 v[174:177], v140 offset:3072
	s_addc_u32 s73, s55, 0
	s_add_i32 s8, s34, s4
	s_add_i32 m0, s5, 0xc000
	s_add_i32 s9, s5, 0xe000
	s_add_i32 s81, s8, 0x2000
	s_add_u32 s70, s68, 0x40000
	s_addc_u32 s71, s69, 0
	s_add_i32 s83, s35, s4
	s_add_i32 s82, s83, 0x2000
	s_add_i32 s79, 0, 0x18000
	s_add_i32 s78, 0, 0x1c000
	s_add_u32 s64, s66, 0x40000
	s_addc_u32 s65, s67, 0
	s_add_i32 s57, s79, s4
	s_add_i32 s55, s57, 0x2000
	s_add_u32 s60, s68, 0x40080
	s_addc_u32 s61, s69, 0
	s_add_i32 s56, s78, s4
	s_add_i32 s54, s56, 0x2000
	v_lshl_add_u64 v[214:215], s[72:73], 0, v[128:129]
	ds_read_b128 v[178:181], v141
	ds_read_b128 v[182:185], v141 offset:1024
	ds_read_b128 v[186:189], v141 offset:2048
	ds_read_b128 v[190:193], v141 offset:3072
	ds_read_b128 v[194:197], v141 offset:4096
	ds_read_b128 v[198:201], v141 offset:5120
	ds_read_b128 v[202:205], v141 offset:6144
	ds_read_b128 v[210:213], v141 offset:7168
	global_load_lds_dwordx4 v[214:215], off
	v_lshl_add_u64 v[214:215], s[72:73], 0, v[132:133]
	s_mov_b32 m0, s9
	s_nop 0
	global_load_lds_dwordx4 v[214:215], off
	s_waitcnt vmcnt(8)
	s_waitcnt lgkmcnt(0)
	s_barrier
	s_waitcnt lgkmcnt(0)
	v_mfma_f32_16x16x32_bf16 v[124:127], v[142:145], v[178:181], v[124:127]
	v_mfma_f32_16x16x32_bf16 v[120:123], v[150:153], v[178:181], v[120:123]
	v_mfma_f32_16x16x32_bf16 v[116:119], v[142:145], v[186:189], v[116:119]
	v_mfma_f32_16x16x32_bf16 v[112:115], v[150:153], v[186:189], v[112:115]
	v_mfma_f32_16x16x32_bf16 v[100:103], v[142:145], v[194:197], v[100:103]
	v_mfma_f32_16x16x32_bf16 v[96:99], v[150:153], v[194:197], v[96:99]
	v_mfma_f32_16x16x32_bf16 v[84:87], v[142:145], v[202:205], v[84:87]
	v_mfma_f32_16x16x32_bf16 v[80:83], v[150:153], v[202:205], v[80:83]
	v_mfma_f32_16x16x32_bf16 v[124:127], v[146:149], v[182:185], v[124:127]
	v_mfma_f32_16x16x32_bf16 v[120:123], v[154:157], v[182:185], v[120:123]
	v_mfma_f32_16x16x32_bf16 v[116:119], v[146:149], v[190:193], v[116:119]
	v_mfma_f32_16x16x32_bf16 v[112:115], v[154:157], v[190:193], v[112:115]
	v_mfma_f32_16x16x32_bf16 v[100:103], v[146:149], v[198:201], v[100:103]
	v_mfma_f32_16x16x32_bf16 v[96:99], v[154:157], v[198:201], v[96:99]
	v_mfma_f32_16x16x32_bf16 v[84:87], v[146:149], v[210:213], v[84:87]
	v_mfma_f32_16x16x32_bf16 v[80:83], v[154:157], v[210:213], v[80:83]
	v_mfma_f32_16x16x32_bf16 v[108:111], v[158:161], v[178:181], v[108:111]
	v_mfma_f32_16x16x32_bf16 v[104:107], v[170:173], v[178:181], v[104:107]
	v_mfma_f32_16x16x32_bf16 v[92:95], v[158:161], v[186:189], v[92:95]
	v_mfma_f32_16x16x32_bf16 v[88:91], v[170:173], v[186:189], v[88:91]
	v_mfma_f32_16x16x32_bf16 v[76:79], v[158:161], v[194:197], v[76:79]
	v_mfma_f32_16x16x32_bf16 v[72:75], v[170:173], v[194:197], v[72:75]
	v_mfma_f32_16x16x32_bf16 v[68:71], v[158:161], v[202:205], v[68:71]
	v_mfma_f32_16x16x32_bf16 v[64:67], v[170:173], v[202:205], v[64:67]
	v_mfma_f32_16x16x32_bf16 v[108:111], v[166:169], v[182:185], v[108:111]
	v_mfma_f32_16x16x32_bf16 v[104:107], v[174:177], v[182:185], v[104:107]
	v_mfma_f32_16x16x32_bf16 v[92:95], v[166:169], v[190:193], v[92:95]
	v_mfma_f32_16x16x32_bf16 v[88:91], v[174:177], v[190:193], v[88:91]
	v_mfma_f32_16x16x32_bf16 v[76:79], v[166:169], v[198:201], v[76:79]
	v_mfma_f32_16x16x32_bf16 v[72:75], v[174:177], v[198:201], v[72:75]
	v_mfma_f32_16x16x32_bf16 v[68:71], v[166:169], v[210:213], v[68:71]
	v_mfma_f32_16x16x32_bf16 v[64:67], v[174:177], v[210:213], v[64:67]
	s_barrier
	s_mov_b32 m0, s8
	v_lshl_add_u64 v[214:215], s[68:69], 0, v[130:131]
	ds_read_b128 v[178:181], v141 offset:16384
	ds_read_b128 v[182:185], v141 offset:17408
	ds_read_b128 v[186:189], v141 offset:18432
	ds_read_b128 v[190:193], v141 offset:19456
	ds_read_b128 v[194:197], v141 offset:20480
	ds_read_b128 v[198:201], v141 offset:21504
	ds_read_b128 v[202:205], v141 offset:22528
	ds_read_b128 v[210:213], v141 offset:23552
	global_load_lds_dwordx4 v[214:215], off
	v_lshl_add_u64 v[216:217], s[68:69], 0, v[134:135]
	s_mov_b32 m0, s81
	v_lshl_add_u64 v[218:219], s[70:71], 0, v[130:131]
	global_load_lds_dwordx4 v[216:217], off
	s_mov_b32 m0, s83
	v_lshl_add_u64 v[220:221], s[66:67], 0, v[132:133]
	global_load_lds_dwordx4 v[218:219], off
	v_lshl_add_u64 v[218:219], s[70:71], 0, v[134:135]
	s_mov_b32 m0, s82
	s_nop 0
	global_load_lds_dwordx4 v[218:219], off
	v_lshl_add_u64 v[218:219], s[66:67], 0, v[128:129]
	s_mov_b32 m0, s5
	s_nop 0
	global_load_lds_dwordx4 v[218:219], off
	s_mov_b32 m0, s6
	s_nop 0
	global_load_lds_dwordx4 v[220:221], off
	s_waitcnt vmcnt(8)
	s_waitcnt lgkmcnt(0)
	s_barrier
; #define PG8_STAGE(bufoff, gbase, voff) do { _Pragma("unroll") for (int _i = 0; _i < 2; ++_i) \
;         __builtin_amdgcn_global_load_lds((const unsigned*)((const char*)(gbase) + (voff)[_i]), (LAS unsigned*)(lds + (bufoff) + ldsw + _i * 8192), 16, 0, 0); } while (0)
; #define PG8_LDA(dst, b, h) do { _Pragma("unroll") for (int m = 0; m < 4; ++m) _Pragma("unroll") for (int k = 0; k < 2; ++k) dst[m][k] = *(const LAS bf16x8*)(lds + PG8_SA(b, h) + aoff + m * 2048 + k * 1024); } while (0)
; #define PG8_LDB(dst, b, h) do { _Pragma("unroll") for (int n = 0; n < 2; ++n) _Pragma("unroll") for (int k = 0; k < 2; ++k) dst[n][k] = *(const LAS bf16x8*)(lds + PG8_SB(b, h) + boff + n * 2048 + k * 1024); } while (0)
; #define PG8_MMA(ai, bj, At, Bt) do { __builtin_amdgcn_s_setprio(1); _Pragma("unroll") for (int m = 0; m < 4; ++m) _Pragma("unroll") for (int n = 0; n < 2; ++n) _Pragma("unroll") for (int k = 0; k < 2; ++k) \
;         acc[ai][bj][m][n] = __builtin_amdgcn_mfma_f32_16x16x32_bf16(Bt[n][k], At[m][k], acc[ai][bj][m][n], 0, 0, 0); __builtin_amdgcn_s_setprio(0); } while (0)
; #define PG8_WAIT_V(n) asm volatile("s_waitcnt vmcnt(" #n ")" ::: "memory")
; #define PG8_WAIT_L(n) asm volatile("s_waitcnt lgkmcnt(" #n ")" ::: "memory")
; #define PG8_BAR __builtin_amdgcn_s_barrier()
; #define PG8_SCHED __builtin_amdgcn_sched_barrier(0)
; template <class GEO, class Epi>
; __device__ __forceinline__ void gemm_phase(LAS unsigned char* lds, const Gemm g, const StaticOrder& S, const Epi& E) {
;     ...
;             PG8_WAIT_V(8); PG8_WAIT_L(0); PG8_BAR; PG8_MMA(1, 0, At, B0); PG8_MMA(1, 1, At, B1); PG8_BAR; PG8_SCHED;
;             PG8_LDB(B0, 1, 0); PG8_LDB(B1, 1, 1); PG8_SCHED; PG8_LDA(At, 1, 0); PG8_STAGE(PG8_SA(0, 1), a2 + hstepA, voffA);
;             PG8_WAIT_V(8); PG8_WAIT_L(0); PG8_BAR; PG8_MMA(0, 0, At, B0); PG8_MMA(0, 1, At, B1); PG8_BAR; PG8_SCHED;
	s_waitcnt lgkmcnt(0)
	v_mfma_f32_16x16x32_bf16 v[60:63], v[142:145], v[178:181], v[60:63]
	v_mfma_f32_16x16x32_bf16 v[56:59], v[150:153], v[178:181], v[56:59]
	v_mfma_f32_16x16x32_bf16 v[52:55], v[142:145], v[186:189], v[52:55]
	v_mfma_f32_16x16x32_bf16 v[48:51], v[150:153], v[186:189], v[48:51]
	v_mfma_f32_16x16x32_bf16 v[36:39], v[142:145], v[194:197], v[36:39]
	v_mfma_f32_16x16x32_bf16 v[32:35], v[150:153], v[194:197], v[32:35]
	v_mfma_f32_16x16x32_bf16 v[20:23], v[142:145], v[202:205], v[20:23]
	v_mfma_f32_16x16x32_bf16 v[16:19], v[150:153], v[202:205], v[16:19]
	v_mfma_f32_16x16x32_bf16 v[60:63], v[146:149], v[182:185], v[60:63]
	v_mfma_f32_16x16x32_bf16 v[56:59], v[154:157], v[182:185], v[56:59]
	v_mfma_f32_16x16x32_bf16 v[52:55], v[146:149], v[190:193], v[52:55]
	v_mfma_f32_16x16x32_bf16 v[48:51], v[154:157], v[190:193], v[48:51]
	v_mfma_f32_16x16x32_bf16 v[36:39], v[146:149], v[198:201], v[36:39]
	v_mfma_f32_16x16x32_bf16 v[32:35], v[154:157], v[198:201], v[32:35]
	v_mfma_f32_16x16x32_bf16 v[20:23], v[146:149], v[210:213], v[20:23]
	v_mfma_f32_16x16x32_bf16 v[16:19], v[154:157], v[210:213], v[16:19]
	v_mfma_f32_16x16x32_bf16 v[44:47], v[158:161], v[178:181], v[44:47]
	v_mfma_f32_16x16x32_bf16 v[40:43], v[170:173], v[178:181], v[40:43]
	v_mfma_f32_16x16x32_bf16 v[28:31], v[158:161], v[186:189], v[28:31]
	v_mfma_f32_16x16x32_bf16 v[24:27], v[170:173], v[186:189], v[24:27]
	v_mfma_f32_16x16x32_bf16 v[12:15], v[158:161], v[194:197], v[12:15]
	v_mfma_f32_16x16x32_bf16 v[8:11], v[170:173], v[194:197], v[8:11]
	v_mfma_f32_16x16x32_bf16 v[4:7], v[158:161], v[202:205], v[4:7]
	v_mfma_f32_16x16x32_bf16 v[0:3], v[170:173], v[202:205], v[0:3]
	v_mfma_f32_16x16x32_bf16 v[44:47], v[166:169], v[182:185], v[44:47]
	v_mfma_f32_16x16x32_bf16 v[40:43], v[174:177], v[182:185], v[40:43]
	v_mfma_f32_16x16x32_bf16 v[28:31], v[166:169], v[190:193], v[28:31]
	v_mfma_f32_16x16x32_bf16 v[24:27], v[174:177], v[190:193], v[24:27]
	v_mfma_f32_16x16x32_bf16 v[12:15], v[166:169], v[198:201], v[12:15]
	v_mfma_f32_16x16x32_bf16 v[8:11], v[174:177], v[198:201], v[8:11]
	v_mfma_f32_16x16x32_bf16 v[4:7], v[166:169], v[210:213], v[4:7]
	v_mfma_f32_16x16x32_bf16 v[0:3], v[174:177], v[210:213], v[0:3]
	s_barrier
	v_add_u32_e32 v154, s79, v137
	v_add_u32_e32 v174, s78, v137
	ds_read_b128 v[142:145], v154
	ds_read_b128 v[146:149], v154 offset:1024
	ds_read_b128 v[150:153], v154 offset:2048
	ds_read_b128 v[154:157], v154 offset:3072
	ds_read_b128 v[158:161], v174
	ds_read_b128 v[166:169], v174 offset:1024
	ds_read_b128 v[170:173], v174 offset:2048
	ds_read_b128 v[174:177], v174 offset:3072
	s_mov_b32 m0, s7
	v_lshl_add_u64 v[222:223], s[64:65], 0, v[128:129]
	ds_read_b128 v[178:181], v141 offset:32768
	ds_read_b128 v[182:185], v141 offset:33792
	ds_read_b128 v[186:189], v141 offset:34816
	ds_read_b128 v[190:193], v141 offset:35840
	ds_read_b128 v[194:197], v141 offset:36864
	ds_read_b128 v[198:201], v141 offset:37888
	ds_read_b128 v[202:205], v141 offset:38912
	ds_read_b128 v[210:213], v141 offset:39936
	global_load_lds_dwordx4 v[222:223], off
	v_lshl_add_u64 v[222:223], s[64:65], 0, v[132:133]
	s_mov_b32 m0, s12
	s_nop 0
	global_load_lds_dwordx4 v[222:223], off
	s_waitcnt vmcnt(8)
	s_waitcnt lgkmcnt(0)
	s_barrier
	s_waitcnt lgkmcnt(0)
	v_mfma_f32_16x16x32_bf16 v[124:127], v[142:145], v[178:181], v[124:127]
	v_mfma_f32_16x16x32_bf16 v[120:123], v[150:153], v[178:181], v[120:123]
	v_mfma_f32_16x16x32_bf16 v[116:119], v[142:145], v[186:189], v[116:119]
	v_mfma_f32_16x16x32_bf16 v[112:115], v[150:153], v[186:189], v[112:115]
	v_mfma_f32_16x16x32_bf16 v[100:103], v[142:145], v[194:197], v[100:103]
	v_mfma_f32_16x16x32_bf16 v[96:99], v[150:153], v[194:197], v[96:99]
	v_mfma_f32_16x16x32_bf16 v[84:87], v[142:145], v[202:205], v[84:87]
	v_mfma_f32_16x16x32_bf16 v[80:83], v[150:153], v[202:205], v[80:83]
	v_mfma_f32_16x16x32_bf16 v[124:127], v[146:149], v[182:185], v[124:127]
	v_mfma_f32_16x16x32_bf16 v[120:123], v[154:157], v[182:185], v[120:123]
	v_mfma_f32_16x16x32_bf16 v[116:119], v[146:149], v[190:193], v[116:119]
	v_mfma_f32_16x16x32_bf16 v[112:115], v[154:157], v[190:193], v[112:115]
	v_mfma_f32_16x16x32_bf16 v[100:103], v[146:149], v[198:201], v[100:103]
	v_mfma_f32_16x16x32_bf16 v[96:99], v[154:157], v[198:201], v[96:99]
	v_mfma_f32_16x16x32_bf16 v[84:87], v[146:149], v[210:213], v[84:87]
	v_mfma_f32_16x16x32_bf16 v[80:83], v[154:157], v[210:213], v[80:83]
	v_mfma_f32_16x16x32_bf16 v[108:111], v[158:161], v[178:181], v[108:111]
	v_mfma_f32_16x16x32_bf16 v[104:107], v[170:173], v[178:181], v[104:107]
	v_mfma_f32_16x16x32_bf16 v[92:95], v[158:161], v[186:189], v[92:95]
	v_mfma_f32_16x16x32_bf16 v[88:91], v[170:173], v[186:189], v[88:91]
	v_mfma_f32_16x16x32_bf16 v[76:79], v[158:161], v[194:197], v[76:79]
	v_mfma_f32_16x16x32_bf16 v[72:75], v[170:173], v[194:197], v[72:75]
	v_mfma_f32_16x16x32_bf16 v[68:71], v[158:161], v[202:205], v[68:71]
	v_mfma_f32_16x16x32_bf16 v[64:67], v[170:173], v[202:205], v[64:67]
	v_mfma_f32_16x16x32_bf16 v[108:111], v[166:169], v[182:185], v[108:111]
	v_mfma_f32_16x16x32_bf16 v[104:107], v[174:177], v[182:185], v[104:107]
	v_mfma_f32_16x16x32_bf16 v[92:95], v[166:169], v[190:193], v[92:95]
	v_mfma_f32_16x16x32_bf16 v[88:91], v[174:177], v[190:193], v[88:91]
	v_mfma_f32_16x16x32_bf16 v[76:79], v[166:169], v[198:201], v[76:79]
	v_mfma_f32_16x16x32_bf16 v[72:75], v[174:177], v[198:201], v[72:75]
	v_mfma_f32_16x16x32_bf16 v[68:71], v[166:169], v[210:213], v[68:71]
	v_mfma_f32_16x16x32_bf16 v[64:67], v[174:177], v[210:213], v[64:67]
	s_barrier
; #define PG8_STAGE(bufoff, gbase, voff) do { _Pragma("unroll") for (int _i = 0; _i < 2; ++_i) \
;         __builtin_amdgcn_global_load_lds((const unsigned*)((const char*)(gbase) + (voff)[_i]), (LAS unsigned*)(lds + (bufoff) + ldsw + _i * 8192), 16, 0, 0); } while (0)
; #define PG8_LDA(dst, b, h) do { _Pragma("unroll") for (int m = 0; m < 4; ++m) _Pragma("unroll") for (int k = 0; k < 2; ++k) dst[m][k] = *(const LAS bf16x8*)(lds + PG8_SA(b, h) + aoff + m * 2048 + k * 1024); } while (0)
; #define PG8_MMA(ai, bj, At, Bt) do { __builtin_amdgcn_s_setprio(1); _Pragma("unroll") for (int m = 0; m < 4; ++m) _Pragma("unroll") for (int n = 0; n < 2; ++n) _Pragma("unroll") for (int k = 0; k < 2; ++k) \
;         acc[ai][bj][m][n] = __builtin_amdgcn_mfma_f32_16x16x32_bf16(Bt[n][k], At[m][k], acc[ai][bj][m][n], 0, 0, 0); __builtin_amdgcn_s_setprio(0); } while (0)
; #define PG8_WAIT_V(n) asm volatile("s_waitcnt vmcnt(" #n ")" ::: "memory")
; #define PG8_WAIT_L(n) asm volatile("s_waitcnt lgkmcnt(" #n ")" ::: "memory")
; #define PG8_BAR __builtin_amdgcn_s_barrier()
; #define PG8_SCHED __builtin_amdgcn_sched_barrier(0)
; template <class GEO, class Epi>
; __device__ __forceinline__ void gemm_phase(LAS unsigned char* lds, const Gemm g, const StaticOrder& S, const Epi& E) {
;     ...
;             PG8_LDA(At, 1, 1); PG8_STAGE(PG8_SB(1, 0), b3, voffB); PG8_STAGE(PG8_SB(1, 1), b3 + hstepB, voffB); PG8_STAGE(PG8_SA(1, 0), a3, voffA);
;             PG8_WAIT_V(8); PG8_WAIT_L(0); PG8_BAR; PG8_MMA(1, 0, At, B0); PG8_MMA(1, 1, At, B1); PG8_BAR; PG8_SCHED;
;         }
;         if (wr == 0) PG8_BAR;
	s_mov_b32 m0, s57
	v_lshl_add_u64 v[214:215], v[214:215], 0, s[22:23]
	ds_read_b128 v[178:181], v141 offset:49152
	ds_read_b128 v[182:185], v141 offset:50176
	ds_read_b128 v[186:189], v141 offset:51200
	ds_read_b128 v[190:193], v141 offset:52224
	ds_read_b128 v[194:197], v141 offset:53248
	ds_read_b128 v[198:201], v141 offset:54272
	ds_read_b128 v[202:205], v141 offset:55296
	ds_read_b128 v[210:213], v141 offset:56320
	global_load_lds_dwordx4 v[214:215], off
	v_lshl_add_u64 v[214:215], v[216:217], 0, s[22:23]
	s_mov_b32 m0, s55
	s_nop 0
	global_load_lds_dwordx4 v[214:215], off
	v_lshl_add_u64 v[214:215], s[60:61], 0, v[130:131]
	s_mov_b32 m0, s56
	s_nop 0
	global_load_lds_dwordx4 v[214:215], off
	v_lshl_add_u64 v[214:215], s[60:61], 0, v[134:135]
	s_mov_b32 m0, s54
	s_nop 0
	global_load_lds_dwordx4 v[214:215], off
	v_lshl_add_u64 v[214:215], v[218:219], 0, s[22:23]
	s_mov_b32 m0, s18
	s_nop 0
	global_load_lds_dwordx4 v[214:215], off
	v_lshl_add_u64 v[214:215], v[220:221], 0, s[22:23]
	s_mov_b32 m0, s19
	s_nop 0
	global_load_lds_dwordx4 v[214:215], off
	s_waitcnt vmcnt(8)
	s_waitcnt lgkmcnt(0)
	s_barrier
	s_waitcnt lgkmcnt(0)
	v_mfma_f32_16x16x32_bf16 v[60:63], v[142:145], v[178:181], v[60:63]
	v_mfma_f32_16x16x32_bf16 v[56:59], v[150:153], v[178:181], v[56:59]
	v_mfma_f32_16x16x32_bf16 v[52:55], v[142:145], v[186:189], v[52:55]
	v_mfma_f32_16x16x32_bf16 v[48:51], v[150:153], v[186:189], v[48:51]
	v_mfma_f32_16x16x32_bf16 v[36:39], v[142:145], v[194:197], v[36:39]
	v_mfma_f32_16x16x32_bf16 v[32:35], v[150:153], v[194:197], v[32:35]
	v_mfma_f32_16x16x32_bf16 v[20:23], v[142:145], v[202:205], v[20:23]
	v_mfma_f32_16x16x32_bf16 v[16:19], v[150:153], v[202:205], v[16:19]
	v_mfma_f32_16x16x32_bf16 v[60:63], v[146:149], v[182:185], v[60:63]
	v_mfma_f32_16x16x32_bf16 v[56:59], v[154:157], v[182:185], v[56:59]
	v_mfma_f32_16x16x32_bf16 v[52:55], v[146:149], v[190:193], v[52:55]
	v_mfma_f32_16x16x32_bf16 v[48:51], v[154:157], v[190:193], v[48:51]
	v_mfma_f32_16x16x32_bf16 v[36:39], v[146:149], v[198:201], v[36:39]
	v_mfma_f32_16x16x32_bf16 v[32:35], v[154:157], v[198:201], v[32:35]
	v_mfma_f32_16x16x32_bf16 v[20:23], v[146:149], v[210:213], v[20:23]
	v_mfma_f32_16x16x32_bf16 v[16:19], v[154:157], v[210:213], v[16:19]
	v_mfma_f32_16x16x32_bf16 v[44:47], v[158:161], v[178:181], v[44:47]
	v_mfma_f32_16x16x32_bf16 v[40:43], v[170:173], v[178:181], v[40:43]
	v_mfma_f32_16x16x32_bf16 v[28:31], v[158:161], v[186:189], v[28:31]
	v_mfma_f32_16x16x32_bf16 v[24:27], v[170:173], v[186:189], v[24:27]
	v_mfma_f32_16x16x32_bf16 v[12:15], v[158:161], v[194:197], v[12:15]
	v_mfma_f32_16x16x32_bf16 v[8:11], v[170:173], v[194:197], v[8:11]
	v_mfma_f32_16x16x32_bf16 v[4:7], v[158:161], v[202:205], v[4:7]
	v_mfma_f32_16x16x32_bf16 v[0:3], v[170:173], v[202:205], v[0:3]
	v_mfma_f32_16x16x32_bf16 v[44:47], v[166:169], v[182:185], v[44:47]
	v_mfma_f32_16x16x32_bf16 v[40:43], v[174:177], v[182:185], v[40:43]
	v_mfma_f32_16x16x32_bf16 v[28:31], v[166:169], v[190:193], v[28:31]
	v_mfma_f32_16x16x32_bf16 v[24:27], v[174:177], v[190:193], v[24:27]
	v_mfma_f32_16x16x32_bf16 v[12:15], v[166:169], v[198:201], v[12:15]
	v_mfma_f32_16x16x32_bf16 v[8:11], v[174:177], v[198:201], v[8:11]
	v_mfma_f32_16x16x32_bf16 v[4:7], v[166:169], v[210:213], v[4:7]
	v_mfma_f32_16x16x32_bf16 v[0:3], v[174:177], v[210:213], v[0:3]
	s_barrier
	s_andn2_b64 vcc, exec, s[58:59]
	s_mov_b64 s[60:61], -1
	s_mov_b64 s[58:59], 0
	s_mov_b64 s[64:65], 0x100
	s_cbranch_vccz .LBB0_425
	s_and_b64 vcc, exec, s[30:31]
	s_cbranch_vccz .LBB0_428
	s_barrier

; #define PG8_STAGE(bufoff, gbase, voff) do { _Pragma("unroll") for (int _i = 0; _i < 2; ++_i) \
;         __builtin_amdgcn_global_load_lds((const unsigned*)((const char*)(gbase) + (voff)[_i]), (LAS unsigned*)(lds + (bufoff) + ldsw + _i * 8192), 16, 0, 0); } while (0)
; #define PG8_LDA(dst, b, h) do { _Pragma("unroll") for (int m = 0; m < 4; ++m) _Pragma("unroll") for (int k = 0; k < 2; ++k) dst[m][k] = *(const LAS bf16x8*)(lds + PG8_SA(b, h) + aoff + m * 2048 + k * 1024); } while (0)
; #define PG8_LDB(dst, b, h) do { _Pragma("unroll") for (int n = 0; n < 2; ++n) _Pragma("unroll") for (int k = 0; k < 2; ++k) dst[n][k] = *(const LAS bf16x8*)(lds + PG8_SB(b, h) + boff + n * 2048 + k * 1024); } while (0)
; #define PG8_MMA(ai, bj, At, Bt) do { __builtin_amdgcn_s_setprio(1); _Pragma("unroll") for (int m = 0; m < 4; ++m) _Pragma("unroll") for (int n = 0; n < 2; ++n) _Pragma("unroll") for (int k = 0; k < 2; ++k) \
;         acc[ai][bj][m][n] = __builtin_amdgcn_mfma_f32_16x16x32_bf16(Bt[n][k], At[m][k], acc[ai][bj][m][n], 0, 0, 0); __builtin_amdgcn_s_setprio(0); } while (0)
; #define PG8_WAIT_V(n) asm volatile("s_waitcnt vmcnt(" #n ")" ::: "memory")
; #define PG8_WAIT_L(n) asm volatile("s_waitcnt lgkmcnt(" #n ")" ::: "memory")
; #define PG8_BAR __builtin_amdgcn_s_barrier()
; #define PG8_SCHED __builtin_amdgcn_sched_barrier(0)
; template <class GEO, class Epi>
; __device__ __forceinline__ void gemm_phase(LAS unsigned char* lds, const Gemm g, const StaticOrder& S, const Epi& E) {
;     ...
;             const bool last = (t == nt - 2);
;             const char* a1 = cA + (size_t)(t + 1) * kstep;
;             const char* a2 = last ? nA : cA + (size_t)(t + 2) * kstep; const char* b2 = last ? nB : cB + (size_t)(t + 2) * kstep;
;             const char* a3 = a2 + kstep; const char* b3 = b2 + kstep;
;             PG8_LDB(B0, 0, 0); PG8_LDB(B1, 0, 1); PG8_SCHED; PG8_LDA(At, 0, 0); PG8_STAGE(PG8_SA(1, 1), a1 + hstepA, voffA);
;             PG8_WAIT_V(8); PG8_WAIT_L(0); PG8_BAR; PG8_MMA(0, 0, At, B0); PG8_MMA(0, 1, At, B1); PG8_BAR; PG8_SCHED;
;             PG8_LDA(At, 0, 1); PG8_STAGE(PG8_SB(0, 0), b2, voffB); PG8_STAGE(PG8_SB(0, 1), b2 + hstepB, voffB); PG8_STAGE(PG8_SA(0, 0), a2, voffA);
;             PG8_WAIT_V(8); PG8_WAIT_L(0); PG8_BAR; PG8_MMA(1, 0, At, B0); PG8_MMA(1, 1, At, B1); PG8_BAR; PG8_SCHED;
.LBB0_691:
	ds_read_b128 v[144:147], v152
	ds_read_b128 v[156:159], v152 offset:1024
	ds_read_b128 v[166:169], v152 offset:2048
	ds_read_b128 v[170:173], v152 offset:3072
	ds_read_b128 v[174:177], v153
	ds_read_b128 v[178:181], v153 offset:1024
	ds_read_b128 v[182:185], v153 offset:2048
	ds_read_b128 v[186:189], v153 offset:3072
	s_add_u32 s8, s54, 0xfffc0080
	s_addc_u32 s9, s55, -1
	s_cmp_eq_u32 s69, 12
	s_cselect_b32 s59, s21, s9
	s_cselect_b32 s58, s47, s8
	s_cselect_b32 s57, s22, s68
	s_cselect_b32 s56, s53, s67
	v_lshl_add_u64 v[160:161], s[54:55], 0, v[136:137]
	s_add_i32 m0, s1, 0xc000
	ds_read_b128 v[190:193], v154
	ds_read_b128 v[194:197], v154 offset:1024
	ds_read_b128 v[198:201], v154 offset:2048
	ds_read_b128 v[202:205], v154 offset:3072
	ds_read_b128 v[212:215], v154 offset:4096
	ds_read_b128 v[216:219], v154 offset:5120
	ds_read_b128 v[220:223], v154 offset:6144
	ds_read_b128 v[224:227], v154 offset:7168
	global_load_lds_dwordx4 v[160:161], off
	v_lshl_add_u64 v[160:161], s[54:55], 0, v[138:139]
	s_add_i32 m0, s1, 0xe000
	s_nop 0
	global_load_lds_dwordx4 v[160:161], off
	s_waitcnt vmcnt(8)
	s_waitcnt lgkmcnt(0)
	s_barrier
	s_waitcnt lgkmcnt(0)
	v_mfma_f32_16x16x32_bf16 v[124:127], v[144:147], v[190:193], v[124:127]
	v_mfma_f32_16x16x32_bf16 v[120:123], v[166:169], v[190:193], v[120:123]
	v_mfma_f32_16x16x32_bf16 v[108:111], v[144:147], v[198:201], v[108:111]
	v_mfma_f32_16x16x32_bf16 v[104:107], v[166:169], v[198:201], v[104:107]
	v_mfma_f32_16x16x32_bf16 v[92:95], v[144:147], v[212:215], v[92:95]
	v_mfma_f32_16x16x32_bf16 v[88:91], v[166:169], v[212:215], v[88:91]
	v_mfma_f32_16x16x32_bf16 v[76:79], v[144:147], v[220:223], v[76:79]
	v_mfma_f32_16x16x32_bf16 v[72:75], v[166:169], v[220:223], v[72:75]
	v_mfma_f32_16x16x32_bf16 v[124:127], v[156:159], v[194:197], v[124:127]
	v_mfma_f32_16x16x32_bf16 v[120:123], v[170:173], v[194:197], v[120:123]
	v_mfma_f32_16x16x32_bf16 v[108:111], v[156:159], v[202:205], v[108:111]
	v_mfma_f32_16x16x32_bf16 v[104:107], v[170:173], v[202:205], v[104:107]
	v_mfma_f32_16x16x32_bf16 v[92:95], v[156:159], v[216:219], v[92:95]
	v_mfma_f32_16x16x32_bf16 v[88:91], v[170:173], v[216:219], v[88:91]
	v_mfma_f32_16x16x32_bf16 v[76:79], v[156:159], v[224:227], v[76:79]
	v_mfma_f32_16x16x32_bf16 v[72:75], v[170:173], v[224:227], v[72:75]
	v_mfma_f32_16x16x32_bf16 v[116:119], v[174:177], v[190:193], v[116:119]
	v_mfma_f32_16x16x32_bf16 v[112:115], v[182:185], v[190:193], v[112:115]
	v_mfma_f32_16x16x32_bf16 v[100:103], v[174:177], v[198:201], v[100:103]
	v_mfma_f32_16x16x32_bf16 v[96:99], v[182:185], v[198:201], v[96:99]
	v_mfma_f32_16x16x32_bf16 v[84:87], v[174:177], v[212:215], v[84:87]
	v_mfma_f32_16x16x32_bf16 v[80:83], v[182:185], v[212:215], v[80:83]
	v_mfma_f32_16x16x32_bf16 v[68:71], v[174:177], v[220:223], v[68:71]
	v_mfma_f32_16x16x32_bf16 v[64:67], v[182:185], v[220:223], v[64:67]
	v_mfma_f32_16x16x32_bf16 v[116:119], v[178:181], v[194:197], v[116:119]
	v_mfma_f32_16x16x32_bf16 v[112:115], v[186:189], v[194:197], v[112:115]
	v_mfma_f32_16x16x32_bf16 v[100:103], v[178:181], v[202:205], v[100:103]
	v_mfma_f32_16x16x32_bf16 v[96:99], v[186:189], v[202:205], v[96:99]
	v_mfma_f32_16x16x32_bf16 v[84:87], v[178:181], v[216:219], v[84:87]
	v_mfma_f32_16x16x32_bf16 v[80:83], v[186:189], v[216:219], v[80:83]
	v_mfma_f32_16x16x32_bf16 v[68:71], v[178:181], v[224:227], v[68:71]
	v_mfma_f32_16x16x32_bf16 v[64:67], v[186:189], v[224:227], v[64:67]
	s_barrier
	s_add_i32 s8, s63, s0
	v_lshl_add_u64 v[160:161], s[56:57], 0, v[130:131]
	s_mov_b32 m0, s8
	ds_read_b128 v[190:193], v154 offset:16384
	ds_read_b128 v[194:197], v154 offset:17408
	ds_read_b128 v[198:201], v154 offset:18432
	ds_read_b128 v[202:205], v154 offset:19456
	ds_read_b128 v[212:215], v154 offset:20480
	ds_read_b128 v[216:219], v154 offset:21504
	ds_read_b128 v[220:223], v154 offset:22528
	ds_read_b128 v[224:227], v154 offset:23552
	global_load_lds_dwordx4 v[160:161], off
	s_add_i32 m0, s8, 0x2000
	s_add_u32 s8, s56, 0x40000
	v_lshl_add_u64 v[206:207], s[56:57], 0, v[134:135]
	s_addc_u32 s9, s57, 0
	s_add_i32 s38, s64, s0
	global_load_lds_dwordx4 v[206:207], off
	v_lshl_add_u64 v[228:229], s[8:9], 0, v[130:131]
	s_mov_b32 m0, s38
	v_lshl_add_u64 v[230:231], s[58:59], 0, v[132:133]
	global_load_lds_dwordx4 v[228:229], off
	v_lshl_add_u64 v[228:229], s[8:9], 0, v[134:135]
	s_add_i32 m0, s38, 0x2000
	s_nop 0
	global_load_lds_dwordx4 v[228:229], off
	v_lshl_add_u64 v[228:229], s[58:59], 0, v[128:129]
	s_mov_b32 m0, s1
	s_nop 0
	global_load_lds_dwordx4 v[228:229], off
	s_mov_b32 m0, s4
	s_nop 0
	global_load_lds_dwordx4 v[230:231], off
	s_waitcnt vmcnt(8)
	s_waitcnt lgkmcnt(0)
	s_barrier
; #define PG8_STAGE(bufoff, gbase, voff) do { _Pragma("unroll") for (int _i = 0; _i < 2; ++_i) \
;         __builtin_amdgcn_global_load_lds((const unsigned*)((const char*)(gbase) + (voff)[_i]), (LAS unsigned*)(lds + (bufoff) + ldsw + _i * 8192), 16, 0, 0); } while (0)
; #define PG8_LDA(dst, b, h) do { _Pragma("unroll") for (int m = 0; m < 4; ++m) _Pragma("unroll") for (int k = 0; k < 2; ++k) dst[m][k] = *(const LAS bf16x8*)(lds + PG8_SA(b, h) + aoff + m * 2048 + k * 1024); } while (0)
; #define PG8_LDB(dst, b, h) do { _Pragma("unroll") for (int n = 0; n < 2; ++n) _Pragma("unroll") for (int k = 0; k < 2; ++k) dst[n][k] = *(const LAS bf16x8*)(lds + PG8_SB(b, h) + boff + n * 2048 + k * 1024); } while (0)
; #define PG8_MMA(ai, bj, At, Bt) do { __builtin_amdgcn_s_setprio(1); _Pragma("unroll") for (int m = 0; m < 4; ++m) _Pragma("unroll") for (int n = 0; n < 2; ++n) _Pragma("unroll") for (int k = 0; k < 2; ++k) \
;         acc[ai][bj][m][n] = __builtin_amdgcn_mfma_f32_16x16x32_bf16(Bt[n][k], At[m][k], acc[ai][bj][m][n], 0, 0, 0); __builtin_amdgcn_s_setprio(0); } while (0)
; #define PG8_WAIT_V(n) asm volatile("s_waitcnt vmcnt(" #n ")" ::: "memory")
; #define PG8_WAIT_L(n) asm volatile("s_waitcnt lgkmcnt(" #n ")" ::: "memory")
; #define PG8_BAR __builtin_amdgcn_s_barrier()
; #define PG8_SCHED __builtin_amdgcn_sched_barrier(0)
; template <class GEO, class Epi>
; __device__ __forceinline__ void gemm_phase(LAS unsigned char* lds, const Gemm g, const StaticOrder& S, const Epi& E) {
;     ...
;             PG8_WAIT_V(8); PG8_WAIT_L(0); PG8_BAR; PG8_MMA(1, 0, At, B0); PG8_MMA(1, 1, At, B1); PG8_BAR; PG8_SCHED;
;             PG8_LDB(B0, 1, 0); PG8_LDB(B1, 1, 1); PG8_SCHED; PG8_LDA(At, 1, 0); PG8_STAGE(PG8_SA(0, 1), a2 + hstepA, voffA);
;             PG8_WAIT_V(8); PG8_WAIT_L(0); PG8_BAR; PG8_MMA(0, 0, At, B0); PG8_MMA(0, 1, At, B1); PG8_BAR; PG8_SCHED;
	s_waitcnt lgkmcnt(0)
	v_mfma_f32_16x16x32_bf16 v[60:63], v[144:147], v[190:193], v[60:63]
	v_mfma_f32_16x16x32_bf16 v[56:59], v[166:169], v[190:193], v[56:59]
	v_mfma_f32_16x16x32_bf16 v[44:47], v[144:147], v[198:201], v[44:47]
	v_mfma_f32_16x16x32_bf16 v[40:43], v[166:169], v[198:201], v[40:43]
	v_mfma_f32_16x16x32_bf16 v[28:31], v[144:147], v[212:215], v[28:31]
	v_mfma_f32_16x16x32_bf16 v[24:27], v[166:169], v[212:215], v[24:27]
	v_mfma_f32_16x16x32_bf16 v[12:15], v[144:147], v[220:223], v[12:15]
	v_mfma_f32_16x16x32_bf16 v[8:11], v[166:169], v[220:223], v[8:11]
	v_mfma_f32_16x16x32_bf16 v[60:63], v[156:159], v[194:197], v[60:63]
	v_mfma_f32_16x16x32_bf16 v[56:59], v[170:173], v[194:197], v[56:59]
	v_mfma_f32_16x16x32_bf16 v[44:47], v[156:159], v[202:205], v[44:47]
	v_mfma_f32_16x16x32_bf16 v[40:43], v[170:173], v[202:205], v[40:43]
	v_mfma_f32_16x16x32_bf16 v[28:31], v[156:159], v[216:219], v[28:31]
	v_mfma_f32_16x16x32_bf16 v[24:27], v[170:173], v[216:219], v[24:27]
	v_mfma_f32_16x16x32_bf16 v[12:15], v[156:159], v[224:227], v[12:15]
	v_mfma_f32_16x16x32_bf16 v[8:11], v[170:173], v[224:227], v[8:11]
	v_mfma_f32_16x16x32_bf16 v[52:55], v[174:177], v[190:193], v[52:55]
	v_mfma_f32_16x16x32_bf16 v[48:51], v[182:185], v[190:193], v[48:51]
	v_mfma_f32_16x16x32_bf16 v[36:39], v[174:177], v[198:201], v[36:39]
	v_mfma_f32_16x16x32_bf16 v[32:35], v[182:185], v[198:201], v[32:35]
	v_mfma_f32_16x16x32_bf16 v[20:23], v[174:177], v[212:215], v[20:23]
	v_mfma_f32_16x16x32_bf16 v[16:19], v[182:185], v[212:215], v[16:19]
	v_mfma_f32_16x16x32_bf16 v[4:7], v[174:177], v[220:223], v[4:7]
	v_mfma_f32_16x16x32_bf16 v[0:3], v[182:185], v[220:223], v[0:3]
	v_mfma_f32_16x16x32_bf16 v[52:55], v[178:181], v[194:197], v[52:55]
	v_mfma_f32_16x16x32_bf16 v[48:51], v[186:189], v[194:197], v[48:51]
	v_mfma_f32_16x16x32_bf16 v[36:39], v[178:181], v[202:205], v[36:39]
	v_mfma_f32_16x16x32_bf16 v[32:35], v[186:189], v[202:205], v[32:35]
	v_mfma_f32_16x16x32_bf16 v[20:23], v[178:181], v[216:219], v[20:23]
	v_mfma_f32_16x16x32_bf16 v[16:19], v[186:189], v[216:219], v[16:19]
	v_mfma_f32_16x16x32_bf16 v[4:7], v[178:181], v[224:227], v[4:7]
	v_mfma_f32_16x16x32_bf16 v[0:3], v[186:189], v[224:227], v[0:3]
	s_barrier
	s_add_i32 s38, 0, 0x18000
	v_add_u32_e32 v155, s38, v149
	s_add_i32 s39, 0, 0x1c000
	ds_read_b128 v[144:147], v155
	ds_read_b128 v[156:159], v155 offset:1024
	ds_read_b128 v[166:169], v155 offset:2048
	ds_read_b128 v[170:173], v155 offset:3072
	v_add_u32_e32 v155, s39, v149
	ds_read_b128 v[174:177], v155
	ds_read_b128 v[178:181], v155 offset:1024
	ds_read_b128 v[182:185], v155 offset:2048
	ds_read_b128 v[186:189], v155 offset:3072
	s_add_u32 s8, s58, 0x40000
	s_addc_u32 s9, s59, 0
	s_mov_b32 m0, s5
	v_lshl_add_u64 v[232:233], s[8:9], 0, v[128:129]
	ds_read_b128 v[190:193], v154 offset:32768
	ds_read_b128 v[194:197], v154 offset:33792
	ds_read_b128 v[198:201], v154 offset:34816
	ds_read_b128 v[202:205], v154 offset:35840
	ds_read_b128 v[212:215], v154 offset:36864
	ds_read_b128 v[216:219], v154 offset:37888
	ds_read_b128 v[220:223], v154 offset:38912
	ds_read_b128 v[224:227], v154 offset:39936
	global_load_lds_dwordx4 v[232:233], off
	v_lshl_add_u64 v[232:233], s[8:9], 0, v[132:133]
	s_mov_b32 m0, s6
	s_nop 0
	global_load_lds_dwordx4 v[232:233], off
	s_waitcnt vmcnt(8)
	s_waitcnt lgkmcnt(0)
	s_barrier
	s_waitcnt lgkmcnt(0)
	v_mfma_f32_16x16x32_bf16 v[124:127], v[144:147], v[190:193], v[124:127]
	v_mfma_f32_16x16x32_bf16 v[120:123], v[166:169], v[190:193], v[120:123]
	v_mfma_f32_16x16x32_bf16 v[108:111], v[144:147], v[198:201], v[108:111]
	v_mfma_f32_16x16x32_bf16 v[104:107], v[166:169], v[198:201], v[104:107]
	v_mfma_f32_16x16x32_bf16 v[92:95], v[144:147], v[212:215], v[92:95]
	v_mfma_f32_16x16x32_bf16 v[88:91], v[166:169], v[212:215], v[88:91]
	v_mfma_f32_16x16x32_bf16 v[76:79], v[144:147], v[220:223], v[76:79]
	v_mfma_f32_16x16x32_bf16 v[72:75], v[166:169], v[220:223], v[72:75]
	v_mfma_f32_16x16x32_bf16 v[124:127], v[156:159], v[194:197], v[124:127]
	v_mfma_f32_16x16x32_bf16 v[120:123], v[170:173], v[194:197], v[120:123]
	v_mfma_f32_16x16x32_bf16 v[108:111], v[156:159], v[202:205], v[108:111]
	v_mfma_f32_16x16x32_bf16 v[104:107], v[170:173], v[202:205], v[104:107]
	v_mfma_f32_16x16x32_bf16 v[92:95], v[156:159], v[216:219], v[92:95]
	v_mfma_f32_16x16x32_bf16 v[88:91], v[170:173], v[216:219], v[88:91]
	v_mfma_f32_16x16x32_bf16 v[76:79], v[156:159], v[224:227], v[76:79]
	v_mfma_f32_16x16x32_bf16 v[72:75], v[170:173], v[224:227], v[72:75]
	v_mfma_f32_16x16x32_bf16 v[116:119], v[174:177], v[190:193], v[116:119]
	v_mfma_f32_16x16x32_bf16 v[112:115], v[182:185], v[190:193], v[112:115]
	v_mfma_f32_16x16x32_bf16 v[100:103], v[174:177], v[198:201], v[100:103]
	v_mfma_f32_16x16x32_bf16 v[96:99], v[182:185], v[198:201], v[96:99]
	v_mfma_f32_16x16x32_bf16 v[84:87], v[174:177], v[212:215], v[84:87]
	v_mfma_f32_16x16x32_bf16 v[80:83], v[182:185], v[212:215], v[80:83]
	v_mfma_f32_16x16x32_bf16 v[68:71], v[174:177], v[220:223], v[68:71]
	v_mfma_f32_16x16x32_bf16 v[64:67], v[182:185], v[220:223], v[64:67]
	v_mfma_f32_16x16x32_bf16 v[116:119], v[178:181], v[194:197], v[116:119]
	v_mfma_f32_16x16x32_bf16 v[112:115], v[186:189], v[194:197], v[112:115]
	v_mfma_f32_16x16x32_bf16 v[100:103], v[178:181], v[202:205], v[100:103]
	v_mfma_f32_16x16x32_bf16 v[96:99], v[186:189], v[202:205], v[96:99]
	v_mfma_f32_16x16x32_bf16 v[84:87], v[178:181], v[216:219], v[84:87]
	v_mfma_f32_16x16x32_bf16 v[80:83], v[186:189], v[216:219], v[80:83]
	v_mfma_f32_16x16x32_bf16 v[68:71], v[178:181], v[224:227], v[68:71]
	v_mfma_f32_16x16x32_bf16 v[64:67], v[186:189], v[224:227], v[64:67]
	s_barrier
; #define PG8_STAGE(bufoff, gbase, voff) do { _Pragma("unroll") for (int _i = 0; _i < 2; ++_i) \
;         __builtin_amdgcn_global_load_lds((const unsigned*)((const char*)(gbase) + (voff)[_i]), (LAS unsigned*)(lds + (bufoff) + ldsw + _i * 8192), 16, 0, 0); } while (0)
; #define PG8_LDA(dst, b, h) do { _Pragma("unroll") for (int m = 0; m < 4; ++m) _Pragma("unroll") for (int k = 0; k < 2; ++k) dst[m][k] = *(const LAS bf16x8*)(lds + PG8_SA(b, h) + aoff + m * 2048 + k * 1024); } while (0)
; #define PG8_MMA(ai, bj, At, Bt) do { __builtin_amdgcn_s_setprio(1); _Pragma("unroll") for (int m = 0; m < 4; ++m) _Pragma("unroll") for (int n = 0; n < 2; ++n) _Pragma("unroll") for (int k = 0; k < 2; ++k) \
;         acc[ai][bj][m][n] = __builtin_amdgcn_mfma_f32_16x16x32_bf16(Bt[n][k], At[m][k], acc[ai][bj][m][n], 0, 0, 0); __builtin_amdgcn_s_setprio(0); } while (0)
; #define PG8_WAIT_V(n) asm volatile("s_waitcnt vmcnt(" #n ")" ::: "memory")
; #define PG8_WAIT_L(n) asm volatile("s_waitcnt lgkmcnt(" #n ")" ::: "memory")
; #define PG8_BAR __builtin_amdgcn_s_barrier()
; #define PG8_SCHED __builtin_amdgcn_sched_barrier(0)
; template <class GEO, class Epi>
; __device__ __forceinline__ void gemm_phase(LAS unsigned char* lds, const Gemm g, const StaticOrder& S, const Epi& E) {
;     ...
;             PG8_LDA(At, 1, 1); PG8_STAGE(PG8_SB(1, 0), b3, voffB); PG8_STAGE(PG8_SB(1, 1), b3 + hstepB, voffB); PG8_STAGE(PG8_SA(1, 0), a3, voffA);
;             PG8_WAIT_V(8); PG8_WAIT_L(0); PG8_BAR; PG8_MMA(1, 0, At, B0); PG8_MMA(1, 1, At, B1); PG8_BAR; PG8_SCHED;
;         }
;         if (wr == 0) PG8_BAR;
	s_add_i32 s8, s38, s0
	v_lshl_add_u64 v[160:161], v[160:161], 0, s[30:31]
	s_mov_b32 m0, s8
	ds_read_b128 v[190:193], v154 offset:49152
	ds_read_b128 v[194:197], v154 offset:50176
	ds_read_b128 v[198:201], v154 offset:51200
	ds_read_b128 v[202:205], v154 offset:52224
	ds_read_b128 v[212:215], v154 offset:53248
	ds_read_b128 v[216:219], v154 offset:54272
	ds_read_b128 v[220:223], v154 offset:55296
	ds_read_b128 v[224:227], v154 offset:56320
	global_load_lds_dwordx4 v[160:161], off
	s_add_i32 m0, s8, 0x2000
	s_add_u32 s8, s56, 0x40080
	v_lshl_add_u64 v[160:161], v[206:207], 0, s[30:31]
	s_addc_u32 s9, s57, 0
	s_add_i32 s38, s39, s0
	global_load_lds_dwordx4 v[160:161], off
	v_lshl_add_u64 v[160:161], s[8:9], 0, v[130:131]
	s_mov_b32 m0, s38
	s_nop 0
	global_load_lds_dwordx4 v[160:161], off
	v_lshl_add_u64 v[160:161], s[8:9], 0, v[134:135]
	s_add_i32 m0, s38, 0x2000
	s_nop 0
	global_load_lds_dwordx4 v[160:161], off
	v_lshl_add_u64 v[160:161], v[228:229], 0, s[30:31]
	s_mov_b32 m0, s7
	s_nop 0
	global_load_lds_dwordx4 v[160:161], off
	v_lshl_add_u64 v[160:161], v[230:231], 0, s[30:31]
	s_mov_b32 m0, s12
	s_nop 0
	global_load_lds_dwordx4 v[160:161], off
	s_waitcnt vmcnt(8)
	s_waitcnt lgkmcnt(0)
	s_barrier
	s_waitcnt lgkmcnt(0)
	v_mfma_f32_16x16x32_bf16 v[60:63], v[144:147], v[190:193], v[60:63]
	v_mfma_f32_16x16x32_bf16 v[56:59], v[166:169], v[190:193], v[56:59]
	v_mfma_f32_16x16x32_bf16 v[44:47], v[144:147], v[198:201], v[44:47]
	v_mfma_f32_16x16x32_bf16 v[40:43], v[166:169], v[198:201], v[40:43]
	v_mfma_f32_16x16x32_bf16 v[28:31], v[144:147], v[212:215], v[28:31]
	v_mfma_f32_16x16x32_bf16 v[24:27], v[166:169], v[212:215], v[24:27]
	v_mfma_f32_16x16x32_bf16 v[12:15], v[144:147], v[220:223], v[12:15]
	v_mfma_f32_16x16x32_bf16 v[8:11], v[166:169], v[220:223], v[8:11]
	v_mfma_f32_16x16x32_bf16 v[60:63], v[156:159], v[194:197], v[60:63]
	v_mfma_f32_16x16x32_bf16 v[56:59], v[170:173], v[194:197], v[56:59]
	v_mfma_f32_16x16x32_bf16 v[44:47], v[156:159], v[202:205], v[44:47]
	v_mfma_f32_16x16x32_bf16 v[40:43], v[170:173], v[202:205], v[40:43]
	v_mfma_f32_16x16x32_bf16 v[28:31], v[156:159], v[216:219], v[28:31]
	v_mfma_f32_16x16x32_bf16 v[24:27], v[170:173], v[216:219], v[24:27]
	v_mfma_f32_16x16x32_bf16 v[12:15], v[156:159], v[224:227], v[12:15]
	v_mfma_f32_16x16x32_bf16 v[8:11], v[170:173], v[224:227], v[8:11]
	v_mfma_f32_16x16x32_bf16 v[52:55], v[174:177], v[190:193], v[52:55]
	v_mfma_f32_16x16x32_bf16 v[48:51], v[182:185], v[190:193], v[48:51]
	v_mfma_f32_16x16x32_bf16 v[36:39], v[174:177], v[198:201], v[36:39]
	v_mfma_f32_16x16x32_bf16 v[32:35], v[182:185], v[198:201], v[32:35]
	v_mfma_f32_16x16x32_bf16 v[20:23], v[174:177], v[212:215], v[20:23]
	v_mfma_f32_16x16x32_bf16 v[16:19], v[182:185], v[212:215], v[16:19]
	v_mfma_f32_16x16x32_bf16 v[4:7], v[174:177], v[220:223], v[4:7]
	v_mfma_f32_16x16x32_bf16 v[0:3], v[182:185], v[220:223], v[0:3]
	v_mfma_f32_16x16x32_bf16 v[52:55], v[178:181], v[194:197], v[52:55]
	v_mfma_f32_16x16x32_bf16 v[48:51], v[186:189], v[194:197], v[48:51]
	v_mfma_f32_16x16x32_bf16 v[36:39], v[178:181], v[202:205], v[36:39]
	v_mfma_f32_16x16x32_bf16 v[32:35], v[186:189], v[202:205], v[32:35]
	v_mfma_f32_16x16x32_bf16 v[20:23], v[178:181], v[216:219], v[20:23]
	v_mfma_f32_16x16x32_bf16 v[16:19], v[186:189], v[216:219], v[16:19]
	v_mfma_f32_16x16x32_bf16 v[4:7], v[178:181], v[224:227], v[4:7]
	v_mfma_f32_16x16x32_bf16 v[0:3], v[186:189], v[224:227], v[0:3]
	s_barrier
	s_add_i32 s69, s69, 2
	s_add_u32 s54, s54, 0x100
	s_addc_u32 s55, s55, 0
	s_add_u32 s67, s67, 0x100
	s_addc_u32 s68, s68, 0
	s_cmp_gt_u32 s69, 13
	s_cbranch_scc0 .LBB0_691
	s_and_b64 vcc, exec, s[34:35]
	s_cbranch_vccz .LBB0_694
	s_barrier

; #define PG8_STAGE(bufoff, gbase, voff) do { _Pragma("unroll") for (int _i = 0; _i < 2; ++_i) \
;         __builtin_amdgcn_global_load_lds((const unsigned*)((const char*)(gbase) + (voff)[_i]), (LAS unsigned*)(lds + (bufoff) + ldsw + _i * 8192), 16, 0, 0); } while (0)
; #define PG8_LDA(dst, b, h) do { _Pragma("unroll") for (int m = 0; m < 4; ++m) _Pragma("unroll") for (int k = 0; k < 2; ++k) dst[m][k] = *(const LAS bf16x8*)(lds + PG8_SA(b, h) + aoff + m * 2048 + k * 1024); } while (0)
; #define PG8_LDB(dst, b, h) do { _Pragma("unroll") for (int n = 0; n < 2; ++n) _Pragma("unroll") for (int k = 0; k < 2; ++k) dst[n][k] = *(const LAS bf16x8*)(lds + PG8_SB(b, h) + boff + n * 2048 + k * 1024); } while (0)
; #define PG8_MMA(ai, bj, At, Bt) do { __builtin_amdgcn_s_setprio(1); _Pragma("unroll") for (int m = 0; m < 4; ++m) _Pragma("unroll") for (int n = 0; n < 2; ++n) _Pragma("unroll") for (int k = 0; k < 2; ++k) \
;         acc[ai][bj][m][n] = __builtin_amdgcn_mfma_f32_16x16x32_bf16(Bt[n][k], At[m][k], acc[ai][bj][m][n], 0, 0, 0); __builtin_amdgcn_s_setprio(0); } while (0)
; #define PG8_WAIT_V(n) asm volatile("s_waitcnt vmcnt(" #n ")" ::: "memory")
; #define PG8_WAIT_L(n) asm volatile("s_waitcnt lgkmcnt(" #n ")" ::: "memory")
; #define PG8_BAR __builtin_amdgcn_s_barrier()
; #define PG8_SCHED __builtin_amdgcn_sched_barrier(0)
; template <class GEO, class Epi>
; __device__ __forceinline__ void gemm_phase(LAS unsigned char* lds, const Gemm g, const StaticOrder& S, const Epi& E) {
;     ...
;             const bool last = (t == nt - 2);
;             const char* a1 = cA + (size_t)(t + 1) * kstep;
;             const char* a2 = last ? nA : cA + (size_t)(t + 2) * kstep; const char* b2 = last ? nB : cB + (size_t)(t + 2) * kstep;
;             const char* a3 = a2 + kstep; const char* b3 = b2 + kstep;
;             PG8_LDB(B0, 0, 0); PG8_LDB(B1, 0, 1); PG8_SCHED; PG8_LDA(At, 0, 0); PG8_STAGE(PG8_SA(1, 1), a1 + hstepA, voffA);
;             PG8_WAIT_V(8); PG8_WAIT_L(0); PG8_BAR; PG8_MMA(0, 0, At, B0); PG8_MMA(0, 1, At, B1); PG8_BAR; PG8_SCHED;
;             PG8_LDA(At, 0, 1); PG8_STAGE(PG8_SB(0, 0), b2, voffB); PG8_STAGE(PG8_SB(0, 1), b2 + hstepB, voffB); PG8_STAGE(PG8_SA(0, 0), a2, voffA);
;             PG8_WAIT_V(8); PG8_WAIT_L(0); PG8_BAR; PG8_MMA(1, 0, At, B0); PG8_MMA(1, 1, At, B1); PG8_BAR; PG8_SCHED;
.LBB0_779:
	ds_read_b128 v[148:151], v179
	ds_read_b128 v[152:155], v179 offset:1024
	ds_read_b128 v[156:159], v179 offset:2048
	ds_read_b128 v[166:169], v179 offset:3072
	ds_read_b128 v[186:189], v181
	ds_read_b128 v[190:193], v181 offset:1024
	ds_read_b128 v[194:197], v181 offset:2048
	ds_read_b128 v[198:201], v181 offset:3072
	s_add_u32 s8, s52, 0xfffc0080
	s_addc_u32 s9, s53, -1
	s_cmp_eq_u32 s69, 12
	s_cselect_b32 s57, s45, s9
	s_cselect_b32 s56, s47, s8
	s_cselect_b32 s55, s16, s68
	s_cselect_b32 s54, s66, s67
	v_lshl_add_u64 v[160:161], s[52:53], 0, v[140:141]
	s_add_i32 m0, s1, 0xc000
	ds_read_b128 v[202:205], v183
	ds_read_b128 v[212:215], v183 offset:1024
	ds_read_b128 v[216:219], v183 offset:2048
	ds_read_b128 v[220:223], v183 offset:3072
	ds_read_b128 v[224:227], v183 offset:4096
	ds_read_b128 v[228:231], v183 offset:5120
	ds_read_b128 v[232:235], v183 offset:6144
	ds_read_b128 v[236:239], v183 offset:7168
	global_load_lds_dwordx4 v[160:161], off
	v_lshl_add_u64 v[160:161], s[52:53], 0, v[142:143]
	s_add_i32 m0, s1, 0xe000
	s_nop 0
	global_load_lds_dwordx4 v[160:161], off
	s_waitcnt vmcnt(8)
	s_waitcnt lgkmcnt(0)
	s_barrier
	s_waitcnt lgkmcnt(0)
	v_mfma_f32_16x16x32_bf16 v[124:127], v[148:151], v[202:205], v[124:127]
	v_mfma_f32_16x16x32_bf16 v[120:123], v[156:159], v[202:205], v[120:123]
	v_mfma_f32_16x16x32_bf16 v[112:115], v[148:151], v[216:219], v[112:115]
	v_mfma_f32_16x16x32_bf16 v[104:107], v[156:159], v[216:219], v[104:107]
	v_mfma_f32_16x16x32_bf16 v[96:99], v[148:151], v[224:227], v[96:99]
	v_mfma_f32_16x16x32_bf16 v[88:91], v[156:159], v[224:227], v[88:91]
	v_mfma_f32_16x16x32_bf16 v[80:83], v[148:151], v[232:235], v[80:83]
	v_mfma_f32_16x16x32_bf16 v[72:75], v[156:159], v[232:235], v[72:75]
	v_mfma_f32_16x16x32_bf16 v[124:127], v[152:155], v[212:215], v[124:127]
	v_mfma_f32_16x16x32_bf16 v[120:123], v[166:169], v[212:215], v[120:123]
	v_mfma_f32_16x16x32_bf16 v[112:115], v[152:155], v[220:223], v[112:115]
	v_mfma_f32_16x16x32_bf16 v[104:107], v[166:169], v[220:223], v[104:107]
	v_mfma_f32_16x16x32_bf16 v[96:99], v[152:155], v[228:231], v[96:99]
	v_mfma_f32_16x16x32_bf16 v[88:91], v[166:169], v[228:231], v[88:91]
	v_mfma_f32_16x16x32_bf16 v[80:83], v[152:155], v[236:239], v[80:83]
	v_mfma_f32_16x16x32_bf16 v[72:75], v[166:169], v[236:239], v[72:75]
	v_mfma_f32_16x16x32_bf16 v[116:119], v[186:189], v[202:205], v[116:119]
	v_mfma_f32_16x16x32_bf16 v[108:111], v[194:197], v[202:205], v[108:111]
	v_mfma_f32_16x16x32_bf16 v[100:103], v[186:189], v[216:219], v[100:103]
	v_mfma_f32_16x16x32_bf16 v[92:95], v[194:197], v[216:219], v[92:95]
	v_mfma_f32_16x16x32_bf16 v[84:87], v[186:189], v[224:227], v[84:87]
	v_mfma_f32_16x16x32_bf16 v[76:79], v[194:197], v[224:227], v[76:79]
	v_mfma_f32_16x16x32_bf16 v[68:71], v[186:189], v[232:235], v[68:71]
	v_mfma_f32_16x16x32_bf16 v[64:67], v[194:197], v[232:235], v[64:67]
	v_mfma_f32_16x16x32_bf16 v[116:119], v[190:193], v[212:215], v[116:119]
	v_mfma_f32_16x16x32_bf16 v[108:111], v[198:201], v[212:215], v[108:111]
	v_mfma_f32_16x16x32_bf16 v[100:103], v[190:193], v[220:223], v[100:103]
	v_mfma_f32_16x16x32_bf16 v[92:95], v[198:201], v[220:223], v[92:95]
	v_mfma_f32_16x16x32_bf16 v[84:87], v[190:193], v[228:231], v[84:87]
	v_mfma_f32_16x16x32_bf16 v[76:79], v[198:201], v[228:231], v[76:79]
	v_mfma_f32_16x16x32_bf16 v[68:71], v[190:193], v[236:239], v[68:71]
	v_mfma_f32_16x16x32_bf16 v[64:67], v[198:201], v[236:239], v[64:67]
	s_barrier
	s_add_i32 s8, s60, s0
	v_lshl_add_u64 v[160:161], s[54:55], 0, v[130:131]
	s_mov_b32 m0, s8
	ds_read_b128 v[202:205], v183 offset:16384
	ds_read_b128 v[212:215], v183 offset:17408
	ds_read_b128 v[216:219], v183 offset:18432
	ds_read_b128 v[220:223], v183 offset:19456
	ds_read_b128 v[224:227], v183 offset:20480
	ds_read_b128 v[228:231], v183 offset:21504
	ds_read_b128 v[232:235], v183 offset:22528
	ds_read_b128 v[236:239], v183 offset:23552
	global_load_lds_dwordx4 v[160:161], off
	s_add_i32 m0, s8, 0x2000
	s_add_u32 s8, s54, 0x40000
	v_lshl_add_u64 v[170:171], s[54:55], 0, v[134:135]
	s_addc_u32 s9, s55, 0
	s_add_i32 s38, s61, s0
	global_load_lds_dwordx4 v[170:171], off
	v_lshl_add_u64 v[206:207], s[8:9], 0, v[130:131]
	s_mov_b32 m0, s38
	v_lshl_add_u64 v[240:241], s[56:57], 0, v[132:133]
	global_load_lds_dwordx4 v[206:207], off
	v_lshl_add_u64 v[206:207], s[8:9], 0, v[134:135]
	s_add_i32 m0, s38, 0x2000
	s_nop 0
	global_load_lds_dwordx4 v[206:207], off
	v_lshl_add_u64 v[206:207], s[56:57], 0, v[128:129]
	s_mov_b32 m0, s1
	s_nop 0
	global_load_lds_dwordx4 v[206:207], off
	s_mov_b32 m0, s4
	s_nop 0
	global_load_lds_dwordx4 v[240:241], off
	s_waitcnt vmcnt(8)
	s_waitcnt lgkmcnt(0)
	s_barrier
; #define PG8_STAGE(bufoff, gbase, voff) do { _Pragma("unroll") for (int _i = 0; _i < 2; ++_i) \
;         __builtin_amdgcn_global_load_lds((const unsigned*)((const char*)(gbase) + (voff)[_i]), (LAS unsigned*)(lds + (bufoff) + ldsw + _i * 8192), 16, 0, 0); } while (0)
; #define PG8_LDA(dst, b, h) do { _Pragma("unroll") for (int m = 0; m < 4; ++m) _Pragma("unroll") for (int k = 0; k < 2; ++k) dst[m][k] = *(const LAS bf16x8*)(lds + PG8_SA(b, h) + aoff + m * 2048 + k * 1024); } while (0)
; #define PG8_LDB(dst, b, h) do { _Pragma("unroll") for (int n = 0; n < 2; ++n) _Pragma("unroll") for (int k = 0; k < 2; ++k) dst[n][k] = *(const LAS bf16x8*)(lds + PG8_SB(b, h) + boff + n * 2048 + k * 1024); } while (0)
; #define PG8_MMA(ai, bj, At, Bt) do { __builtin_amdgcn_s_setprio(1); _Pragma("unroll") for (int m = 0; m < 4; ++m) _Pragma("unroll") for (int n = 0; n < 2; ++n) _Pragma("unroll") for (int k = 0; k < 2; ++k) \
;         acc[ai][bj][m][n] = __builtin_amdgcn_mfma_f32_16x16x32_bf16(Bt[n][k], At[m][k], acc[ai][bj][m][n], 0, 0, 0); __builtin_amdgcn_s_setprio(0); } while (0)
; #define PG8_WAIT_V(n) asm volatile("s_waitcnt vmcnt(" #n ")" ::: "memory")
; #define PG8_WAIT_L(n) asm volatile("s_waitcnt lgkmcnt(" #n ")" ::: "memory")
; #define PG8_BAR __builtin_amdgcn_s_barrier()
; #define PG8_SCHED __builtin_amdgcn_sched_barrier(0)
; template <class GEO, class Epi>
; __device__ __forceinline__ void gemm_phase(LAS unsigned char* lds, const Gemm g, const StaticOrder& S, const Epi& E) {
;     ...
;             PG8_WAIT_V(8); PG8_WAIT_L(0); PG8_BAR; PG8_MMA(1, 0, At, B0); PG8_MMA(1, 1, At, B1); PG8_BAR; PG8_SCHED;
;             PG8_LDB(B0, 1, 0); PG8_LDB(B1, 1, 1); PG8_SCHED; PG8_LDA(At, 1, 0); PG8_STAGE(PG8_SA(0, 1), a2 + hstepA, voffA);
;             PG8_WAIT_V(8); PG8_WAIT_L(0); PG8_BAR; PG8_MMA(0, 0, At, B0); PG8_MMA(0, 1, At, B1); PG8_BAR; PG8_SCHED;
	s_waitcnt lgkmcnt(0)
	v_mfma_f32_16x16x32_bf16 v[60:63], v[148:151], v[202:205], v[60:63]
	v_mfma_f32_16x16x32_bf16 v[56:59], v[156:159], v[202:205], v[56:59]
	v_mfma_f32_16x16x32_bf16 v[48:51], v[148:151], v[216:219], v[48:51]
	v_mfma_f32_16x16x32_bf16 v[40:43], v[156:159], v[216:219], v[40:43]
	v_mfma_f32_16x16x32_bf16 v[32:35], v[148:151], v[224:227], v[32:35]
	v_mfma_f32_16x16x32_bf16 v[24:27], v[156:159], v[224:227], v[24:27]
	v_mfma_f32_16x16x32_bf16 v[16:19], v[148:151], v[232:235], v[16:19]
	v_mfma_f32_16x16x32_bf16 v[8:11], v[156:159], v[232:235], v[8:11]
	v_mfma_f32_16x16x32_bf16 v[60:63], v[152:155], v[212:215], v[60:63]
	v_mfma_f32_16x16x32_bf16 v[56:59], v[166:169], v[212:215], v[56:59]
	v_mfma_f32_16x16x32_bf16 v[48:51], v[152:155], v[220:223], v[48:51]
	v_mfma_f32_16x16x32_bf16 v[40:43], v[166:169], v[220:223], v[40:43]
	v_mfma_f32_16x16x32_bf16 v[32:35], v[152:155], v[228:231], v[32:35]
	v_mfma_f32_16x16x32_bf16 v[24:27], v[166:169], v[228:231], v[24:27]
	v_mfma_f32_16x16x32_bf16 v[16:19], v[152:155], v[236:239], v[16:19]
	v_mfma_f32_16x16x32_bf16 v[8:11], v[166:169], v[236:239], v[8:11]
	v_mfma_f32_16x16x32_bf16 v[52:55], v[186:189], v[202:205], v[52:55]
	v_mfma_f32_16x16x32_bf16 v[44:47], v[194:197], v[202:205], v[44:47]
	v_mfma_f32_16x16x32_bf16 v[36:39], v[186:189], v[216:219], v[36:39]
	v_mfma_f32_16x16x32_bf16 v[28:31], v[194:197], v[216:219], v[28:31]
	v_mfma_f32_16x16x32_bf16 v[20:23], v[186:189], v[224:227], v[20:23]
	v_mfma_f32_16x16x32_bf16 v[12:15], v[194:197], v[224:227], v[12:15]
	v_mfma_f32_16x16x32_bf16 v[4:7], v[186:189], v[232:235], v[4:7]
	v_mfma_f32_16x16x32_bf16 v[0:3], v[194:197], v[232:235], v[0:3]
	v_mfma_f32_16x16x32_bf16 v[52:55], v[190:193], v[212:215], v[52:55]
	v_mfma_f32_16x16x32_bf16 v[44:47], v[198:201], v[212:215], v[44:47]
	v_mfma_f32_16x16x32_bf16 v[36:39], v[190:193], v[220:223], v[36:39]
	v_mfma_f32_16x16x32_bf16 v[28:31], v[198:201], v[220:223], v[28:31]
	v_mfma_f32_16x16x32_bf16 v[20:23], v[190:193], v[228:231], v[20:23]
	v_mfma_f32_16x16x32_bf16 v[12:15], v[198:201], v[228:231], v[12:15]
	v_mfma_f32_16x16x32_bf16 v[4:7], v[190:193], v[236:239], v[4:7]
	v_mfma_f32_16x16x32_bf16 v[0:3], v[198:201], v[236:239], v[0:3]
	s_barrier
	s_add_i32 s38, 0, 0x18000
	s_add_i32 s39, 0, 0x1c000
	v_add_u32_e32 v166, s38, v175
	v_add_u32_e32 v172, s39, v175
	ds_read_b128 v[148:151], v166
	ds_read_b128 v[152:155], v166 offset:1024
	ds_read_b128 v[156:159], v166 offset:2048
	ds_read_b128 v[166:169], v166 offset:3072
	ds_read_b128 v[186:189], v172
	ds_read_b128 v[190:193], v172 offset:1024
	ds_read_b128 v[194:197], v172 offset:2048
	ds_read_b128 v[198:201], v172 offset:3072
	s_add_u32 s8, s56, 0x40000
	s_addc_u32 s9, s57, 0
	s_mov_b32 m0, s5
	v_lshl_add_u64 v[242:243], s[8:9], 0, v[128:129]
	ds_read_b128 v[202:205], v183 offset:32768
	ds_read_b128 v[212:215], v183 offset:33792
	ds_read_b128 v[216:219], v183 offset:34816
	ds_read_b128 v[220:223], v183 offset:35840
	ds_read_b128 v[224:227], v183 offset:36864
	ds_read_b128 v[228:231], v183 offset:37888
	ds_read_b128 v[232:235], v183 offset:38912
	ds_read_b128 v[236:239], v183 offset:39936
	global_load_lds_dwordx4 v[242:243], off
	v_lshl_add_u64 v[242:243], s[8:9], 0, v[132:133]
	s_mov_b32 m0, s6
	s_nop 0
	global_load_lds_dwordx4 v[242:243], off
	s_waitcnt vmcnt(8)
	s_waitcnt lgkmcnt(0)
	s_barrier
	s_waitcnt lgkmcnt(0)
	v_mfma_f32_16x16x32_bf16 v[124:127], v[148:151], v[202:205], v[124:127]
	v_mfma_f32_16x16x32_bf16 v[120:123], v[156:159], v[202:205], v[120:123]
	v_mfma_f32_16x16x32_bf16 v[112:115], v[148:151], v[216:219], v[112:115]
	v_mfma_f32_16x16x32_bf16 v[104:107], v[156:159], v[216:219], v[104:107]
	v_mfma_f32_16x16x32_bf16 v[96:99], v[148:151], v[224:227], v[96:99]
	v_mfma_f32_16x16x32_bf16 v[88:91], v[156:159], v[224:227], v[88:91]
	v_mfma_f32_16x16x32_bf16 v[80:83], v[148:151], v[232:235], v[80:83]
	v_mfma_f32_16x16x32_bf16 v[72:75], v[156:159], v[232:235], v[72:75]
	v_mfma_f32_16x16x32_bf16 v[124:127], v[152:155], v[212:215], v[124:127]
	v_mfma_f32_16x16x32_bf16 v[120:123], v[166:169], v[212:215], v[120:123]
	v_mfma_f32_16x16x32_bf16 v[112:115], v[152:155], v[220:223], v[112:115]
	v_mfma_f32_16x16x32_bf16 v[104:107], v[166:169], v[220:223], v[104:107]
	v_mfma_f32_16x16x32_bf16 v[96:99], v[152:155], v[228:231], v[96:99]
	v_mfma_f32_16x16x32_bf16 v[88:91], v[166:169], v[228:231], v[88:91]
	v_mfma_f32_16x16x32_bf16 v[80:83], v[152:155], v[236:239], v[80:83]
	v_mfma_f32_16x16x32_bf16 v[72:75], v[166:169], v[236:239], v[72:75]
	v_mfma_f32_16x16x32_bf16 v[116:119], v[186:189], v[202:205], v[116:119]
	v_mfma_f32_16x16x32_bf16 v[108:111], v[194:197], v[202:205], v[108:111]
	v_mfma_f32_16x16x32_bf16 v[100:103], v[186:189], v[216:219], v[100:103]
	v_mfma_f32_16x16x32_bf16 v[92:95], v[194:197], v[216:219], v[92:95]
	v_mfma_f32_16x16x32_bf16 v[84:87], v[186:189], v[224:227], v[84:87]
	v_mfma_f32_16x16x32_bf16 v[76:79], v[194:197], v[224:227], v[76:79]
	v_mfma_f32_16x16x32_bf16 v[68:71], v[186:189], v[232:235], v[68:71]
	v_mfma_f32_16x16x32_bf16 v[64:67], v[194:197], v[232:235], v[64:67]
	v_mfma_f32_16x16x32_bf16 v[116:119], v[190:193], v[212:215], v[116:119]
	v_mfma_f32_16x16x32_bf16 v[108:111], v[198:201], v[212:215], v[108:111]
	v_mfma_f32_16x16x32_bf16 v[100:103], v[190:193], v[220:223], v[100:103]
	v_mfma_f32_16x16x32_bf16 v[92:95], v[198:201], v[220:223], v[92:95]
	v_mfma_f32_16x16x32_bf16 v[84:87], v[190:193], v[228:231], v[84:87]
	v_mfma_f32_16x16x32_bf16 v[76:79], v[198:201], v[228:231], v[76:79]
	v_mfma_f32_16x16x32_bf16 v[68:71], v[190:193], v[236:239], v[68:71]
	v_mfma_f32_16x16x32_bf16 v[64:67], v[198:201], v[236:239], v[64:67]
	s_barrier
; #define PG8_STAGE(bufoff, gbase, voff) do { _Pragma("unroll") for (int _i = 0; _i < 2; ++_i) \
;         __builtin_amdgcn_global_load_lds((const unsigned*)((const char*)(gbase) + (voff)[_i]), (LAS unsigned*)(lds + (bufoff) + ldsw + _i * 8192), 16, 0, 0); } while (0)
; #define PG8_LDA(dst, b, h) do { _Pragma("unroll") for (int m = 0; m < 4; ++m) _Pragma("unroll") for (int k = 0; k < 2; ++k) dst[m][k] = *(const LAS bf16x8*)(lds + PG8_SA(b, h) + aoff + m * 2048 + k * 1024); } while (0)
; #define PG8_MMA(ai, bj, At, Bt) do { __builtin_amdgcn_s_setprio(1); _Pragma("unroll") for (int m = 0; m < 4; ++m) _Pragma("unroll") for (int n = 0; n < 2; ++n) _Pragma("unroll") for (int k = 0; k < 2; ++k) \
;         acc[ai][bj][m][n] = __builtin_amdgcn_mfma_f32_16x16x32_bf16(Bt[n][k], At[m][k], acc[ai][bj][m][n], 0, 0, 0); __builtin_amdgcn_s_setprio(0); } while (0)
; #define PG8_WAIT_V(n) asm volatile("s_waitcnt vmcnt(" #n ")" ::: "memory")
; #define PG8_WAIT_L(n) asm volatile("s_waitcnt lgkmcnt(" #n ")" ::: "memory")
; #define PG8_BAR __builtin_amdgcn_s_barrier()
; #define PG8_SCHED __builtin_amdgcn_sched_barrier(0)
;     DI void operator()(Acc& acc, const Unit& u, int wr, int wc, int fr, int fq, LAS unsigned char* lds) const {
;     ...
;             for (int m = 0; m < 4; ++m) { const int row = u.pm * BM + ai * HALF + wr * 64 + m * 16 + fr;
;                 float rs = 1.0f; if (sumsq) { const f32x4 q4 = *(const f32x4*)(sumsq + (size_t)row * 4); rs = rsqrtf(((q4.x + q4.y) + (q4.z + q4.w)) * (1.0f / DM) + EPS); } float ss = 0.f;
; template <class GEO, class Epi>
; __device__ __forceinline__ void gemm_phase(LAS unsigned char* lds, const Gemm g, const StaticOrder& S, const Epi& E) {
;     ...
;             PG8_LDA(At, 1, 1); PG8_STAGE(PG8_SB(1, 0), b3, voffB); PG8_STAGE(PG8_SB(1, 1), b3 + hstepB, voffB); PG8_STAGE(PG8_SA(1, 0), a3, voffA);
;             PG8_WAIT_V(8); PG8_WAIT_L(0); PG8_BAR; PG8_MMA(1, 0, At, B0); PG8_MMA(1, 1, At, B1); PG8_BAR; PG8_SCHED;
;         }
;         if (wr == 0) PG8_BAR;
	s_add_i32 s8, s38, s0
	v_lshl_add_u64 v[160:161], v[160:161], 0, s[28:29]
	s_mov_b32 m0, s8
	ds_read_b128 v[202:205], v183 offset:49152
	ds_read_b128 v[212:215], v183 offset:50176
	ds_read_b128 v[216:219], v183 offset:51200
	ds_read_b128 v[220:223], v183 offset:52224
	ds_read_b128 v[224:227], v183 offset:53248
	ds_read_b128 v[228:231], v183 offset:54272
	ds_read_b128 v[232:235], v183 offset:55296
	ds_read_b128 v[236:239], v183 offset:56320
	global_load_lds_dwordx4 v[160:161], off
	s_add_i32 m0, s8, 0x2000
	s_add_u32 s8, s54, 0x40080
	v_lshl_add_u64 v[160:161], v[170:171], 0, s[28:29]
	s_addc_u32 s9, s55, 0
	s_add_i32 s38, s39, s0
	global_load_lds_dwordx4 v[160:161], off
	v_lshl_add_u64 v[160:161], s[8:9], 0, v[130:131]
	s_mov_b32 m0, s38
	s_nop 0
	global_load_lds_dwordx4 v[160:161], off
	v_lshl_add_u64 v[160:161], s[8:9], 0, v[134:135]
	s_add_i32 m0, s38, 0x2000
	s_nop 0
	global_load_lds_dwordx4 v[160:161], off
	v_lshl_add_u64 v[160:161], v[206:207], 0, s[28:29]
	s_mov_b32 m0, s7
	s_nop 0
	global_load_lds_dwordx4 v[160:161], off
	v_lshl_add_u64 v[160:161], v[240:241], 0, s[28:29]
	s_mov_b32 m0, s12
	s_nop 0
	global_load_lds_dwordx4 v[160:161], off
	s_waitcnt vmcnt(8)
	s_waitcnt lgkmcnt(0)
	s_barrier
	s_waitcnt lgkmcnt(0)
	v_mfma_f32_16x16x32_bf16 v[60:63], v[148:151], v[202:205], v[60:63]
	v_mfma_f32_16x16x32_bf16 v[56:59], v[156:159], v[202:205], v[56:59]
	v_mfma_f32_16x16x32_bf16 v[48:51], v[148:151], v[216:219], v[48:51]
	v_mfma_f32_16x16x32_bf16 v[40:43], v[156:159], v[216:219], v[40:43]
	v_mfma_f32_16x16x32_bf16 v[32:35], v[148:151], v[224:227], v[32:35]
	v_mfma_f32_16x16x32_bf16 v[24:27], v[156:159], v[224:227], v[24:27]
	v_mfma_f32_16x16x32_bf16 v[16:19], v[148:151], v[232:235], v[16:19]
	v_mfma_f32_16x16x32_bf16 v[8:11], v[156:159], v[232:235], v[8:11]
	v_mfma_f32_16x16x32_bf16 v[60:63], v[152:155], v[212:215], v[60:63]
	v_mfma_f32_16x16x32_bf16 v[56:59], v[166:169], v[212:215], v[56:59]
	v_mfma_f32_16x16x32_bf16 v[48:51], v[152:155], v[220:223], v[48:51]
	v_mfma_f32_16x16x32_bf16 v[40:43], v[166:169], v[220:223], v[40:43]
	v_mfma_f32_16x16x32_bf16 v[32:35], v[152:155], v[228:231], v[32:35]
	v_mfma_f32_16x16x32_bf16 v[24:27], v[166:169], v[228:231], v[24:27]
	v_mfma_f32_16x16x32_bf16 v[16:19], v[152:155], v[236:239], v[16:19]
	v_mfma_f32_16x16x32_bf16 v[8:11], v[166:169], v[236:239], v[8:11]
	v_mfma_f32_16x16x32_bf16 v[52:55], v[186:189], v[202:205], v[52:55]
	v_mfma_f32_16x16x32_bf16 v[44:47], v[194:197], v[202:205], v[44:47]
	v_mfma_f32_16x16x32_bf16 v[36:39], v[186:189], v[216:219], v[36:39]
	v_mfma_f32_16x16x32_bf16 v[28:31], v[194:197], v[216:219], v[28:31]
	v_mfma_f32_16x16x32_bf16 v[20:23], v[186:189], v[224:227], v[20:23]
	v_mfma_f32_16x16x32_bf16 v[12:15], v[194:197], v[224:227], v[12:15]
	v_mfma_f32_16x16x32_bf16 v[4:7], v[186:189], v[232:235], v[4:7]
	v_mfma_f32_16x16x32_bf16 v[0:3], v[194:197], v[232:235], v[0:3]
	v_mfma_f32_16x16x32_bf16 v[52:55], v[190:193], v[212:215], v[52:55]
	v_mfma_f32_16x16x32_bf16 v[44:47], v[198:201], v[212:215], v[44:47]
	v_mfma_f32_16x16x32_bf16 v[36:39], v[190:193], v[220:223], v[36:39]
	v_mfma_f32_16x16x32_bf16 v[28:31], v[198:201], v[220:223], v[28:31]
	v_mfma_f32_16x16x32_bf16 v[20:23], v[190:193], v[228:231], v[20:23]
	v_mfma_f32_16x16x32_bf16 v[12:15], v[198:201], v[228:231], v[12:15]
	v_mfma_f32_16x16x32_bf16 v[4:7], v[190:193], v[236:239], v[4:7]
	v_mfma_f32_16x16x32_bf16 v[0:3], v[198:201], v[236:239], v[0:3]
	s_barrier
	s_add_i32 s69, s69, 2
	s_add_u32 s52, s52, 0x100
	s_addc_u32 s53, s53, 0
	s_add_u32 s67, s67, 0x100
	s_addc_u32 s68, s68, 0
	s_cmp_gt_u32 s69, 13
	s_cbranch_scc0 .LBB0_779
	v_lshl_add_u32 v244, s44, 8, v173
	v_ashrrev_i32_e32 v245, 31, v244
	v_lshl_add_u64 v[244:245], v[244:245], 4, s[76:77]
	global_load_dwordx4 v[212:215], v[244:245], off
	global_load_dwordx4 v[216:219], v[244:245], off offset:256
	global_load_dwordx4 v[220:223], v[244:245], off offset:512
	global_load_dwordx4 v[224:227], v[244:245], off offset:768
	global_load_dwordx4 v[228:231], v[244:245], off offset:2048
	global_load_dwordx4 v[232:235], v[244:245], off offset:2304
	global_load_dwordx4 v[236:239], v[244:245], off offset:2560
	global_load_dwordx4 v[240:243], v[244:245], off offset:2816
	s_and_b64 vcc, exec, s[30:31]
	s_cbranch_vccz .LBB0_782
	s_barrier

; #define PG8_STAGE(bufoff, gbase, voff) do { _Pragma("unroll") for (int _i = 0; _i < 2; ++_i) \
;         __builtin_amdgcn_global_load_lds((const unsigned*)((const char*)(gbase) + (voff)[_i]), (LAS unsigned*)(lds + (bufoff) + ldsw + _i * 8192), 16, 0, 0); } while (0)
; #define PG8_LDA(dst, b, h) do { _Pragma("unroll") for (int m = 0; m < 4; ++m) _Pragma("unroll") for (int k = 0; k < 2; ++k) dst[m][k] = *(const LAS bf16x8*)(lds + PG8_SA(b, h) + aoff + m * 2048 + k * 1024); } while (0)
; #define PG8_LDB(dst, b, h) do { _Pragma("unroll") for (int n = 0; n < 2; ++n) _Pragma("unroll") for (int k = 0; k < 2; ++k) dst[n][k] = *(const LAS bf16x8*)(lds + PG8_SB(b, h) + boff + n * 2048 + k * 1024); } while (0)
; #define PG8_MMA(ai, bj, At, Bt) do { __builtin_amdgcn_s_setprio(1); _Pragma("unroll") for (int m = 0; m < 4; ++m) _Pragma("unroll") for (int n = 0; n < 2; ++n) _Pragma("unroll") for (int k = 0; k < 2; ++k) \
;         acc[ai][bj][m][n] = __builtin_amdgcn_mfma_f32_16x16x32_bf16(Bt[n][k], At[m][k], acc[ai][bj][m][n], 0, 0, 0); __builtin_amdgcn_s_setprio(0); } while (0)
; #define PG8_WAIT_V(n) asm volatile("s_waitcnt vmcnt(" #n ")" ::: "memory")
; #define PG8_WAIT_L(n) asm volatile("s_waitcnt lgkmcnt(" #n ")" ::: "memory")
; #define PG8_BAR __builtin_amdgcn_s_barrier()
; #define PG8_SCHED __builtin_amdgcn_sched_barrier(0)
; template <class GEO, class Epi>
; __device__ __forceinline__ void gemm_phase(LAS unsigned char* lds, const Gemm g, const StaticOrder& S, const Epi& E) {
;     ...
;         for (int t = 0; t < nt; t += 2) {
;             const bool last = (t == nt - 2);
;             const char* a1 = cA + (size_t)(t + 1) * kstep;
;             const char* a2 = last ? nA : cA + (size_t)(t + 2) * kstep; const char* b2 = last ? nB : cB + (size_t)(t + 2) * kstep;
;             const char* a3 = a2 + kstep; const char* b3 = b2 + kstep;
;             PG8_LDB(B0, 0, 0); PG8_LDB(B1, 0, 1); PG8_SCHED; PG8_LDA(At, 0, 0); PG8_STAGE(PG8_SA(1, 1), a1 + hstepA, voffA);
;             PG8_WAIT_V(8); PG8_WAIT_L(0); PG8_BAR; PG8_MMA(0, 0, At, B0); PG8_MMA(0, 1, At, B1); PG8_BAR; PG8_SCHED;
;             PG8_LDA(At, 0, 1); PG8_STAGE(PG8_SB(0, 0), b2, voffB); PG8_STAGE(PG8_SB(0, 1), b2 + hstepB, voffB); PG8_STAGE(PG8_SA(0, 0), a2, voffA);
;             PG8_WAIT_V(8); PG8_WAIT_L(0); PG8_BAR; PG8_MMA(1, 0, At, B0); PG8_MMA(1, 1, At, B1); PG8_BAR; PG8_SCHED;
.LBB0_882:
	s_add_u32 s38, s54, s60
	s_addc_u32 s39, s55, s61
	s_add_u32 s62, s38, 0x100
	s_addc_u32 s63, s39, 0
	s_and_b64 s[8:9], s[58:59], exec
	s_cselect_b32 s63, s20, s63
	s_cselect_b32 s62, s45, s62
	s_add_u32 s8, s52, s60
	s_addc_u32 s9, s53, s61
	s_add_u32 s60, s8, 0x100
	s_addc_u32 s61, s9, 0
	s_and_b64 s[8:9], s[58:59], exec
	s_cselect_b32 s65, s51, s61
	s_cselect_b32 s64, s91, s60
	s_add_u32 s68, s38, 0x40080
	ds_read_b128 v[128:131], v177
	ds_read_b128 v[132:135], v177 offset:1024
	ds_read_b128 v[136:139], v177 offset:2048
	ds_read_b128 v[140:143], v177 offset:3072
	ds_read_b128 v[144:147], v178
	ds_read_b128 v[166:169], v178 offset:1024
	ds_read_b128 v[170:173], v178 offset:2048
	ds_read_b128 v[180:183], v178 offset:3072
	s_addc_u32 s69, s39, 0
	s_add_i32 s9, s85, s0
	s_add_i32 m0, s22, 0xc000
	s_add_i32 s1, s22, 0xe000
	s_add_i32 s38, s9, 0x2000
	s_add_u32 s66, s64, 0x40000
	s_addc_u32 s67, s65, 0
	s_add_i32 s39, s86, s0
	s_add_i32 s8, s39, 0x2000
	s_add_i32 vcc_hi, 0, 0x18000
	s_add_i32 vcc_lo, 0, 0x1c000
	s_add_u32 s60, s62, 0x40000
	s_addc_u32 s61, s63, 0
	s_add_i32 s95, vcc_hi, s0
	s_add_i32 s93, s95, 0x2000
	s_add_u32 s58, s64, 0x40080
	s_addc_u32 s59, s65, 0
	s_add_i32 s94, vcc_lo, s0
	s_add_i32 s92, s94, 0x2000
	v_lshl_add_u64 v[220:221], s[68:69], 0, v[148:149]
	ds_read_b128 v[184:187], v179
	ds_read_b128 v[188:191], v179 offset:1024
	ds_read_b128 v[192:195], v179 offset:2048
	ds_read_b128 v[196:199], v179 offset:3072
	ds_read_b128 v[200:203], v179 offset:4096
	ds_read_b128 v[204:207], v179 offset:5120
	ds_read_b128 v[212:215], v179 offset:6144
	ds_read_b128 v[216:219], v179 offset:7168
	global_load_lds_dwordx4 v[220:221], off
	v_lshl_add_u64 v[220:221], s[68:69], 0, v[152:153]
	s_mov_b32 m0, s1
	s_nop 0
	global_load_lds_dwordx4 v[220:221], off
	s_waitcnt vmcnt(8)
	s_waitcnt lgkmcnt(0)
	s_barrier
	s_waitcnt lgkmcnt(0)
	v_mfma_f32_16x16x32_bf16 v[124:127], v[128:131], v[184:187], v[124:127]
	v_mfma_f32_16x16x32_bf16 v[120:123], v[136:139], v[184:187], v[120:123]
	v_mfma_f32_16x16x32_bf16 v[108:111], v[128:131], v[192:195], v[108:111]
	v_mfma_f32_16x16x32_bf16 v[104:107], v[136:139], v[192:195], v[104:107]
	v_mfma_f32_16x16x32_bf16 v[92:95], v[128:131], v[200:203], v[92:95]
	v_mfma_f32_16x16x32_bf16 v[88:91], v[136:139], v[200:203], v[88:91]
	v_mfma_f32_16x16x32_bf16 v[76:79], v[128:131], v[212:215], v[76:79]
	v_mfma_f32_16x16x32_bf16 v[72:75], v[136:139], v[212:215], v[72:75]
	v_mfma_f32_16x16x32_bf16 v[124:127], v[132:135], v[188:191], v[124:127]
	v_mfma_f32_16x16x32_bf16 v[120:123], v[140:143], v[188:191], v[120:123]
	v_mfma_f32_16x16x32_bf16 v[108:111], v[132:135], v[196:199], v[108:111]
	v_mfma_f32_16x16x32_bf16 v[104:107], v[140:143], v[196:199], v[104:107]
	v_mfma_f32_16x16x32_bf16 v[92:95], v[132:135], v[204:207], v[92:95]
	v_mfma_f32_16x16x32_bf16 v[88:91], v[140:143], v[204:207], v[88:91]
	v_mfma_f32_16x16x32_bf16 v[76:79], v[132:135], v[216:219], v[76:79]
	v_mfma_f32_16x16x32_bf16 v[72:75], v[140:143], v[216:219], v[72:75]
	v_mfma_f32_16x16x32_bf16 v[116:119], v[144:147], v[184:187], v[116:119]
	v_mfma_f32_16x16x32_bf16 v[112:115], v[170:173], v[184:187], v[112:115]
	v_mfma_f32_16x16x32_bf16 v[100:103], v[144:147], v[192:195], v[100:103]
	v_mfma_f32_16x16x32_bf16 v[96:99], v[170:173], v[192:195], v[96:99]
	v_mfma_f32_16x16x32_bf16 v[84:87], v[144:147], v[200:203], v[84:87]
	v_mfma_f32_16x16x32_bf16 v[80:83], v[170:173], v[200:203], v[80:83]
	v_mfma_f32_16x16x32_bf16 v[68:71], v[144:147], v[212:215], v[68:71]
	v_mfma_f32_16x16x32_bf16 v[64:67], v[170:173], v[212:215], v[64:67]
	v_mfma_f32_16x16x32_bf16 v[116:119], v[166:169], v[188:191], v[116:119]
	v_mfma_f32_16x16x32_bf16 v[112:115], v[180:183], v[188:191], v[112:115]
	v_mfma_f32_16x16x32_bf16 v[100:103], v[166:169], v[196:199], v[100:103]
	v_mfma_f32_16x16x32_bf16 v[96:99], v[180:183], v[196:199], v[96:99]
	v_mfma_f32_16x16x32_bf16 v[84:87], v[166:169], v[204:207], v[84:87]
	v_mfma_f32_16x16x32_bf16 v[80:83], v[180:183], v[204:207], v[80:83]
	v_mfma_f32_16x16x32_bf16 v[68:71], v[166:169], v[216:219], v[68:71]
	v_mfma_f32_16x16x32_bf16 v[64:67], v[180:183], v[216:219], v[64:67]
	s_barrier
	s_mov_b32 m0, s9
	v_lshl_add_u64 v[220:221], s[64:65], 0, v[150:151]
	ds_read_b128 v[184:187], v179 offset:16384
	ds_read_b128 v[188:191], v179 offset:17408
	ds_read_b128 v[192:195], v179 offset:18432
	ds_read_b128 v[196:199], v179 offset:19456
	ds_read_b128 v[200:203], v179 offset:20480
	ds_read_b128 v[204:207], v179 offset:21504
	ds_read_b128 v[212:215], v179 offset:22528
	ds_read_b128 v[216:219], v179 offset:23552
	global_load_lds_dwordx4 v[220:221], off
	v_lshl_add_u64 v[222:223], s[64:65], 0, v[154:155]
	s_mov_b32 m0, s38
	v_lshl_add_u64 v[224:225], s[66:67], 0, v[150:151]
	global_load_lds_dwordx4 v[222:223], off
	s_mov_b32 m0, s39
	v_lshl_add_u64 v[226:227], s[62:63], 0, v[152:153]
	global_load_lds_dwordx4 v[224:225], off
	v_lshl_add_u64 v[224:225], s[66:67], 0, v[154:155]
	s_mov_b32 m0, s8
	s_nop 0
	global_load_lds_dwordx4 v[224:225], off
	v_lshl_add_u64 v[224:225], s[62:63], 0, v[148:149]
	s_mov_b32 m0, s22
	s_nop 0
	global_load_lds_dwordx4 v[224:225], off
	s_mov_b32 m0, s4
	s_nop 0
	global_load_lds_dwordx4 v[226:227], off
	s_waitcnt vmcnt(8)
	s_waitcnt lgkmcnt(0)
	s_barrier
; #define PG8_STAGE(bufoff, gbase, voff) do { _Pragma("unroll") for (int _i = 0; _i < 2; ++_i) \
;         __builtin_amdgcn_global_load_lds((const unsigned*)((const char*)(gbase) + (voff)[_i]), (LAS unsigned*)(lds + (bufoff) + ldsw + _i * 8192), 16, 0, 0); } while (0)
; #define PG8_LDA(dst, b, h) do { _Pragma("unroll") for (int m = 0; m < 4; ++m) _Pragma("unroll") for (int k = 0; k < 2; ++k) dst[m][k] = *(const LAS bf16x8*)(lds + PG8_SA(b, h) + aoff + m * 2048 + k * 1024); } while (0)
; #define PG8_LDB(dst, b, h) do { _Pragma("unroll") for (int n = 0; n < 2; ++n) _Pragma("unroll") for (int k = 0; k < 2; ++k) dst[n][k] = *(const LAS bf16x8*)(lds + PG8_SB(b, h) + boff + n * 2048 + k * 1024); } while (0)
; #define PG8_MMA(ai, bj, At, Bt) do { __builtin_amdgcn_s_setprio(1); _Pragma("unroll") for (int m = 0; m < 4; ++m) _Pragma("unroll") for (int n = 0; n < 2; ++n) _Pragma("unroll") for (int k = 0; k < 2; ++k) \
;         acc[ai][bj][m][n] = __builtin_amdgcn_mfma_f32_16x16x32_bf16(Bt[n][k], At[m][k], acc[ai][bj][m][n], 0, 0, 0); __builtin_amdgcn_s_setprio(0); } while (0)
; #define PG8_WAIT_V(n) asm volatile("s_waitcnt vmcnt(" #n ")" ::: "memory")
; #define PG8_WAIT_L(n) asm volatile("s_waitcnt lgkmcnt(" #n ")" ::: "memory")
; #define PG8_BAR __builtin_amdgcn_s_barrier()
; #define PG8_SCHED __builtin_amdgcn_sched_barrier(0)
; template <class GEO, class Epi>
; __device__ __forceinline__ void gemm_phase(LAS unsigned char* lds, const Gemm g, const StaticOrder& S, const Epi& E) {
;     ...
;             PG8_WAIT_V(8); PG8_WAIT_L(0); PG8_BAR; PG8_MMA(1, 0, At, B0); PG8_MMA(1, 1, At, B1); PG8_BAR; PG8_SCHED;
;             PG8_LDB(B0, 1, 0); PG8_LDB(B1, 1, 1); PG8_SCHED; PG8_LDA(At, 1, 0); PG8_STAGE(PG8_SA(0, 1), a2 + hstepA, voffA);
;             PG8_WAIT_V(8); PG8_WAIT_L(0); PG8_BAR; PG8_MMA(0, 0, At, B0); PG8_MMA(0, 1, At, B1); PG8_BAR; PG8_SCHED;
	s_waitcnt lgkmcnt(0)
	v_mfma_f32_16x16x32_bf16 v[60:63], v[128:131], v[184:187], v[60:63]
	v_mfma_f32_16x16x32_bf16 v[56:59], v[136:139], v[184:187], v[56:59]
	v_mfma_f32_16x16x32_bf16 v[44:47], v[128:131], v[192:195], v[44:47]
	v_mfma_f32_16x16x32_bf16 v[40:43], v[136:139], v[192:195], v[40:43]
	v_mfma_f32_16x16x32_bf16 v[28:31], v[128:131], v[200:203], v[28:31]
	v_mfma_f32_16x16x32_bf16 v[24:27], v[136:139], v[200:203], v[24:27]
	v_mfma_f32_16x16x32_bf16 v[12:15], v[128:131], v[212:215], v[12:15]
	v_mfma_f32_16x16x32_bf16 v[8:11], v[136:139], v[212:215], v[8:11]
	v_mfma_f32_16x16x32_bf16 v[60:63], v[132:135], v[188:191], v[60:63]
	v_mfma_f32_16x16x32_bf16 v[56:59], v[140:143], v[188:191], v[56:59]
	v_mfma_f32_16x16x32_bf16 v[44:47], v[132:135], v[196:199], v[44:47]
	v_mfma_f32_16x16x32_bf16 v[40:43], v[140:143], v[196:199], v[40:43]
	v_mfma_f32_16x16x32_bf16 v[28:31], v[132:135], v[204:207], v[28:31]
	v_mfma_f32_16x16x32_bf16 v[24:27], v[140:143], v[204:207], v[24:27]
	v_mfma_f32_16x16x32_bf16 v[12:15], v[132:135], v[216:219], v[12:15]
	v_mfma_f32_16x16x32_bf16 v[8:11], v[140:143], v[216:219], v[8:11]
	v_mfma_f32_16x16x32_bf16 v[52:55], v[144:147], v[184:187], v[52:55]
	v_mfma_f32_16x16x32_bf16 v[48:51], v[170:173], v[184:187], v[48:51]
	v_mfma_f32_16x16x32_bf16 v[36:39], v[144:147], v[192:195], v[36:39]
	v_mfma_f32_16x16x32_bf16 v[32:35], v[170:173], v[192:195], v[32:35]
	v_mfma_f32_16x16x32_bf16 v[20:23], v[144:147], v[200:203], v[20:23]
	v_mfma_f32_16x16x32_bf16 v[16:19], v[170:173], v[200:203], v[16:19]
	v_mfma_f32_16x16x32_bf16 v[4:7], v[144:147], v[212:215], v[4:7]
	v_mfma_f32_16x16x32_bf16 v[0:3], v[170:173], v[212:215], v[0:3]
	v_mfma_f32_16x16x32_bf16 v[52:55], v[166:169], v[188:191], v[52:55]
	v_mfma_f32_16x16x32_bf16 v[48:51], v[180:183], v[188:191], v[48:51]
	v_mfma_f32_16x16x32_bf16 v[36:39], v[166:169], v[196:199], v[36:39]
	v_mfma_f32_16x16x32_bf16 v[32:35], v[180:183], v[196:199], v[32:35]
	v_mfma_f32_16x16x32_bf16 v[20:23], v[166:169], v[204:207], v[20:23]
	v_mfma_f32_16x16x32_bf16 v[16:19], v[180:183], v[204:207], v[16:19]
	v_mfma_f32_16x16x32_bf16 v[4:7], v[166:169], v[216:219], v[4:7]
	v_mfma_f32_16x16x32_bf16 v[0:3], v[180:183], v[216:219], v[0:3]
	s_barrier
	v_add_u32_e32 v140, vcc_hi, v175
	v_add_u32_e32 v180, vcc_lo, v175
	ds_read_b128 v[128:131], v140
	ds_read_b128 v[132:135], v140 offset:1024
	ds_read_b128 v[136:139], v140 offset:2048
	ds_read_b128 v[140:143], v140 offset:3072
	ds_read_b128 v[144:147], v180
	ds_read_b128 v[166:169], v180 offset:1024
	ds_read_b128 v[170:173], v180 offset:2048
	ds_read_b128 v[180:183], v180 offset:3072
	s_mov_b32 m0, s5
	v_lshl_add_u64 v[228:229], s[60:61], 0, v[148:149]
	ds_read_b128 v[184:187], v179 offset:32768
	ds_read_b128 v[188:191], v179 offset:33792
	ds_read_b128 v[192:195], v179 offset:34816
	ds_read_b128 v[196:199], v179 offset:35840
	ds_read_b128 v[200:203], v179 offset:36864
	ds_read_b128 v[204:207], v179 offset:37888
	ds_read_b128 v[212:215], v179 offset:38912
	ds_read_b128 v[216:219], v179 offset:39936
	global_load_lds_dwordx4 v[228:229], off
	v_lshl_add_u64 v[228:229], s[60:61], 0, v[152:153]
	s_mov_b32 m0, s6
	s_nop 0
	global_load_lds_dwordx4 v[228:229], off
	s_waitcnt vmcnt(8)
	s_waitcnt lgkmcnt(0)
	s_barrier
	s_waitcnt lgkmcnt(0)
	v_mfma_f32_16x16x32_bf16 v[124:127], v[128:131], v[184:187], v[124:127]
	v_mfma_f32_16x16x32_bf16 v[120:123], v[136:139], v[184:187], v[120:123]
	v_mfma_f32_16x16x32_bf16 v[108:111], v[128:131], v[192:195], v[108:111]
	v_mfma_f32_16x16x32_bf16 v[104:107], v[136:139], v[192:195], v[104:107]
	v_mfma_f32_16x16x32_bf16 v[92:95], v[128:131], v[200:203], v[92:95]
	v_mfma_f32_16x16x32_bf16 v[88:91], v[136:139], v[200:203], v[88:91]
	v_mfma_f32_16x16x32_bf16 v[76:79], v[128:131], v[212:215], v[76:79]
	v_mfma_f32_16x16x32_bf16 v[72:75], v[136:139], v[212:215], v[72:75]
	v_mfma_f32_16x16x32_bf16 v[124:127], v[132:135], v[188:191], v[124:127]
	v_mfma_f32_16x16x32_bf16 v[120:123], v[140:143], v[188:191], v[120:123]
	v_mfma_f32_16x16x32_bf16 v[108:111], v[132:135], v[196:199], v[108:111]
	v_mfma_f32_16x16x32_bf16 v[104:107], v[140:143], v[196:199], v[104:107]
	v_mfma_f32_16x16x32_bf16 v[92:95], v[132:135], v[204:207], v[92:95]
	v_mfma_f32_16x16x32_bf16 v[88:91], v[140:143], v[204:207], v[88:91]
	v_mfma_f32_16x16x32_bf16 v[76:79], v[132:135], v[216:219], v[76:79]
	v_mfma_f32_16x16x32_bf16 v[72:75], v[140:143], v[216:219], v[72:75]
	v_mfma_f32_16x16x32_bf16 v[116:119], v[144:147], v[184:187], v[116:119]
	v_mfma_f32_16x16x32_bf16 v[112:115], v[170:173], v[184:187], v[112:115]
	v_mfma_f32_16x16x32_bf16 v[100:103], v[144:147], v[192:195], v[100:103]
	v_mfma_f32_16x16x32_bf16 v[96:99], v[170:173], v[192:195], v[96:99]
	v_mfma_f32_16x16x32_bf16 v[84:87], v[144:147], v[200:203], v[84:87]
	v_mfma_f32_16x16x32_bf16 v[80:83], v[170:173], v[200:203], v[80:83]
	v_mfma_f32_16x16x32_bf16 v[68:71], v[144:147], v[212:215], v[68:71]
	v_mfma_f32_16x16x32_bf16 v[64:67], v[170:173], v[212:215], v[64:67]
	v_mfma_f32_16x16x32_bf16 v[116:119], v[166:169], v[188:191], v[116:119]
	v_mfma_f32_16x16x32_bf16 v[112:115], v[180:183], v[188:191], v[112:115]
	v_mfma_f32_16x16x32_bf16 v[100:103], v[166:169], v[196:199], v[100:103]
	v_mfma_f32_16x16x32_bf16 v[96:99], v[180:183], v[196:199], v[96:99]
	v_mfma_f32_16x16x32_bf16 v[84:87], v[166:169], v[204:207], v[84:87]
	v_mfma_f32_16x16x32_bf16 v[80:83], v[180:183], v[204:207], v[80:83]
	v_mfma_f32_16x16x32_bf16 v[68:71], v[166:169], v[216:219], v[68:71]
	v_mfma_f32_16x16x32_bf16 v[64:67], v[180:183], v[216:219], v[64:67]
	s_barrier
; #define PG8_STAGE(bufoff, gbase, voff) do { _Pragma("unroll") for (int _i = 0; _i < 2; ++_i) \
;         __builtin_amdgcn_global_load_lds((const unsigned*)((const char*)(gbase) + (voff)[_i]), (LAS unsigned*)(lds + (bufoff) + ldsw + _i * 8192), 16, 0, 0); } while (0)
; #define PG8_LDA(dst, b, h) do { _Pragma("unroll") for (int m = 0; m < 4; ++m) _Pragma("unroll") for (int k = 0; k < 2; ++k) dst[m][k] = *(const LAS bf16x8*)(lds + PG8_SA(b, h) + aoff + m * 2048 + k * 1024); } while (0)
; #define PG8_MMA(ai, bj, At, Bt) do { __builtin_amdgcn_s_setprio(1); _Pragma("unroll") for (int m = 0; m < 4; ++m) _Pragma("unroll") for (int n = 0; n < 2; ++n) _Pragma("unroll") for (int k = 0; k < 2; ++k) \
;         acc[ai][bj][m][n] = __builtin_amdgcn_mfma_f32_16x16x32_bf16(Bt[n][k], At[m][k], acc[ai][bj][m][n], 0, 0, 0); __builtin_amdgcn_s_setprio(0); } while (0)
; #define PG8_WAIT_V(n) asm volatile("s_waitcnt vmcnt(" #n ")" ::: "memory")
; #define PG8_WAIT_L(n) asm volatile("s_waitcnt lgkmcnt(" #n ")" ::: "memory")
; #define PG8_BAR __builtin_amdgcn_s_barrier()
; #define PG8_SCHED __builtin_amdgcn_sched_barrier(0)
; template <class GEO, class Epi>
; __device__ __forceinline__ void gemm_phase(LAS unsigned char* lds, const Gemm g, const StaticOrder& S, const Epi& E) {
;     ...
;             PG8_LDA(At, 1, 1); PG8_STAGE(PG8_SB(1, 0), b3, voffB); PG8_STAGE(PG8_SB(1, 1), b3 + hstepB, voffB); PG8_STAGE(PG8_SA(1, 0), a3, voffA);
;             PG8_WAIT_V(8); PG8_WAIT_L(0); PG8_BAR; PG8_MMA(1, 0, At, B0); PG8_MMA(1, 1, At, B1); PG8_BAR; PG8_SCHED;
;         }
;         if (wr == 0) PG8_BAR;
	s_mov_b32 m0, s95
	v_lshl_add_u64 v[220:221], v[220:221], 0, s[28:29]
	ds_read_b128 v[184:187], v179 offset:49152
	ds_read_b128 v[188:191], v179 offset:50176
	ds_read_b128 v[192:195], v179 offset:51200
	ds_read_b128 v[196:199], v179 offset:52224
	ds_read_b128 v[200:203], v179 offset:53248
	ds_read_b128 v[204:207], v179 offset:54272
	ds_read_b128 v[212:215], v179 offset:55296
	ds_read_b128 v[216:219], v179 offset:56320
	global_load_lds_dwordx4 v[220:221], off
	v_lshl_add_u64 v[220:221], v[222:223], 0, s[28:29]
	s_mov_b32 m0, s93
	s_nop 0
	global_load_lds_dwordx4 v[220:221], off
	v_lshl_add_u64 v[220:221], s[58:59], 0, v[150:151]
	s_mov_b32 m0, s94
	s_nop 0
	global_load_lds_dwordx4 v[220:221], off
	v_lshl_add_u64 v[220:221], s[58:59], 0, v[154:155]
	s_mov_b32 m0, s92
	s_nop 0
	global_load_lds_dwordx4 v[220:221], off
	v_lshl_add_u64 v[220:221], v[224:225], 0, s[28:29]
	s_mov_b32 m0, s7
	s_nop 0
	global_load_lds_dwordx4 v[220:221], off
	v_lshl_add_u64 v[220:221], v[226:227], 0, s[28:29]
	s_mov_b32 m0, s12
	s_nop 0
	global_load_lds_dwordx4 v[220:221], off
	s_waitcnt vmcnt(8)
	s_waitcnt lgkmcnt(0)
	s_barrier
	s_waitcnt lgkmcnt(0)
	v_mfma_f32_16x16x32_bf16 v[60:63], v[128:131], v[184:187], v[60:63]
	v_mfma_f32_16x16x32_bf16 v[56:59], v[136:139], v[184:187], v[56:59]
	v_mfma_f32_16x16x32_bf16 v[44:47], v[128:131], v[192:195], v[44:47]
	v_mfma_f32_16x16x32_bf16 v[40:43], v[136:139], v[192:195], v[40:43]
	v_mfma_f32_16x16x32_bf16 v[28:31], v[128:131], v[200:203], v[28:31]
	v_mfma_f32_16x16x32_bf16 v[24:27], v[136:139], v[200:203], v[24:27]
	v_mfma_f32_16x16x32_bf16 v[12:15], v[128:131], v[212:215], v[12:15]
	v_mfma_f32_16x16x32_bf16 v[8:11], v[136:139], v[212:215], v[8:11]
	v_mfma_f32_16x16x32_bf16 v[60:63], v[132:135], v[188:191], v[60:63]
	v_mfma_f32_16x16x32_bf16 v[56:59], v[140:143], v[188:191], v[56:59]
	v_mfma_f32_16x16x32_bf16 v[44:47], v[132:135], v[196:199], v[44:47]
	v_mfma_f32_16x16x32_bf16 v[40:43], v[140:143], v[196:199], v[40:43]
	v_mfma_f32_16x16x32_bf16 v[28:31], v[132:135], v[204:207], v[28:31]
	v_mfma_f32_16x16x32_bf16 v[24:27], v[140:143], v[204:207], v[24:27]
	v_mfma_f32_16x16x32_bf16 v[12:15], v[132:135], v[216:219], v[12:15]
	v_mfma_f32_16x16x32_bf16 v[8:11], v[140:143], v[216:219], v[8:11]
	v_mfma_f32_16x16x32_bf16 v[52:55], v[144:147], v[184:187], v[52:55]
	v_mfma_f32_16x16x32_bf16 v[48:51], v[170:173], v[184:187], v[48:51]
	v_mfma_f32_16x16x32_bf16 v[36:39], v[144:147], v[192:195], v[36:39]
	v_mfma_f32_16x16x32_bf16 v[32:35], v[170:173], v[192:195], v[32:35]
	v_mfma_f32_16x16x32_bf16 v[20:23], v[144:147], v[200:203], v[20:23]
	v_mfma_f32_16x16x32_bf16 v[16:19], v[170:173], v[200:203], v[16:19]
	v_mfma_f32_16x16x32_bf16 v[4:7], v[144:147], v[212:215], v[4:7]
	v_mfma_f32_16x16x32_bf16 v[0:3], v[170:173], v[212:215], v[0:3]
	v_mfma_f32_16x16x32_bf16 v[52:55], v[166:169], v[188:191], v[52:55]
	v_mfma_f32_16x16x32_bf16 v[48:51], v[180:183], v[188:191], v[48:51]
	v_mfma_f32_16x16x32_bf16 v[36:39], v[166:169], v[196:199], v[36:39]
	v_mfma_f32_16x16x32_bf16 v[32:35], v[180:183], v[196:199], v[32:35]
	v_mfma_f32_16x16x32_bf16 v[20:23], v[166:169], v[204:207], v[20:23]
	v_mfma_f32_16x16x32_bf16 v[16:19], v[180:183], v[204:207], v[16:19]
	v_mfma_f32_16x16x32_bf16 v[4:7], v[166:169], v[216:219], v[4:7]
	v_mfma_f32_16x16x32_bf16 v[0:3], v[180:183], v[216:219], v[0:3]
	s_barrier
	s_andn2_b64 vcc, exec, s[56:57]
	s_mov_b64 s[58:59], -1
	s_mov_b64 s[56:57], 0
	s_mov_b64 s[60:61], 0x100
	s_cbranch_vccz .LBB0_882
	s_and_b64 vcc, exec, s[30:31]
	s_cbranch_vccz .LBB0_885
	s_barrier

; #define PG8_STAGE(bufoff, gbase, voff) do { _Pragma("unroll") for (int _i = 0; _i < 2; ++_i) \
;         __builtin_amdgcn_global_load_lds((const unsigned*)((const char*)(gbase) + (voff)[_i]), (LAS unsigned*)(lds + (bufoff) + ldsw + _i * 8192), 16, 0, 0); } while (0)
; #define PG8_LDA(dst, b, h) do { _Pragma("unroll") for (int m = 0; m < 4; ++m) _Pragma("unroll") for (int k = 0; k < 2; ++k) dst[m][k] = *(const LAS bf16x8*)(lds + PG8_SA(b, h) + aoff + m * 2048 + k * 1024); } while (0)
; #define PG8_LDB(dst, b, h) do { _Pragma("unroll") for (int n = 0; n < 2; ++n) _Pragma("unroll") for (int k = 0; k < 2; ++k) dst[n][k] = *(const LAS bf16x8*)(lds + PG8_SB(b, h) + boff + n * 2048 + k * 1024); } while (0)
; #define PG8_MMA(ai, bj, At, Bt) do { __builtin_amdgcn_s_setprio(1); _Pragma("unroll") for (int m = 0; m < 4; ++m) _Pragma("unroll") for (int n = 0; n < 2; ++n) _Pragma("unroll") for (int k = 0; k < 2; ++k) \
;         acc[ai][bj][m][n] = __builtin_amdgcn_mfma_f32_16x16x32_bf16(Bt[n][k], At[m][k], acc[ai][bj][m][n], 0, 0, 0); __builtin_amdgcn_s_setprio(0); } while (0)
; #define PG8_WAIT_V(n) asm volatile("s_waitcnt vmcnt(" #n ")" ::: "memory")
; #define PG8_WAIT_L(n) asm volatile("s_waitcnt lgkmcnt(" #n ")" ::: "memory")
; #define PG8_BAR __builtin_amdgcn_s_barrier()
; #define PG8_SCHED __builtin_amdgcn_sched_barrier(0)
; template <class GEO, class Epi>
; __device__ __forceinline__ void gemm_phase(LAS unsigned char* lds, const Gemm g, const StaticOrder& S, const Epi& E) {
;     ...
;             const bool last = (t == nt - 2);
;             const char* a1 = cA + (size_t)(t + 1) * kstep;
;             const char* a2 = last ? nA : cA + (size_t)(t + 2) * kstep; const char* b2 = last ? nB : cB + (size_t)(t + 2) * kstep;
;             const char* a3 = a2 + kstep; const char* b3 = b2 + kstep;
;             PG8_LDB(B0, 0, 0); PG8_LDB(B1, 0, 1); PG8_SCHED; PG8_LDA(At, 0, 0); PG8_STAGE(PG8_SA(1, 1), a1 + hstepA, voffA);
;             PG8_WAIT_V(8); PG8_WAIT_L(0); PG8_BAR; PG8_MMA(0, 0, At, B0); PG8_MMA(0, 1, At, B1); PG8_BAR; PG8_SCHED;
;             PG8_LDA(At, 0, 1); PG8_STAGE(PG8_SB(0, 0), b2, voffB); PG8_STAGE(PG8_SB(0, 1), b2 + hstepB, voffB); PG8_STAGE(PG8_SA(0, 0), a2, voffA);
;             PG8_WAIT_V(8); PG8_WAIT_L(0); PG8_BAR; PG8_MMA(1, 0, At, B0); PG8_MMA(1, 1, At, B1); PG8_BAR; PG8_SCHED;
.LBB0_989:
	ds_read_b128 v[144:147], v152
	ds_read_b128 v[156:159], v152 offset:1024
	ds_read_b128 v[166:169], v152 offset:2048
	ds_read_b128 v[170:173], v152 offset:3072
	ds_read_b128 v[174:177], v153
	ds_read_b128 v[178:181], v153 offset:1024
	ds_read_b128 v[182:185], v153 offset:2048
	ds_read_b128 v[186:189], v153 offset:3072
	s_add_u32 s38, s52, 0xfffc0080
	s_addc_u32 s39, s53, -1
	s_cmp_eq_u32 s67, 12
	s_cselect_b32 s57, s15, s39
	s_cselect_b32 s56, s23, s38
	s_cselect_b32 s55, s28, s66
	s_cselect_b32 s54, s47, s65
	v_lshl_add_u64 v[160:161], s[52:53], 0, v[136:137]
	s_add_i32 m0, s1, 0xc000
	ds_read_b128 v[190:193], v154
	ds_read_b128 v[194:197], v154 offset:1024
	ds_read_b128 v[198:201], v154 offset:2048
	ds_read_b128 v[202:205], v154 offset:3072
	ds_read_b128 v[212:215], v154 offset:4096
	ds_read_b128 v[216:219], v154 offset:5120
	ds_read_b128 v[220:223], v154 offset:6144
	ds_read_b128 v[224:227], v154 offset:7168
	global_load_lds_dwordx4 v[160:161], off
	v_lshl_add_u64 v[160:161], s[52:53], 0, v[138:139]
	s_add_i32 m0, s1, 0xe000
	s_nop 0
	global_load_lds_dwordx4 v[160:161], off
	s_waitcnt vmcnt(8)
	s_waitcnt lgkmcnt(0)
	s_barrier
	s_waitcnt lgkmcnt(0)
	v_mfma_f32_16x16x32_bf16 v[124:127], v[144:147], v[190:193], v[124:127]
	v_mfma_f32_16x16x32_bf16 v[120:123], v[166:169], v[190:193], v[120:123]
	v_mfma_f32_16x16x32_bf16 v[108:111], v[144:147], v[198:201], v[108:111]
	v_mfma_f32_16x16x32_bf16 v[104:107], v[166:169], v[198:201], v[104:107]
	v_mfma_f32_16x16x32_bf16 v[92:95], v[144:147], v[212:215], v[92:95]
	v_mfma_f32_16x16x32_bf16 v[88:91], v[166:169], v[212:215], v[88:91]
	v_mfma_f32_16x16x32_bf16 v[76:79], v[144:147], v[220:223], v[76:79]
	v_mfma_f32_16x16x32_bf16 v[72:75], v[166:169], v[220:223], v[72:75]
	v_mfma_f32_16x16x32_bf16 v[124:127], v[156:159], v[194:197], v[124:127]
	v_mfma_f32_16x16x32_bf16 v[120:123], v[170:173], v[194:197], v[120:123]
	v_mfma_f32_16x16x32_bf16 v[108:111], v[156:159], v[202:205], v[108:111]
	v_mfma_f32_16x16x32_bf16 v[104:107], v[170:173], v[202:205], v[104:107]
	v_mfma_f32_16x16x32_bf16 v[92:95], v[156:159], v[216:219], v[92:95]
	v_mfma_f32_16x16x32_bf16 v[88:91], v[170:173], v[216:219], v[88:91]
	v_mfma_f32_16x16x32_bf16 v[76:79], v[156:159], v[224:227], v[76:79]
	v_mfma_f32_16x16x32_bf16 v[72:75], v[170:173], v[224:227], v[72:75]
	v_mfma_f32_16x16x32_bf16 v[116:119], v[174:177], v[190:193], v[116:119]
	v_mfma_f32_16x16x32_bf16 v[112:115], v[182:185], v[190:193], v[112:115]
	v_mfma_f32_16x16x32_bf16 v[100:103], v[174:177], v[198:201], v[100:103]
	v_mfma_f32_16x16x32_bf16 v[96:99], v[182:185], v[198:201], v[96:99]
	v_mfma_f32_16x16x32_bf16 v[84:87], v[174:177], v[212:215], v[84:87]
	v_mfma_f32_16x16x32_bf16 v[80:83], v[182:185], v[212:215], v[80:83]
	v_mfma_f32_16x16x32_bf16 v[68:71], v[174:177], v[220:223], v[68:71]
	v_mfma_f32_16x16x32_bf16 v[64:67], v[182:185], v[220:223], v[64:67]
	v_mfma_f32_16x16x32_bf16 v[116:119], v[178:181], v[194:197], v[116:119]
	v_mfma_f32_16x16x32_bf16 v[112:115], v[186:189], v[194:197], v[112:115]
	v_mfma_f32_16x16x32_bf16 v[100:103], v[178:181], v[202:205], v[100:103]
	v_mfma_f32_16x16x32_bf16 v[96:99], v[186:189], v[202:205], v[96:99]
	v_mfma_f32_16x16x32_bf16 v[84:87], v[178:181], v[216:219], v[84:87]
	v_mfma_f32_16x16x32_bf16 v[80:83], v[186:189], v[216:219], v[80:83]
	v_mfma_f32_16x16x32_bf16 v[68:71], v[178:181], v[224:227], v[68:71]
	v_mfma_f32_16x16x32_bf16 v[64:67], v[186:189], v[224:227], v[64:67]
	s_barrier
	s_add_i32 s38, s61, s0
	v_lshl_add_u64 v[160:161], s[54:55], 0, v[130:131]
	s_mov_b32 m0, s38
	ds_read_b128 v[190:193], v154 offset:16384
	ds_read_b128 v[194:197], v154 offset:17408
	ds_read_b128 v[198:201], v154 offset:18432
	ds_read_b128 v[202:205], v154 offset:19456
	ds_read_b128 v[212:215], v154 offset:20480
	ds_read_b128 v[216:219], v154 offset:21504
	ds_read_b128 v[220:223], v154 offset:22528
	ds_read_b128 v[224:227], v154 offset:23552
	global_load_lds_dwordx4 v[160:161], off
	s_add_i32 m0, s38, 0x2000
	s_add_u32 s38, s54, 0x100000
	v_lshl_add_u64 v[206:207], s[54:55], 0, v[134:135]
	s_addc_u32 s39, s55, 0
	s_add_i32 s68, s62, s0
	global_load_lds_dwordx4 v[206:207], off
	v_lshl_add_u64 v[228:229], s[38:39], 0, v[130:131]
	s_mov_b32 m0, s68
	v_lshl_add_u64 v[230:231], s[56:57], 0, v[132:133]
	global_load_lds_dwordx4 v[228:229], off
	v_lshl_add_u64 v[228:229], s[38:39], 0, v[134:135]
	s_add_i32 m0, s68, 0x2000
	s_nop 0
	global_load_lds_dwordx4 v[228:229], off
	v_lshl_add_u64 v[228:229], s[56:57], 0, v[128:129]
	s_mov_b32 m0, s1
	s_nop 0
	global_load_lds_dwordx4 v[228:229], off
	s_mov_b32 m0, s4
	s_nop 0
	global_load_lds_dwordx4 v[230:231], off
	s_waitcnt vmcnt(8)
	s_waitcnt lgkmcnt(0)
	s_barrier
; #define PG8_STAGE(bufoff, gbase, voff) do { _Pragma("unroll") for (int _i = 0; _i < 2; ++_i) \
;         __builtin_amdgcn_global_load_lds((const unsigned*)((const char*)(gbase) + (voff)[_i]), (LAS unsigned*)(lds + (bufoff) + ldsw + _i * 8192), 16, 0, 0); } while (0)
; #define PG8_LDA(dst, b, h) do { _Pragma("unroll") for (int m = 0; m < 4; ++m) _Pragma("unroll") for (int k = 0; k < 2; ++k) dst[m][k] = *(const LAS bf16x8*)(lds + PG8_SA(b, h) + aoff + m * 2048 + k * 1024); } while (0)
; #define PG8_LDB(dst, b, h) do { _Pragma("unroll") for (int n = 0; n < 2; ++n) _Pragma("unroll") for (int k = 0; k < 2; ++k) dst[n][k] = *(const LAS bf16x8*)(lds + PG8_SB(b, h) + boff + n * 2048 + k * 1024); } while (0)
; #define PG8_MMA(ai, bj, At, Bt) do { __builtin_amdgcn_s_setprio(1); _Pragma("unroll") for (int m = 0; m < 4; ++m) _Pragma("unroll") for (int n = 0; n < 2; ++n) _Pragma("unroll") for (int k = 0; k < 2; ++k) \
;         acc[ai][bj][m][n] = __builtin_amdgcn_mfma_f32_16x16x32_bf16(Bt[n][k], At[m][k], acc[ai][bj][m][n], 0, 0, 0); __builtin_amdgcn_s_setprio(0); } while (0)
; #define PG8_WAIT_V(n) asm volatile("s_waitcnt vmcnt(" #n ")" ::: "memory")
; #define PG8_WAIT_L(n) asm volatile("s_waitcnt lgkmcnt(" #n ")" ::: "memory")
; #define PG8_BAR __builtin_amdgcn_s_barrier()
; #define PG8_SCHED __builtin_amdgcn_sched_barrier(0)
; template <class GEO, class Epi>
; __device__ __forceinline__ void gemm_phase(LAS unsigned char* lds, const Gemm g, const StaticOrder& S, const Epi& E) {
;     ...
;             PG8_WAIT_V(8); PG8_WAIT_L(0); PG8_BAR; PG8_MMA(1, 0, At, B0); PG8_MMA(1, 1, At, B1); PG8_BAR; PG8_SCHED;
;             PG8_LDB(B0, 1, 0); PG8_LDB(B1, 1, 1); PG8_SCHED; PG8_LDA(At, 1, 0); PG8_STAGE(PG8_SA(0, 1), a2 + hstepA, voffA);
;             PG8_WAIT_V(8); PG8_WAIT_L(0); PG8_BAR; PG8_MMA(0, 0, At, B0); PG8_MMA(0, 1, At, B1); PG8_BAR; PG8_SCHED;
	s_waitcnt lgkmcnt(0)
	v_mfma_f32_16x16x32_bf16 v[60:63], v[144:147], v[190:193], v[60:63]
	v_mfma_f32_16x16x32_bf16 v[56:59], v[166:169], v[190:193], v[56:59]
	v_mfma_f32_16x16x32_bf16 v[44:47], v[144:147], v[198:201], v[44:47]
	v_mfma_f32_16x16x32_bf16 v[40:43], v[166:169], v[198:201], v[40:43]
	v_mfma_f32_16x16x32_bf16 v[28:31], v[144:147], v[212:215], v[28:31]
	v_mfma_f32_16x16x32_bf16 v[24:27], v[166:169], v[212:215], v[24:27]
	v_mfma_f32_16x16x32_bf16 v[12:15], v[144:147], v[220:223], v[12:15]
	v_mfma_f32_16x16x32_bf16 v[8:11], v[166:169], v[220:223], v[8:11]
	v_mfma_f32_16x16x32_bf16 v[60:63], v[156:159], v[194:197], v[60:63]
	v_mfma_f32_16x16x32_bf16 v[56:59], v[170:173], v[194:197], v[56:59]
	v_mfma_f32_16x16x32_bf16 v[44:47], v[156:159], v[202:205], v[44:47]
	v_mfma_f32_16x16x32_bf16 v[40:43], v[170:173], v[202:205], v[40:43]
	v_mfma_f32_16x16x32_bf16 v[28:31], v[156:159], v[216:219], v[28:31]
	v_mfma_f32_16x16x32_bf16 v[24:27], v[170:173], v[216:219], v[24:27]
	v_mfma_f32_16x16x32_bf16 v[12:15], v[156:159], v[224:227], v[12:15]
	v_mfma_f32_16x16x32_bf16 v[8:11], v[170:173], v[224:227], v[8:11]
	v_mfma_f32_16x16x32_bf16 v[52:55], v[174:177], v[190:193], v[52:55]
	v_mfma_f32_16x16x32_bf16 v[48:51], v[182:185], v[190:193], v[48:51]
	v_mfma_f32_16x16x32_bf16 v[36:39], v[174:177], v[198:201], v[36:39]
	v_mfma_f32_16x16x32_bf16 v[32:35], v[182:185], v[198:201], v[32:35]
	v_mfma_f32_16x16x32_bf16 v[20:23], v[174:177], v[212:215], v[20:23]
	v_mfma_f32_16x16x32_bf16 v[16:19], v[182:185], v[212:215], v[16:19]
	v_mfma_f32_16x16x32_bf16 v[4:7], v[174:177], v[220:223], v[4:7]
	v_mfma_f32_16x16x32_bf16 v[0:3], v[182:185], v[220:223], v[0:3]
	v_mfma_f32_16x16x32_bf16 v[52:55], v[178:181], v[194:197], v[52:55]
	v_mfma_f32_16x16x32_bf16 v[48:51], v[186:189], v[194:197], v[48:51]
	v_mfma_f32_16x16x32_bf16 v[36:39], v[178:181], v[202:205], v[36:39]
	v_mfma_f32_16x16x32_bf16 v[32:35], v[186:189], v[202:205], v[32:35]
	v_mfma_f32_16x16x32_bf16 v[20:23], v[178:181], v[216:219], v[20:23]
	v_mfma_f32_16x16x32_bf16 v[16:19], v[186:189], v[216:219], v[16:19]
	v_mfma_f32_16x16x32_bf16 v[4:7], v[178:181], v[224:227], v[4:7]
	v_mfma_f32_16x16x32_bf16 v[0:3], v[186:189], v[224:227], v[0:3]
	s_barrier
	s_add_i32 s68, 0, 0x18000
	v_add_u32_e32 v155, s68, v149
	s_add_i32 s69, 0, 0x1c000
	ds_read_b128 v[144:147], v155
	ds_read_b128 v[156:159], v155 offset:1024
	ds_read_b128 v[166:169], v155 offset:2048
	ds_read_b128 v[170:173], v155 offset:3072
	v_add_u32_e32 v155, s69, v149
	ds_read_b128 v[174:177], v155
	ds_read_b128 v[178:181], v155 offset:1024
	ds_read_b128 v[182:185], v155 offset:2048
	ds_read_b128 v[186:189], v155 offset:3072
	s_add_u32 s38, s56, 0x40000
	s_addc_u32 s39, s57, 0
	s_mov_b32 m0, s5
	v_lshl_add_u64 v[232:233], s[38:39], 0, v[128:129]
	ds_read_b128 v[190:193], v154 offset:32768
	ds_read_b128 v[194:197], v154 offset:33792
	ds_read_b128 v[198:201], v154 offset:34816
	ds_read_b128 v[202:205], v154 offset:35840
	ds_read_b128 v[212:215], v154 offset:36864
	ds_read_b128 v[216:219], v154 offset:37888
	ds_read_b128 v[220:223], v154 offset:38912
	ds_read_b128 v[224:227], v154 offset:39936
	global_load_lds_dwordx4 v[232:233], off
	v_lshl_add_u64 v[232:233], s[38:39], 0, v[132:133]
	s_mov_b32 m0, s6
	s_nop 0
	global_load_lds_dwordx4 v[232:233], off
	s_waitcnt vmcnt(8)
	s_waitcnt lgkmcnt(0)
	s_barrier
	s_waitcnt lgkmcnt(0)
	v_mfma_f32_16x16x32_bf16 v[124:127], v[144:147], v[190:193], v[124:127]
	v_mfma_f32_16x16x32_bf16 v[120:123], v[166:169], v[190:193], v[120:123]
	v_mfma_f32_16x16x32_bf16 v[108:111], v[144:147], v[198:201], v[108:111]
	v_mfma_f32_16x16x32_bf16 v[104:107], v[166:169], v[198:201], v[104:107]
	v_mfma_f32_16x16x32_bf16 v[92:95], v[144:147], v[212:215], v[92:95]
	v_mfma_f32_16x16x32_bf16 v[88:91], v[166:169], v[212:215], v[88:91]
	v_mfma_f32_16x16x32_bf16 v[76:79], v[144:147], v[220:223], v[76:79]
	v_mfma_f32_16x16x32_bf16 v[72:75], v[166:169], v[220:223], v[72:75]
	v_mfma_f32_16x16x32_bf16 v[124:127], v[156:159], v[194:197], v[124:127]
	v_mfma_f32_16x16x32_bf16 v[120:123], v[170:173], v[194:197], v[120:123]
	v_mfma_f32_16x16x32_bf16 v[108:111], v[156:159], v[202:205], v[108:111]
	v_mfma_f32_16x16x32_bf16 v[104:107], v[170:173], v[202:205], v[104:107]
	v_mfma_f32_16x16x32_bf16 v[92:95], v[156:159], v[216:219], v[92:95]
	v_mfma_f32_16x16x32_bf16 v[88:91], v[170:173], v[216:219], v[88:91]
	v_mfma_f32_16x16x32_bf16 v[76:79], v[156:159], v[224:227], v[76:79]
	v_mfma_f32_16x16x32_bf16 v[72:75], v[170:173], v[224:227], v[72:75]
	v_mfma_f32_16x16x32_bf16 v[116:119], v[174:177], v[190:193], v[116:119]
	v_mfma_f32_16x16x32_bf16 v[112:115], v[182:185], v[190:193], v[112:115]
	v_mfma_f32_16x16x32_bf16 v[100:103], v[174:177], v[198:201], v[100:103]
	v_mfma_f32_16x16x32_bf16 v[96:99], v[182:185], v[198:201], v[96:99]
	v_mfma_f32_16x16x32_bf16 v[84:87], v[174:177], v[212:215], v[84:87]
	v_mfma_f32_16x16x32_bf16 v[80:83], v[182:185], v[212:215], v[80:83]
	v_mfma_f32_16x16x32_bf16 v[68:71], v[174:177], v[220:223], v[68:71]
	v_mfma_f32_16x16x32_bf16 v[64:67], v[182:185], v[220:223], v[64:67]
	v_mfma_f32_16x16x32_bf16 v[116:119], v[178:181], v[194:197], v[116:119]
	v_mfma_f32_16x16x32_bf16 v[112:115], v[186:189], v[194:197], v[112:115]
	v_mfma_f32_16x16x32_bf16 v[100:103], v[178:181], v[202:205], v[100:103]
	v_mfma_f32_16x16x32_bf16 v[96:99], v[186:189], v[202:205], v[96:99]
	v_mfma_f32_16x16x32_bf16 v[84:87], v[178:181], v[216:219], v[84:87]
	v_mfma_f32_16x16x32_bf16 v[80:83], v[186:189], v[216:219], v[80:83]
	v_mfma_f32_16x16x32_bf16 v[68:71], v[178:181], v[224:227], v[68:71]
	v_mfma_f32_16x16x32_bf16 v[64:67], v[186:189], v[224:227], v[64:67]
	s_barrier
; #define PG8_STAGE(bufoff, gbase, voff) do { _Pragma("unroll") for (int _i = 0; _i < 2; ++_i) \
;         __builtin_amdgcn_global_load_lds((const unsigned*)((const char*)(gbase) + (voff)[_i]), (LAS unsigned*)(lds + (bufoff) + ldsw + _i * 8192), 16, 0, 0); } while (0)
; #define PG8_LDA(dst, b, h) do { _Pragma("unroll") for (int m = 0; m < 4; ++m) _Pragma("unroll") for (int k = 0; k < 2; ++k) dst[m][k] = *(const LAS bf16x8*)(lds + PG8_SA(b, h) + aoff + m * 2048 + k * 1024); } while (0)
; #define PG8_MMA(ai, bj, At, Bt) do { __builtin_amdgcn_s_setprio(1); _Pragma("unroll") for (int m = 0; m < 4; ++m) _Pragma("unroll") for (int n = 0; n < 2; ++n) _Pragma("unroll") for (int k = 0; k < 2; ++k) \
;         acc[ai][bj][m][n] = __builtin_amdgcn_mfma_f32_16x16x32_bf16(Bt[n][k], At[m][k], acc[ai][bj][m][n], 0, 0, 0); __builtin_amdgcn_s_setprio(0); } while (0)
; #define PG8_WAIT_V(n) asm volatile("s_waitcnt vmcnt(" #n ")" ::: "memory")
; #define PG8_WAIT_L(n) asm volatile("s_waitcnt lgkmcnt(" #n ")" ::: "memory")
; #define PG8_BAR __builtin_amdgcn_s_barrier()
; #define PG8_SCHED __builtin_amdgcn_sched_barrier(0)
; template <class GEO, class Epi>
; __device__ __forceinline__ void gemm_phase(LAS unsigned char* lds, const Gemm g, const StaticOrder& S, const Epi& E) {
;     ...
;             PG8_LDA(At, 1, 1); PG8_STAGE(PG8_SB(1, 0), b3, voffB); PG8_STAGE(PG8_SB(1, 1), b3 + hstepB, voffB); PG8_STAGE(PG8_SA(1, 0), a3, voffA);
;             PG8_WAIT_V(8); PG8_WAIT_L(0); PG8_BAR; PG8_MMA(1, 0, At, B0); PG8_MMA(1, 1, At, B1); PG8_BAR; PG8_SCHED;
;         }
;         if (wr == 0) PG8_BAR;
	s_add_i32 s38, s68, s0
	v_lshl_add_u64 v[160:161], v[160:161], 0, s[34:35]
	s_mov_b32 m0, s38
	ds_read_b128 v[190:193], v154 offset:49152
	ds_read_b128 v[194:197], v154 offset:50176
	ds_read_b128 v[198:201], v154 offset:51200
	ds_read_b128 v[202:205], v154 offset:52224
	ds_read_b128 v[212:215], v154 offset:53248
	ds_read_b128 v[216:219], v154 offset:54272
	ds_read_b128 v[220:223], v154 offset:55296
	ds_read_b128 v[224:227], v154 offset:56320
	global_load_lds_dwordx4 v[160:161], off
	s_add_i32 m0, s38, 0x2000
	s_add_u32 s38, s54, 0x100080
	v_lshl_add_u64 v[160:161], v[206:207], 0, s[34:35]
	s_addc_u32 s39, s55, 0
	s_add_i32 s54, s69, s0
	global_load_lds_dwordx4 v[160:161], off
	v_lshl_add_u64 v[160:161], s[38:39], 0, v[130:131]
	s_mov_b32 m0, s54
	s_nop 0
	global_load_lds_dwordx4 v[160:161], off
	v_lshl_add_u64 v[160:161], s[38:39], 0, v[134:135]
	s_add_i32 m0, s54, 0x2000
	s_nop 0
	global_load_lds_dwordx4 v[160:161], off
	v_lshl_add_u64 v[160:161], v[228:229], 0, s[34:35]
	s_mov_b32 m0, s7
	s_nop 0
	global_load_lds_dwordx4 v[160:161], off
	v_lshl_add_u64 v[160:161], v[230:231], 0, s[34:35]
	s_mov_b32 m0, s12
	s_nop 0
	global_load_lds_dwordx4 v[160:161], off
	s_waitcnt vmcnt(8)
	s_waitcnt lgkmcnt(0)
	s_barrier
	s_waitcnt lgkmcnt(0)
	v_mfma_f32_16x16x32_bf16 v[60:63], v[144:147], v[190:193], v[60:63]
	v_mfma_f32_16x16x32_bf16 v[56:59], v[166:169], v[190:193], v[56:59]
	v_mfma_f32_16x16x32_bf16 v[44:47], v[144:147], v[198:201], v[44:47]
	v_mfma_f32_16x16x32_bf16 v[40:43], v[166:169], v[198:201], v[40:43]
	v_mfma_f32_16x16x32_bf16 v[28:31], v[144:147], v[212:215], v[28:31]
	v_mfma_f32_16x16x32_bf16 v[24:27], v[166:169], v[212:215], v[24:27]
	v_mfma_f32_16x16x32_bf16 v[12:15], v[144:147], v[220:223], v[12:15]
	v_mfma_f32_16x16x32_bf16 v[8:11], v[166:169], v[220:223], v[8:11]
	v_mfma_f32_16x16x32_bf16 v[60:63], v[156:159], v[194:197], v[60:63]
	v_mfma_f32_16x16x32_bf16 v[56:59], v[170:173], v[194:197], v[56:59]
	v_mfma_f32_16x16x32_bf16 v[44:47], v[156:159], v[202:205], v[44:47]
	v_mfma_f32_16x16x32_bf16 v[40:43], v[170:173], v[202:205], v[40:43]
	v_mfma_f32_16x16x32_bf16 v[28:31], v[156:159], v[216:219], v[28:31]
	v_mfma_f32_16x16x32_bf16 v[24:27], v[170:173], v[216:219], v[24:27]
	v_mfma_f32_16x16x32_bf16 v[12:15], v[156:159], v[224:227], v[12:15]
	v_mfma_f32_16x16x32_bf16 v[8:11], v[170:173], v[224:227], v[8:11]
	v_mfma_f32_16x16x32_bf16 v[52:55], v[174:177], v[190:193], v[52:55]
	v_mfma_f32_16x16x32_bf16 v[48:51], v[182:185], v[190:193], v[48:51]
	v_mfma_f32_16x16x32_bf16 v[36:39], v[174:177], v[198:201], v[36:39]
	v_mfma_f32_16x16x32_bf16 v[32:35], v[182:185], v[198:201], v[32:35]
	v_mfma_f32_16x16x32_bf16 v[20:23], v[174:177], v[212:215], v[20:23]
	v_mfma_f32_16x16x32_bf16 v[16:19], v[182:185], v[212:215], v[16:19]
	v_mfma_f32_16x16x32_bf16 v[4:7], v[174:177], v[220:223], v[4:7]
	v_mfma_f32_16x16x32_bf16 v[0:3], v[182:185], v[220:223], v[0:3]
	v_mfma_f32_16x16x32_bf16 v[52:55], v[178:181], v[194:197], v[52:55]
	v_mfma_f32_16x16x32_bf16 v[48:51], v[186:189], v[194:197], v[48:51]
	v_mfma_f32_16x16x32_bf16 v[36:39], v[178:181], v[202:205], v[36:39]
	v_mfma_f32_16x16x32_bf16 v[32:35], v[186:189], v[202:205], v[32:35]
	v_mfma_f32_16x16x32_bf16 v[20:23], v[178:181], v[216:219], v[20:23]
	v_mfma_f32_16x16x32_bf16 v[16:19], v[186:189], v[216:219], v[16:19]
	v_mfma_f32_16x16x32_bf16 v[4:7], v[178:181], v[224:227], v[4:7]
	v_mfma_f32_16x16x32_bf16 v[0:3], v[186:189], v[224:227], v[0:3]
	s_barrier
	s_add_i32 s67, s67, 2
	s_add_u32 s52, s52, 0x100
	s_addc_u32 s53, s53, 0
	s_add_u32 s65, s65, 0x100
	s_addc_u32 s66, s66, 0
	s_cmp_gt_u32 s67, 13
	s_cbranch_scc0 .LBB0_989
	s_and_b64 vcc, exec, s[20:21]
	s_cbranch_vccz .LBB0_992
	s_barrier

; #define PG8_STAGE(bufoff, gbase, voff) do { _Pragma("unroll") for (int _i = 0; _i < 2; ++_i) \
;         __builtin_amdgcn_global_load_lds((const unsigned*)((const char*)(gbase) + (voff)[_i]), (LAS unsigned*)(lds + (bufoff) + ldsw + _i * 8192), 16, 0, 0); } while (0)
; #define PG8_LDA(dst, b, h) do { _Pragma("unroll") for (int m = 0; m < 4; ++m) _Pragma("unroll") for (int k = 0; k < 2; ++k) dst[m][k] = *(const LAS bf16x8*)(lds + PG8_SA(b, h) + aoff + m * 2048 + k * 1024); } while (0)
; #define PG8_LDB(dst, b, h) do { _Pragma("unroll") for (int n = 0; n < 2; ++n) _Pragma("unroll") for (int k = 0; k < 2; ++k) dst[n][k] = *(const LAS bf16x8*)(lds + PG8_SB(b, h) + boff + n * 2048 + k * 1024); } while (0)
; #define PG8_MMA(ai, bj, At, Bt) do { __builtin_amdgcn_s_setprio(1); _Pragma("unroll") for (int m = 0; m < 4; ++m) _Pragma("unroll") for (int n = 0; n < 2; ++n) _Pragma("unroll") for (int k = 0; k < 2; ++k) \
;         acc[ai][bj][m][n] = __builtin_amdgcn_mfma_f32_16x16x32_bf16(Bt[n][k], At[m][k], acc[ai][bj][m][n], 0, 0, 0); __builtin_amdgcn_s_setprio(0); } while (0)
; #define PG8_WAIT_V(n) asm volatile("s_waitcnt vmcnt(" #n ")" ::: "memory")
; #define PG8_WAIT_L(n) asm volatile("s_waitcnt lgkmcnt(" #n ")" ::: "memory")
; #define PG8_BAR __builtin_amdgcn_s_barrier()
; #define PG8_SCHED __builtin_amdgcn_sched_barrier(0)
; template <class GEO, class Epi>
; __device__ __forceinline__ void gemm_phase(LAS unsigned char* lds, const Gemm g, const StaticOrder& S, const Epi& E) {
;     ...
;             const bool last = (t == nt - 2);
;             const char* a1 = cA + (size_t)(t + 1) * kstep;
;             const char* a2 = last ? nA : cA + (size_t)(t + 2) * kstep; const char* b2 = last ? nB : cB + (size_t)(t + 2) * kstep;
;             const char* a3 = a2 + kstep; const char* b3 = b2 + kstep;
;             PG8_LDB(B0, 0, 0); PG8_LDB(B1, 0, 1); PG8_SCHED; PG8_LDA(At, 0, 0); PG8_STAGE(PG8_SA(1, 1), a1 + hstepA, voffA);
;             PG8_WAIT_V(8); PG8_WAIT_L(0); PG8_BAR; PG8_MMA(0, 0, At, B0); PG8_MMA(0, 1, At, B1); PG8_BAR; PG8_SCHED;
;             PG8_LDA(At, 0, 1); PG8_STAGE(PG8_SB(0, 0), b2, voffB); PG8_STAGE(PG8_SB(0, 1), b2 + hstepB, voffB); PG8_STAGE(PG8_SA(0, 0), a2, voffA);
;             PG8_WAIT_V(8); PG8_WAIT_L(0); PG8_BAR; PG8_MMA(1, 0, At, B0); PG8_MMA(1, 1, At, B1); PG8_BAR; PG8_SCHED;
.LBB0_1075:
	ds_read_b128 v[144:147], v151
	ds_read_b128 v[156:159], v151 offset:1024
	ds_read_b128 v[166:169], v151 offset:2048
	ds_read_b128 v[170:173], v151 offset:3072
	ds_read_b128 v[174:177], v152
	ds_read_b128 v[178:181], v152 offset:1024
	ds_read_b128 v[182:185], v152 offset:2048
	ds_read_b128 v[186:189], v152 offset:3072
	s_add_u32 s38, s22, 0xfffc0080
	s_addc_u32 s39, s23, -1
	s_cmp_eq_u32 s51, 12
	s_cselect_b32 s47, s21, s39
	s_cselect_b32 s46, s31, s38
	s_cselect_b32 s45, s14, s50
	s_cselect_b32 s44, s48, s49
	v_lshl_add_u64 v[160:161], s[22:23], 0, v[136:137]
	s_add_i32 m0, s1, 0xc000
	ds_read_b128 v[190:193], v153
	ds_read_b128 v[194:197], v153 offset:1024
	ds_read_b128 v[198:201], v153 offset:2048
	ds_read_b128 v[202:205], v153 offset:3072
	ds_read_b128 v[210:213], v153 offset:4096
	ds_read_b128 v[214:217], v153 offset:5120
	ds_read_b128 v[218:221], v153 offset:6144
	ds_read_b128 v[222:225], v153 offset:7168
	global_load_lds_dwordx4 v[160:161], off
	v_lshl_add_u64 v[160:161], s[22:23], 0, v[138:139]
	s_add_i32 m0, s1, 0xe000
	s_nop 0
	global_load_lds_dwordx4 v[160:161], off
	s_waitcnt vmcnt(8)
	s_waitcnt lgkmcnt(0)
	s_barrier
	s_waitcnt lgkmcnt(0)
	v_mfma_f32_16x16x32_bf16 v[124:127], v[144:147], v[190:193], v[124:127]
	v_mfma_f32_16x16x32_bf16 v[120:123], v[166:169], v[190:193], v[120:123]
	v_mfma_f32_16x16x32_bf16 v[108:111], v[144:147], v[198:201], v[108:111]
	v_mfma_f32_16x16x32_bf16 v[104:107], v[166:169], v[198:201], v[104:107]
	v_mfma_f32_16x16x32_bf16 v[92:95], v[144:147], v[210:213], v[92:95]
	v_mfma_f32_16x16x32_bf16 v[88:91], v[166:169], v[210:213], v[88:91]
	v_mfma_f32_16x16x32_bf16 v[76:79], v[144:147], v[218:221], v[76:79]
	v_mfma_f32_16x16x32_bf16 v[72:75], v[166:169], v[218:221], v[72:75]
	v_mfma_f32_16x16x32_bf16 v[124:127], v[156:159], v[194:197], v[124:127]
	v_mfma_f32_16x16x32_bf16 v[120:123], v[170:173], v[194:197], v[120:123]
	v_mfma_f32_16x16x32_bf16 v[108:111], v[156:159], v[202:205], v[108:111]
	v_mfma_f32_16x16x32_bf16 v[104:107], v[170:173], v[202:205], v[104:107]
	v_mfma_f32_16x16x32_bf16 v[92:95], v[156:159], v[214:217], v[92:95]
	v_mfma_f32_16x16x32_bf16 v[88:91], v[170:173], v[214:217], v[88:91]
	v_mfma_f32_16x16x32_bf16 v[76:79], v[156:159], v[222:225], v[76:79]
	v_mfma_f32_16x16x32_bf16 v[72:75], v[170:173], v[222:225], v[72:75]
	v_mfma_f32_16x16x32_bf16 v[116:119], v[174:177], v[190:193], v[116:119]
	v_mfma_f32_16x16x32_bf16 v[112:115], v[182:185], v[190:193], v[112:115]
	v_mfma_f32_16x16x32_bf16 v[100:103], v[174:177], v[198:201], v[100:103]
	v_mfma_f32_16x16x32_bf16 v[96:99], v[182:185], v[198:201], v[96:99]
	v_mfma_f32_16x16x32_bf16 v[84:87], v[174:177], v[210:213], v[84:87]
	v_mfma_f32_16x16x32_bf16 v[80:83], v[182:185], v[210:213], v[80:83]
	v_mfma_f32_16x16x32_bf16 v[68:71], v[174:177], v[218:221], v[68:71]
	v_mfma_f32_16x16x32_bf16 v[64:67], v[182:185], v[218:221], v[64:67]
	v_mfma_f32_16x16x32_bf16 v[116:119], v[178:181], v[194:197], v[116:119]
	v_mfma_f32_16x16x32_bf16 v[112:115], v[186:189], v[194:197], v[112:115]
	v_mfma_f32_16x16x32_bf16 v[100:103], v[178:181], v[202:205], v[100:103]
	v_mfma_f32_16x16x32_bf16 v[96:99], v[186:189], v[202:205], v[96:99]
	v_mfma_f32_16x16x32_bf16 v[84:87], v[178:181], v[214:217], v[84:87]
	v_mfma_f32_16x16x32_bf16 v[80:83], v[186:189], v[214:217], v[80:83]
	v_mfma_f32_16x16x32_bf16 v[68:71], v[178:181], v[222:225], v[68:71]
	v_mfma_f32_16x16x32_bf16 v[64:67], v[186:189], v[222:225], v[64:67]
	s_barrier
	s_add_i32 s38, s13, s0
	v_lshl_add_u64 v[160:161], s[44:45], 0, v[132:133]
	s_mov_b32 m0, s38
	ds_read_b128 v[190:193], v153 offset:16384
	ds_read_b128 v[194:197], v153 offset:17408
	ds_read_b128 v[198:201], v153 offset:18432
	ds_read_b128 v[202:205], v153 offset:19456
	ds_read_b128 v[210:213], v153 offset:20480
	ds_read_b128 v[214:217], v153 offset:21504
	ds_read_b128 v[218:221], v153 offset:22528
	ds_read_b128 v[222:225], v153 offset:23552
	global_load_lds_dwordx4 v[160:161], off
	s_add_i32 m0, s38, 0x2000
	s_add_u32 s38, s44, 0x40000
	v_lshl_add_u64 v[206:207], s[44:45], 0, v[128:129]
	s_addc_u32 s39, s45, 0
	s_add_i32 s52, s18, s0
	global_load_lds_dwordx4 v[206:207], off
	v_lshl_add_u64 v[226:227], s[38:39], 0, v[132:133]
	s_mov_b32 m0, s52
	v_lshl_add_u64 v[228:229], s[46:47], 0, v[130:131]
	global_load_lds_dwordx4 v[226:227], off
	v_lshl_add_u64 v[226:227], s[38:39], 0, v[128:129]
	s_add_i32 m0, s52, 0x2000
	s_nop 0
	global_load_lds_dwordx4 v[226:227], off
	v_lshl_add_u64 v[226:227], s[46:47], 0, v[134:135]
	s_mov_b32 m0, s1
	s_nop 0
	global_load_lds_dwordx4 v[226:227], off
	s_mov_b32 m0, s4
	s_nop 0
	global_load_lds_dwordx4 v[228:229], off
	s_waitcnt vmcnt(8)
	s_waitcnt lgkmcnt(0)
	s_barrier
; #define PG8_STAGE(bufoff, gbase, voff) do { _Pragma("unroll") for (int _i = 0; _i < 2; ++_i) \
;         __builtin_amdgcn_global_load_lds((const unsigned*)((const char*)(gbase) + (voff)[_i]), (LAS unsigned*)(lds + (bufoff) + ldsw + _i * 8192), 16, 0, 0); } while (0)
; #define PG8_LDA(dst, b, h) do { _Pragma("unroll") for (int m = 0; m < 4; ++m) _Pragma("unroll") for (int k = 0; k < 2; ++k) dst[m][k] = *(const LAS bf16x8*)(lds + PG8_SA(b, h) + aoff + m * 2048 + k * 1024); } while (0)
; #define PG8_LDB(dst, b, h) do { _Pragma("unroll") for (int n = 0; n < 2; ++n) _Pragma("unroll") for (int k = 0; k < 2; ++k) dst[n][k] = *(const LAS bf16x8*)(lds + PG8_SB(b, h) + boff + n * 2048 + k * 1024); } while (0)
; #define PG8_MMA(ai, bj, At, Bt) do { __builtin_amdgcn_s_setprio(1); _Pragma("unroll") for (int m = 0; m < 4; ++m) _Pragma("unroll") for (int n = 0; n < 2; ++n) _Pragma("unroll") for (int k = 0; k < 2; ++k) \
;         acc[ai][bj][m][n] = __builtin_amdgcn_mfma_f32_16x16x32_bf16(Bt[n][k], At[m][k], acc[ai][bj][m][n], 0, 0, 0); __builtin_amdgcn_s_setprio(0); } while (0)
; #define PG8_WAIT_V(n) asm volatile("s_waitcnt vmcnt(" #n ")" ::: "memory")
; #define PG8_WAIT_L(n) asm volatile("s_waitcnt lgkmcnt(" #n ")" ::: "memory")
; #define PG8_BAR __builtin_amdgcn_s_barrier()
; #define PG8_SCHED __builtin_amdgcn_sched_barrier(0)
; template <class GEO, class Epi>
; __device__ __forceinline__ void gemm_phase(LAS unsigned char* lds, const Gemm g, const StaticOrder& S, const Epi& E) {
;     ...
;             PG8_WAIT_V(8); PG8_WAIT_L(0); PG8_BAR; PG8_MMA(1, 0, At, B0); PG8_MMA(1, 1, At, B1); PG8_BAR; PG8_SCHED;
;             PG8_LDB(B0, 1, 0); PG8_LDB(B1, 1, 1); PG8_SCHED; PG8_LDA(At, 1, 0); PG8_STAGE(PG8_SA(0, 1), a2 + hstepA, voffA);
;             PG8_WAIT_V(8); PG8_WAIT_L(0); PG8_BAR; PG8_MMA(0, 0, At, B0); PG8_MMA(0, 1, At, B1); PG8_BAR; PG8_SCHED;
	s_waitcnt lgkmcnt(0)
	v_mfma_f32_16x16x32_bf16 v[60:63], v[144:147], v[190:193], v[60:63]
	v_mfma_f32_16x16x32_bf16 v[56:59], v[166:169], v[190:193], v[56:59]
	v_mfma_f32_16x16x32_bf16 v[44:47], v[144:147], v[198:201], v[44:47]
	v_mfma_f32_16x16x32_bf16 v[40:43], v[166:169], v[198:201], v[40:43]
	v_mfma_f32_16x16x32_bf16 v[28:31], v[144:147], v[210:213], v[28:31]
	v_mfma_f32_16x16x32_bf16 v[24:27], v[166:169], v[210:213], v[24:27]
	v_mfma_f32_16x16x32_bf16 v[12:15], v[144:147], v[218:221], v[12:15]
	v_mfma_f32_16x16x32_bf16 v[8:11], v[166:169], v[218:221], v[8:11]
	v_mfma_f32_16x16x32_bf16 v[60:63], v[156:159], v[194:197], v[60:63]
	v_mfma_f32_16x16x32_bf16 v[56:59], v[170:173], v[194:197], v[56:59]
	v_mfma_f32_16x16x32_bf16 v[44:47], v[156:159], v[202:205], v[44:47]
	v_mfma_f32_16x16x32_bf16 v[40:43], v[170:173], v[202:205], v[40:43]
	v_mfma_f32_16x16x32_bf16 v[28:31], v[156:159], v[214:217], v[28:31]
	v_mfma_f32_16x16x32_bf16 v[24:27], v[170:173], v[214:217], v[24:27]
	v_mfma_f32_16x16x32_bf16 v[12:15], v[156:159], v[222:225], v[12:15]
	v_mfma_f32_16x16x32_bf16 v[8:11], v[170:173], v[222:225], v[8:11]
	v_mfma_f32_16x16x32_bf16 v[52:55], v[174:177], v[190:193], v[52:55]
	v_mfma_f32_16x16x32_bf16 v[48:51], v[182:185], v[190:193], v[48:51]
	v_mfma_f32_16x16x32_bf16 v[36:39], v[174:177], v[198:201], v[36:39]
	v_mfma_f32_16x16x32_bf16 v[32:35], v[182:185], v[198:201], v[32:35]
	v_mfma_f32_16x16x32_bf16 v[20:23], v[174:177], v[210:213], v[20:23]
	v_mfma_f32_16x16x32_bf16 v[16:19], v[182:185], v[210:213], v[16:19]
	v_mfma_f32_16x16x32_bf16 v[4:7], v[174:177], v[218:221], v[4:7]
	v_mfma_f32_16x16x32_bf16 v[0:3], v[182:185], v[218:221], v[0:3]
	v_mfma_f32_16x16x32_bf16 v[52:55], v[178:181], v[194:197], v[52:55]
	v_mfma_f32_16x16x32_bf16 v[48:51], v[186:189], v[194:197], v[48:51]
	v_mfma_f32_16x16x32_bf16 v[36:39], v[178:181], v[202:205], v[36:39]
	v_mfma_f32_16x16x32_bf16 v[32:35], v[186:189], v[202:205], v[32:35]
	v_mfma_f32_16x16x32_bf16 v[20:23], v[178:181], v[214:217], v[20:23]
	v_mfma_f32_16x16x32_bf16 v[16:19], v[186:189], v[214:217], v[16:19]
	v_mfma_f32_16x16x32_bf16 v[4:7], v[178:181], v[222:225], v[4:7]
	v_mfma_f32_16x16x32_bf16 v[0:3], v[186:189], v[222:225], v[0:3]
	s_barrier
	s_add_i32 s52, 0, 0x18000
	v_add_u32_e32 v155, s52, v149
	s_add_i32 s53, 0, 0x1c000
	ds_read_b128 v[144:147], v155
	ds_read_b128 v[156:159], v155 offset:1024
	ds_read_b128 v[166:169], v155 offset:2048
	ds_read_b128 v[170:173], v155 offset:3072
	v_add_u32_e32 v155, s53, v149
	ds_read_b128 v[174:177], v155
	ds_read_b128 v[178:181], v155 offset:1024
	ds_read_b128 v[182:185], v155 offset:2048
	ds_read_b128 v[186:189], v155 offset:3072
	s_add_u32 s38, s46, 0x40000
	s_addc_u32 s39, s47, 0
	s_mov_b32 m0, s5
	v_lshl_add_u64 v[230:231], s[38:39], 0, v[134:135]
	ds_read_b128 v[190:193], v153 offset:32768
	ds_read_b128 v[194:197], v153 offset:33792
	ds_read_b128 v[198:201], v153 offset:34816
	ds_read_b128 v[202:205], v153 offset:35840
	ds_read_b128 v[210:213], v153 offset:36864
	ds_read_b128 v[214:217], v153 offset:37888
	ds_read_b128 v[218:221], v153 offset:38912
	ds_read_b128 v[222:225], v153 offset:39936
	global_load_lds_dwordx4 v[230:231], off
	v_lshl_add_u64 v[230:231], s[38:39], 0, v[130:131]
	s_mov_b32 m0, s6
	s_nop 0
	global_load_lds_dwordx4 v[230:231], off
	s_waitcnt vmcnt(8)
	s_waitcnt lgkmcnt(0)
	s_barrier
	s_waitcnt lgkmcnt(0)
	v_mfma_f32_16x16x32_bf16 v[124:127], v[144:147], v[190:193], v[124:127]
	v_mfma_f32_16x16x32_bf16 v[120:123], v[166:169], v[190:193], v[120:123]
	v_mfma_f32_16x16x32_bf16 v[108:111], v[144:147], v[198:201], v[108:111]
	v_mfma_f32_16x16x32_bf16 v[104:107], v[166:169], v[198:201], v[104:107]
	v_mfma_f32_16x16x32_bf16 v[92:95], v[144:147], v[210:213], v[92:95]
	v_mfma_f32_16x16x32_bf16 v[88:91], v[166:169], v[210:213], v[88:91]
	v_mfma_f32_16x16x32_bf16 v[76:79], v[144:147], v[218:221], v[76:79]
	v_mfma_f32_16x16x32_bf16 v[72:75], v[166:169], v[218:221], v[72:75]
	v_mfma_f32_16x16x32_bf16 v[124:127], v[156:159], v[194:197], v[124:127]
	v_mfma_f32_16x16x32_bf16 v[120:123], v[170:173], v[194:197], v[120:123]
	v_mfma_f32_16x16x32_bf16 v[108:111], v[156:159], v[202:205], v[108:111]
	v_mfma_f32_16x16x32_bf16 v[104:107], v[170:173], v[202:205], v[104:107]
	v_mfma_f32_16x16x32_bf16 v[92:95], v[156:159], v[214:217], v[92:95]
	v_mfma_f32_16x16x32_bf16 v[88:91], v[170:173], v[214:217], v[88:91]
	v_mfma_f32_16x16x32_bf16 v[76:79], v[156:159], v[222:225], v[76:79]
	v_mfma_f32_16x16x32_bf16 v[72:75], v[170:173], v[222:225], v[72:75]
	v_mfma_f32_16x16x32_bf16 v[116:119], v[174:177], v[190:193], v[116:119]
	v_mfma_f32_16x16x32_bf16 v[112:115], v[182:185], v[190:193], v[112:115]
	v_mfma_f32_16x16x32_bf16 v[100:103], v[174:177], v[198:201], v[100:103]
	v_mfma_f32_16x16x32_bf16 v[96:99], v[182:185], v[198:201], v[96:99]
	v_mfma_f32_16x16x32_bf16 v[84:87], v[174:177], v[210:213], v[84:87]
	v_mfma_f32_16x16x32_bf16 v[80:83], v[182:185], v[210:213], v[80:83]
	v_mfma_f32_16x16x32_bf16 v[68:71], v[174:177], v[218:221], v[68:71]
	v_mfma_f32_16x16x32_bf16 v[64:67], v[182:185], v[218:221], v[64:67]
	v_mfma_f32_16x16x32_bf16 v[116:119], v[178:181], v[194:197], v[116:119]
	v_mfma_f32_16x16x32_bf16 v[112:115], v[186:189], v[194:197], v[112:115]
	v_mfma_f32_16x16x32_bf16 v[100:103], v[178:181], v[202:205], v[100:103]
	v_mfma_f32_16x16x32_bf16 v[96:99], v[186:189], v[202:205], v[96:99]
	v_mfma_f32_16x16x32_bf16 v[84:87], v[178:181], v[214:217], v[84:87]
	v_mfma_f32_16x16x32_bf16 v[80:83], v[186:189], v[214:217], v[80:83]
	v_mfma_f32_16x16x32_bf16 v[68:71], v[178:181], v[222:225], v[68:71]
	v_mfma_f32_16x16x32_bf16 v[64:67], v[186:189], v[222:225], v[64:67]
	s_barrier
; #define PG8_STAGE(bufoff, gbase, voff) do { _Pragma("unroll") for (int _i = 0; _i < 2; ++_i) \
;         __builtin_amdgcn_global_load_lds((const unsigned*)((const char*)(gbase) + (voff)[_i]), (LAS unsigned*)(lds + (bufoff) + ldsw + _i * 8192), 16, 0, 0); } while (0)
; #define PG8_LDA(dst, b, h) do { _Pragma("unroll") for (int m = 0; m < 4; ++m) _Pragma("unroll") for (int k = 0; k < 2; ++k) dst[m][k] = *(const LAS bf16x8*)(lds + PG8_SA(b, h) + aoff + m * 2048 + k * 1024); } while (0)
; #define PG8_MMA(ai, bj, At, Bt) do { __builtin_amdgcn_s_setprio(1); _Pragma("unroll") for (int m = 0; m < 4; ++m) _Pragma("unroll") for (int n = 0; n < 2; ++n) _Pragma("unroll") for (int k = 0; k < 2; ++k) \
;         acc[ai][bj][m][n] = __builtin_amdgcn_mfma_f32_16x16x32_bf16(Bt[n][k], At[m][k], acc[ai][bj][m][n], 0, 0, 0); __builtin_amdgcn_s_setprio(0); } while (0)
; #define PG8_WAIT_V(n) asm volatile("s_waitcnt vmcnt(" #n ")" ::: "memory")
; #define PG8_WAIT_L(n) asm volatile("s_waitcnt lgkmcnt(" #n ")" ::: "memory")
; #define PG8_BAR __builtin_amdgcn_s_barrier()
; #define PG8_SCHED __builtin_amdgcn_sched_barrier(0)
;     DI void operator()(Acc& acc, const Unit& u, int wr, int wc, int fr, int fq, LAS unsigned char*) const {
;     ...
;             for (int m = 0; m < 4; ++m) { const int row = u.pm * BM + ai * HALF + wr * 64 + m * 16 + fr; bf16_t* rowp = O + (size_t)row * ldc + col0;
;                 float rs = 1.0f; if (HAS_RS) { const f32x4 q4 = *(const f32x4*)(sumsq + (size_t)row * 4); rs = rsqrtf(((q4.x + q4.y) + (q4.z + q4.w)) * (1.0f / DM) + EPS); }
; template <class GEO, class Epi>
; __device__ __forceinline__ void gemm_phase(LAS unsigned char* lds, const Gemm g, const StaticOrder& S, const Epi& E) {
;     ...
;             PG8_LDA(At, 1, 1); PG8_STAGE(PG8_SB(1, 0), b3, voffB); PG8_STAGE(PG8_SB(1, 1), b3 + hstepB, voffB); PG8_STAGE(PG8_SA(1, 0), a3, voffA);
;             PG8_WAIT_V(8); PG8_WAIT_L(0); PG8_BAR; PG8_MMA(1, 0, At, B0); PG8_MMA(1, 1, At, B1); PG8_BAR; PG8_SCHED;
;         }
;         if (wr == 0) PG8_BAR;
	s_add_i32 s38, s52, s0
	v_lshl_add_u64 v[160:161], v[160:161], 0, s[24:25]
	s_mov_b32 m0, s38
	ds_read_b128 v[190:193], v153 offset:49152
	ds_read_b128 v[194:197], v153 offset:50176
	ds_read_b128 v[198:201], v153 offset:51200
	ds_read_b128 v[202:205], v153 offset:52224
	ds_read_b128 v[210:213], v153 offset:53248
	ds_read_b128 v[214:217], v153 offset:54272
	ds_read_b128 v[218:221], v153 offset:55296
	ds_read_b128 v[222:225], v153 offset:56320
	global_load_lds_dwordx4 v[160:161], off
	s_add_i32 m0, s38, 0x2000
	s_add_u32 s38, s44, 0x40080
	v_lshl_add_u64 v[160:161], v[206:207], 0, s[24:25]
	s_addc_u32 s39, s45, 0
	s_add_i32 s44, s53, s0
	global_load_lds_dwordx4 v[160:161], off
	v_lshl_add_u64 v[160:161], s[38:39], 0, v[132:133]
	s_mov_b32 m0, s44
	s_nop 0
	global_load_lds_dwordx4 v[160:161], off
	v_lshl_add_u64 v[160:161], s[38:39], 0, v[128:129]
	s_add_i32 m0, s44, 0x2000
	s_nop 0
	global_load_lds_dwordx4 v[160:161], off
	v_lshl_add_u64 v[160:161], v[226:227], 0, s[24:25]
	s_mov_b32 m0, s7
	s_nop 0
	global_load_lds_dwordx4 v[160:161], off
	v_lshl_add_u64 v[160:161], v[228:229], 0, s[24:25]
	s_mov_b32 m0, s12
	s_nop 0
	global_load_lds_dwordx4 v[160:161], off
	s_waitcnt vmcnt(8)
	s_waitcnt lgkmcnt(0)
	s_barrier
	s_waitcnt lgkmcnt(0)
	v_mfma_f32_16x16x32_bf16 v[60:63], v[144:147], v[190:193], v[60:63]
	v_mfma_f32_16x16x32_bf16 v[56:59], v[166:169], v[190:193], v[56:59]
	v_mfma_f32_16x16x32_bf16 v[44:47], v[144:147], v[198:201], v[44:47]
	v_mfma_f32_16x16x32_bf16 v[40:43], v[166:169], v[198:201], v[40:43]
	v_mfma_f32_16x16x32_bf16 v[28:31], v[144:147], v[210:213], v[28:31]
	v_mfma_f32_16x16x32_bf16 v[24:27], v[166:169], v[210:213], v[24:27]
	v_mfma_f32_16x16x32_bf16 v[12:15], v[144:147], v[218:221], v[12:15]
	v_mfma_f32_16x16x32_bf16 v[8:11], v[166:169], v[218:221], v[8:11]
	v_mfma_f32_16x16x32_bf16 v[60:63], v[156:159], v[194:197], v[60:63]
	v_mfma_f32_16x16x32_bf16 v[56:59], v[170:173], v[194:197], v[56:59]
	v_mfma_f32_16x16x32_bf16 v[44:47], v[156:159], v[202:205], v[44:47]
	v_mfma_f32_16x16x32_bf16 v[40:43], v[170:173], v[202:205], v[40:43]
	v_mfma_f32_16x16x32_bf16 v[28:31], v[156:159], v[214:217], v[28:31]
	v_mfma_f32_16x16x32_bf16 v[24:27], v[170:173], v[214:217], v[24:27]
	v_mfma_f32_16x16x32_bf16 v[12:15], v[156:159], v[222:225], v[12:15]
	v_mfma_f32_16x16x32_bf16 v[8:11], v[170:173], v[222:225], v[8:11]
	v_mfma_f32_16x16x32_bf16 v[52:55], v[174:177], v[190:193], v[52:55]
	v_mfma_f32_16x16x32_bf16 v[48:51], v[182:185], v[190:193], v[48:51]
	v_mfma_f32_16x16x32_bf16 v[36:39], v[174:177], v[198:201], v[36:39]
	v_mfma_f32_16x16x32_bf16 v[32:35], v[182:185], v[198:201], v[32:35]
	v_mfma_f32_16x16x32_bf16 v[20:23], v[174:177], v[210:213], v[20:23]
	v_mfma_f32_16x16x32_bf16 v[16:19], v[182:185], v[210:213], v[16:19]
	v_mfma_f32_16x16x32_bf16 v[4:7], v[174:177], v[218:221], v[4:7]
	v_mfma_f32_16x16x32_bf16 v[0:3], v[182:185], v[218:221], v[0:3]
	v_mfma_f32_16x16x32_bf16 v[52:55], v[178:181], v[194:197], v[52:55]
	v_mfma_f32_16x16x32_bf16 v[48:51], v[186:189], v[194:197], v[48:51]
	v_mfma_f32_16x16x32_bf16 v[36:39], v[178:181], v[202:205], v[36:39]
	v_mfma_f32_16x16x32_bf16 v[32:35], v[186:189], v[202:205], v[32:35]
	v_mfma_f32_16x16x32_bf16 v[20:23], v[178:181], v[214:217], v[20:23]
	v_mfma_f32_16x16x32_bf16 v[16:19], v[186:189], v[214:217], v[16:19]
	v_mfma_f32_16x16x32_bf16 v[4:7], v[178:181], v[222:225], v[4:7]
	v_mfma_f32_16x16x32_bf16 v[0:3], v[186:189], v[222:225], v[0:3]
	s_barrier
	s_add_i32 s51, s51, 2
	s_add_u32 s22, s22, 0x100
	s_addc_u32 s23, s23, 0
	s_add_u32 s49, s49, 0x100
	s_addc_u32 s50, s50, 0
	s_cmp_gt_u32 s51, 13
	s_cbranch_scc0 .LBB0_1075
	v_lshl_add_u32 v144, s20, 8, v148
	v_lshl_or_b32 v146, s37, 8, v150
	v_ashrrev_i32_e32 v145, 31, v144
	v_ashrrev_i32_e32 v147, 31, v146
	v_lshl_add_u64 v[156:157], v[144:145], 4, s[8:9]
	global_load_dwordx4 v[166:169], v[156:157], off offset:2048
	global_load_dwordx4 v[170:173], v[156:157], off offset:2304
	global_load_dwordx4 v[174:177], v[156:157], off offset:2560
	global_load_dwordx4 v[178:181], v[156:157], off offset:2816
	s_and_b64 vcc, exec, s[28:29]
	s_cbranch_vccz .LBB0_1078
	s_barrier

; #define PG8_STAGE(bufoff, gbase, voff) do { _Pragma("unroll") for (int _i = 0; _i < 2; ++_i) \
;         __builtin_amdgcn_global_load_lds((const unsigned*)((const char*)(gbase) + (voff)[_i]), (LAS unsigned*)(lds + (bufoff) + ldsw + _i * 8192), 16, 0, 0); } while (0)
; #define PG8_LDA(dst, b, h) do { _Pragma("unroll") for (int m = 0; m < 4; ++m) _Pragma("unroll") for (int k = 0; k < 2; ++k) dst[m][k] = *(const LAS bf16x8*)(lds + PG8_SA(b, h) + aoff + m * 2048 + k * 1024); } while (0)
; #define PG8_LDB(dst, b, h) do { _Pragma("unroll") for (int n = 0; n < 2; ++n) _Pragma("unroll") for (int k = 0; k < 2; ++k) dst[n][k] = *(const LAS bf16x8*)(lds + PG8_SB(b, h) + boff + n * 2048 + k * 1024); } while (0)
; #define PG8_MMA(ai, bj, At, Bt) do { __builtin_amdgcn_s_setprio(1); _Pragma("unroll") for (int m = 0; m < 4; ++m) _Pragma("unroll") for (int n = 0; n < 2; ++n) _Pragma("unroll") for (int k = 0; k < 2; ++k) \
;         acc[ai][bj][m][n] = __builtin_amdgcn_mfma_f32_16x16x32_bf16(Bt[n][k], At[m][k], acc[ai][bj][m][n], 0, 0, 0); __builtin_amdgcn_s_setprio(0); } while (0)
; #define PG8_WAIT_V(n) asm volatile("s_waitcnt vmcnt(" #n ")" ::: "memory")
; #define PG8_WAIT_L(n) asm volatile("s_waitcnt lgkmcnt(" #n ")" ::: "memory")
; #define PG8_BAR __builtin_amdgcn_s_barrier()
; #define PG8_SCHED __builtin_amdgcn_sched_barrier(0)
; template <class GEO, class Epi>
; __device__ __forceinline__ void gemm_phase(LAS unsigned char* lds, const Gemm g, const StaticOrder& S, const Epi& E) {
;     ...
;             const bool last = (t == nt - 2);
;             const char* a1 = cA + (size_t)(t + 1) * kstep;
;             const char* a2 = last ? nA : cA + (size_t)(t + 2) * kstep; const char* b2 = last ? nB : cB + (size_t)(t + 2) * kstep;
;             const char* a3 = a2 + kstep; const char* b3 = b2 + kstep;
;             PG8_LDB(B0, 0, 0); PG8_LDB(B1, 0, 1); PG8_SCHED; PG8_LDA(At, 0, 0); PG8_STAGE(PG8_SA(1, 1), a1 + hstepA, voffA);
;             PG8_WAIT_V(8); PG8_WAIT_L(0); PG8_BAR; PG8_MMA(0, 0, At, B0); PG8_MMA(0, 1, At, B1); PG8_BAR; PG8_SCHED;
;             PG8_LDA(At, 0, 1); PG8_STAGE(PG8_SB(0, 0), b2, voffB); PG8_STAGE(PG8_SB(0, 1), b2 + hstepB, voffB); PG8_STAGE(PG8_SA(0, 0), a2, voffA);
.LBB0_1148:
	ds_read_b128 v[144:147], v151
	ds_read_b128 v[154:157], v151 offset:1024
	ds_read_b128 v[158:161], v151 offset:2048
	ds_read_b128 v[162:165], v151 offset:3072
	ds_read_b128 v[166:169], v152
	ds_read_b128 v[170:173], v152 offset:1024
	ds_read_b128 v[174:177], v152 offset:2048
	ds_read_b128 v[178:181], v152 offset:3072
	s_add_u32 s24, s22, 0xfff00080
	s_addc_u32 s25, s23, -1
	s_cmp_eq_u32 s46, 60
	s_cselect_b32 s29, s15, s25
	s_cselect_b32 s28, s42, s24
	s_cselect_b32 s25, s4, s45
	s_cselect_b32 s24, s43, s44
	v_lshl_add_u64 v[214:215], s[22:23], 0, v[136:137]
	s_add_i32 m0, s21, 0xc000
	ds_read_b128 v[182:185], v153
	ds_read_b128 v[186:189], v153 offset:1024
	ds_read_b128 v[190:193], v153 offset:2048
	ds_read_b128 v[194:197], v153 offset:3072
	ds_read_b128 v[198:201], v153 offset:4096
	ds_read_b128 v[202:205], v153 offset:5120
	ds_read_b128 v[206:209], v153 offset:6144
	ds_read_b128 v[210:213], v153 offset:7168
	global_load_lds_dwordx4 v[214:215], off
	v_lshl_add_u64 v[214:215], s[22:23], 0, v[138:139]
	s_add_i32 m0, s21, 0xe000
	s_nop 0
	global_load_lds_dwordx4 v[214:215], off
	s_waitcnt vmcnt(8)
	s_waitcnt lgkmcnt(0)
	s_barrier
	s_waitcnt lgkmcnt(0)
	v_mfma_f32_16x16x32_bf16 v[124:127], v[144:147], v[182:185], v[124:127]
	v_mfma_f32_16x16x32_bf16 v[120:123], v[158:161], v[182:185], v[120:123]
	v_mfma_f32_16x16x32_bf16 v[108:111], v[144:147], v[190:193], v[108:111]
	v_mfma_f32_16x16x32_bf16 v[104:107], v[158:161], v[190:193], v[104:107]
	v_mfma_f32_16x16x32_bf16 v[92:95], v[144:147], v[198:201], v[92:95]
	v_mfma_f32_16x16x32_bf16 v[88:91], v[158:161], v[198:201], v[88:91]
	v_mfma_f32_16x16x32_bf16 v[76:79], v[144:147], v[206:209], v[76:79]
	v_mfma_f32_16x16x32_bf16 v[72:75], v[158:161], v[206:209], v[72:75]
	v_mfma_f32_16x16x32_bf16 v[124:127], v[154:157], v[186:189], v[124:127]
	v_mfma_f32_16x16x32_bf16 v[120:123], v[162:165], v[186:189], v[120:123]
	v_mfma_f32_16x16x32_bf16 v[108:111], v[154:157], v[194:197], v[108:111]
	v_mfma_f32_16x16x32_bf16 v[104:107], v[162:165], v[194:197], v[104:107]
	v_mfma_f32_16x16x32_bf16 v[92:95], v[154:157], v[202:205], v[92:95]
	v_mfma_f32_16x16x32_bf16 v[88:91], v[162:165], v[202:205], v[88:91]
	v_mfma_f32_16x16x32_bf16 v[76:79], v[154:157], v[210:213], v[76:79]
	v_mfma_f32_16x16x32_bf16 v[72:75], v[162:165], v[210:213], v[72:75]
	v_mfma_f32_16x16x32_bf16 v[116:119], v[166:169], v[182:185], v[116:119]
	v_mfma_f32_16x16x32_bf16 v[112:115], v[174:177], v[182:185], v[112:115]
	v_mfma_f32_16x16x32_bf16 v[100:103], v[166:169], v[190:193], v[100:103]
	v_mfma_f32_16x16x32_bf16 v[96:99], v[174:177], v[190:193], v[96:99]
	v_mfma_f32_16x16x32_bf16 v[84:87], v[166:169], v[198:201], v[84:87]
	v_mfma_f32_16x16x32_bf16 v[80:83], v[174:177], v[198:201], v[80:83]
	v_mfma_f32_16x16x32_bf16 v[68:71], v[166:169], v[206:209], v[68:71]
	v_mfma_f32_16x16x32_bf16 v[64:67], v[174:177], v[206:209], v[64:67]
	v_mfma_f32_16x16x32_bf16 v[116:119], v[170:173], v[186:189], v[116:119]
	v_mfma_f32_16x16x32_bf16 v[112:115], v[178:181], v[186:189], v[112:115]
	v_mfma_f32_16x16x32_bf16 v[100:103], v[170:173], v[194:197], v[100:103]
	v_mfma_f32_16x16x32_bf16 v[96:99], v[178:181], v[194:197], v[96:99]
	v_mfma_f32_16x16x32_bf16 v[84:87], v[170:173], v[202:205], v[84:87]
	v_mfma_f32_16x16x32_bf16 v[80:83], v[178:181], v[202:205], v[80:83]
	v_mfma_f32_16x16x32_bf16 v[68:71], v[170:173], v[210:213], v[68:71]
	v_mfma_f32_16x16x32_bf16 v[64:67], v[178:181], v[210:213], v[64:67]
	s_barrier
	s_add_i32 s47, s37, s30
	v_lshl_add_u64 v[214:215], s[24:25], 0, v[130:131]
	s_mov_b32 m0, s47
	ds_read_b128 v[182:185], v153 offset:16384
	ds_read_b128 v[186:189], v153 offset:17408
	ds_read_b128 v[190:193], v153 offset:18432
	ds_read_b128 v[194:197], v153 offset:19456
	ds_read_b128 v[198:201], v153 offset:20480
	ds_read_b128 v[202:205], v153 offset:21504
	ds_read_b128 v[206:209], v153 offset:22528
	ds_read_b128 v[210:213], v153 offset:23552
	global_load_lds_dwordx4 v[214:215], off
	s_add_i32 m0, s47, 0x2000
	s_add_u32 s48, s24, 0x100000
	v_lshl_add_u64 v[216:217], s[24:25], 0, v[134:135]
	s_addc_u32 s49, s25, 0
	s_add_i32 s47, s38, s30
	global_load_lds_dwordx4 v[216:217], off
	v_lshl_add_u64 v[218:219], s[48:49], 0, v[130:131]
	s_mov_b32 m0, s47
	v_lshl_add_u64 v[220:221], s[28:29], 0, v[132:133]
	global_load_lds_dwordx4 v[218:219], off
	v_lshl_add_u64 v[218:219], s[48:49], 0, v[134:135]
	s_add_i32 m0, s47, 0x2000
	s_nop 0
	global_load_lds_dwordx4 v[218:219], off
	v_lshl_add_u64 v[218:219], s[28:29], 0, v[128:129]
	s_mov_b32 m0, s21
	s_nop 0
	global_load_lds_dwordx4 v[218:219], off
	s_mov_b32 m0, s31
	s_nop 0
	global_load_lds_dwordx4 v[220:221], off
	s_waitcnt vmcnt(8)
	s_waitcnt lgkmcnt(0)
	s_barrier
; #define PG8_STAGE(bufoff, gbase, voff) do { _Pragma("unroll") for (int _i = 0; _i < 2; ++_i) \
;         __builtin_amdgcn_global_load_lds((const unsigned*)((const char*)(gbase) + (voff)[_i]), (LAS unsigned*)(lds + (bufoff) + ldsw + _i * 8192), 16, 0, 0); } while (0)
; #define PG8_LDA(dst, b, h) do { _Pragma("unroll") for (int m = 0; m < 4; ++m) _Pragma("unroll") for (int k = 0; k < 2; ++k) dst[m][k] = *(const LAS bf16x8*)(lds + PG8_SA(b, h) + aoff + m * 2048 + k * 1024); } while (0)
; #define PG8_LDB(dst, b, h) do { _Pragma("unroll") for (int n = 0; n < 2; ++n) _Pragma("unroll") for (int k = 0; k < 2; ++k) dst[n][k] = *(const LAS bf16x8*)(lds + PG8_SB(b, h) + boff + n * 2048 + k * 1024); } while (0)
; #define PG8_MMA(ai, bj, At, Bt) do { __builtin_amdgcn_s_setprio(1); _Pragma("unroll") for (int m = 0; m < 4; ++m) _Pragma("unroll") for (int n = 0; n < 2; ++n) _Pragma("unroll") for (int k = 0; k < 2; ++k) \
;         acc[ai][bj][m][n] = __builtin_amdgcn_mfma_f32_16x16x32_bf16(Bt[n][k], At[m][k], acc[ai][bj][m][n], 0, 0, 0); __builtin_amdgcn_s_setprio(0); } while (0)
; #define PG8_WAIT_V(n) asm volatile("s_waitcnt vmcnt(" #n ")" ::: "memory")
; #define PG8_WAIT_L(n) asm volatile("s_waitcnt lgkmcnt(" #n ")" ::: "memory")
; #define PG8_BAR __builtin_amdgcn_s_barrier()
; #define PG8_SCHED __builtin_amdgcn_sched_barrier(0)
; template <class GEO, class Epi>
; __device__ __forceinline__ void gemm_phase(LAS unsigned char* lds, const Gemm g, const StaticOrder& S, const Epi& E) {
;     ...
;             PG8_WAIT_V(8); PG8_WAIT_L(0); PG8_BAR; PG8_MMA(1, 0, At, B0); PG8_MMA(1, 1, At, B1); PG8_BAR; PG8_SCHED;
;             PG8_LDB(B0, 1, 0); PG8_LDB(B1, 1, 1); PG8_SCHED; PG8_LDA(At, 1, 0); PG8_STAGE(PG8_SA(0, 1), a2 + hstepA, voffA);
;             PG8_WAIT_V(8); PG8_WAIT_L(0); PG8_BAR; PG8_MMA(0, 0, At, B0); PG8_MMA(0, 1, At, B1); PG8_BAR; PG8_SCHED;
	s_waitcnt lgkmcnt(0)
	v_mfma_f32_16x16x32_bf16 v[60:63], v[144:147], v[182:185], v[60:63]
	v_mfma_f32_16x16x32_bf16 v[56:59], v[158:161], v[182:185], v[56:59]
	v_mfma_f32_16x16x32_bf16 v[44:47], v[144:147], v[190:193], v[44:47]
	v_mfma_f32_16x16x32_bf16 v[40:43], v[158:161], v[190:193], v[40:43]
	v_mfma_f32_16x16x32_bf16 v[28:31], v[144:147], v[198:201], v[28:31]
	v_mfma_f32_16x16x32_bf16 v[24:27], v[158:161], v[198:201], v[24:27]
	v_mfma_f32_16x16x32_bf16 v[12:15], v[144:147], v[206:209], v[12:15]
	v_mfma_f32_16x16x32_bf16 v[8:11], v[158:161], v[206:209], v[8:11]
	v_mfma_f32_16x16x32_bf16 v[60:63], v[154:157], v[186:189], v[60:63]
	v_mfma_f32_16x16x32_bf16 v[56:59], v[162:165], v[186:189], v[56:59]
	v_mfma_f32_16x16x32_bf16 v[44:47], v[154:157], v[194:197], v[44:47]
	v_mfma_f32_16x16x32_bf16 v[40:43], v[162:165], v[194:197], v[40:43]
	v_mfma_f32_16x16x32_bf16 v[28:31], v[154:157], v[202:205], v[28:31]
	v_mfma_f32_16x16x32_bf16 v[24:27], v[162:165], v[202:205], v[24:27]
	v_mfma_f32_16x16x32_bf16 v[12:15], v[154:157], v[210:213], v[12:15]
	v_mfma_f32_16x16x32_bf16 v[8:11], v[162:165], v[210:213], v[8:11]
	v_mfma_f32_16x16x32_bf16 v[52:55], v[166:169], v[182:185], v[52:55]
	v_mfma_f32_16x16x32_bf16 v[48:51], v[174:177], v[182:185], v[48:51]
	v_mfma_f32_16x16x32_bf16 v[36:39], v[166:169], v[190:193], v[36:39]
	v_mfma_f32_16x16x32_bf16 v[32:35], v[174:177], v[190:193], v[32:35]
	v_mfma_f32_16x16x32_bf16 v[20:23], v[166:169], v[198:201], v[20:23]
	v_mfma_f32_16x16x32_bf16 v[16:19], v[174:177], v[198:201], v[16:19]
	v_mfma_f32_16x16x32_bf16 v[4:7], v[166:169], v[206:209], v[4:7]
	v_mfma_f32_16x16x32_bf16 v[0:3], v[174:177], v[206:209], v[0:3]
	v_mfma_f32_16x16x32_bf16 v[52:55], v[170:173], v[186:189], v[52:55]
	v_mfma_f32_16x16x32_bf16 v[48:51], v[178:181], v[186:189], v[48:51]
	v_mfma_f32_16x16x32_bf16 v[36:39], v[170:173], v[194:197], v[36:39]
	v_mfma_f32_16x16x32_bf16 v[32:35], v[178:181], v[194:197], v[32:35]
	v_mfma_f32_16x16x32_bf16 v[20:23], v[170:173], v[202:205], v[20:23]
	v_mfma_f32_16x16x32_bf16 v[16:19], v[178:181], v[202:205], v[16:19]
	v_mfma_f32_16x16x32_bf16 v[4:7], v[170:173], v[210:213], v[4:7]
	v_mfma_f32_16x16x32_bf16 v[0:3], v[178:181], v[210:213], v[0:3]
	s_barrier
	s_add_i32 s47, 0, 0x18000
	s_add_i32 s48, 0, 0x1c000
	v_add_u32_e32 v162, s47, v149
	v_add_u32_e32 v178, s48, v149
	ds_read_b128 v[144:147], v162
	ds_read_b128 v[154:157], v162 offset:1024
	ds_read_b128 v[158:161], v162 offset:2048
	ds_read_b128 v[162:165], v162 offset:3072
	ds_read_b128 v[166:169], v178
	ds_read_b128 v[170:173], v178 offset:1024
	ds_read_b128 v[174:177], v178 offset:2048
	ds_read_b128 v[178:181], v178 offset:3072
	s_add_u32 s28, s28, 0x100000
	s_addc_u32 s29, s29, 0
	s_mov_b32 m0, s33
	v_lshl_add_u64 v[222:223], s[28:29], 0, v[128:129]
	ds_read_b128 v[182:185], v153 offset:32768
	ds_read_b128 v[186:189], v153 offset:33792
	ds_read_b128 v[190:193], v153 offset:34816
	ds_read_b128 v[194:197], v153 offset:35840
	ds_read_b128 v[198:201], v153 offset:36864
	ds_read_b128 v[202:205], v153 offset:37888
	ds_read_b128 v[206:209], v153 offset:38912
	ds_read_b128 v[210:213], v153 offset:39936
	global_load_lds_dwordx4 v[222:223], off
	v_lshl_add_u64 v[222:223], s[28:29], 0, v[132:133]
	s_mov_b32 m0, s34
	s_nop 0
	global_load_lds_dwordx4 v[222:223], off
	s_waitcnt vmcnt(8)
	s_waitcnt lgkmcnt(0)
	s_barrier
	s_waitcnt lgkmcnt(0)
	v_mfma_f32_16x16x32_bf16 v[124:127], v[144:147], v[182:185], v[124:127]
	v_mfma_f32_16x16x32_bf16 v[120:123], v[158:161], v[182:185], v[120:123]
	v_mfma_f32_16x16x32_bf16 v[108:111], v[144:147], v[190:193], v[108:111]
	v_mfma_f32_16x16x32_bf16 v[104:107], v[158:161], v[190:193], v[104:107]
	v_mfma_f32_16x16x32_bf16 v[92:95], v[144:147], v[198:201], v[92:95]
	v_mfma_f32_16x16x32_bf16 v[88:91], v[158:161], v[198:201], v[88:91]
	v_mfma_f32_16x16x32_bf16 v[76:79], v[144:147], v[206:209], v[76:79]
	v_mfma_f32_16x16x32_bf16 v[72:75], v[158:161], v[206:209], v[72:75]
	v_mfma_f32_16x16x32_bf16 v[124:127], v[154:157], v[186:189], v[124:127]
	v_mfma_f32_16x16x32_bf16 v[120:123], v[162:165], v[186:189], v[120:123]
	v_mfma_f32_16x16x32_bf16 v[108:111], v[154:157], v[194:197], v[108:111]
	v_mfma_f32_16x16x32_bf16 v[104:107], v[162:165], v[194:197], v[104:107]
	v_mfma_f32_16x16x32_bf16 v[92:95], v[154:157], v[202:205], v[92:95]
	v_mfma_f32_16x16x32_bf16 v[88:91], v[162:165], v[202:205], v[88:91]
	v_mfma_f32_16x16x32_bf16 v[76:79], v[154:157], v[210:213], v[76:79]
	v_mfma_f32_16x16x32_bf16 v[72:75], v[162:165], v[210:213], v[72:75]
	v_mfma_f32_16x16x32_bf16 v[116:119], v[166:169], v[182:185], v[116:119]
	v_mfma_f32_16x16x32_bf16 v[112:115], v[174:177], v[182:185], v[112:115]
	v_mfma_f32_16x16x32_bf16 v[100:103], v[166:169], v[190:193], v[100:103]
	v_mfma_f32_16x16x32_bf16 v[96:99], v[174:177], v[190:193], v[96:99]
	v_mfma_f32_16x16x32_bf16 v[84:87], v[166:169], v[198:201], v[84:87]
	v_mfma_f32_16x16x32_bf16 v[80:83], v[174:177], v[198:201], v[80:83]
	v_mfma_f32_16x16x32_bf16 v[68:71], v[166:169], v[206:209], v[68:71]
	v_mfma_f32_16x16x32_bf16 v[64:67], v[174:177], v[206:209], v[64:67]
	v_mfma_f32_16x16x32_bf16 v[116:119], v[170:173], v[186:189], v[116:119]
	v_mfma_f32_16x16x32_bf16 v[112:115], v[178:181], v[186:189], v[112:115]
	v_mfma_f32_16x16x32_bf16 v[100:103], v[170:173], v[194:197], v[100:103]
	v_mfma_f32_16x16x32_bf16 v[96:99], v[178:181], v[194:197], v[96:99]
	v_mfma_f32_16x16x32_bf16 v[84:87], v[170:173], v[202:205], v[84:87]
	v_mfma_f32_16x16x32_bf16 v[80:83], v[178:181], v[202:205], v[80:83]
	v_mfma_f32_16x16x32_bf16 v[68:71], v[170:173], v[210:213], v[68:71]
	v_mfma_f32_16x16x32_bf16 v[64:67], v[178:181], v[210:213], v[64:67]
	s_barrier
; DI float bflo(unsigned w) { return __uint_as_float(w << 16); }
; DI float bfhi(unsigned w) { return __uint_as_float(w & 0xffff0000u); }
; #define PG8_STAGE(bufoff, gbase, voff) do { _Pragma("unroll") for (int _i = 0; _i < 2; ++_i) \
;         __builtin_amdgcn_global_load_lds((const unsigned*)((const char*)(gbase) + (voff)[_i]), (LAS unsigned*)(lds + (bufoff) + ldsw + _i * 8192), 16, 0, 0); } while (0)
; #define PG8_LDA(dst, b, h) do { _Pragma("unroll") for (int m = 0; m < 4; ++m) _Pragma("unroll") for (int k = 0; k < 2; ++k) dst[m][k] = *(const LAS bf16x8*)(lds + PG8_SA(b, h) + aoff + m * 2048 + k * 1024); } while (0)
; #define PG8_MMA(ai, bj, At, Bt) do { __builtin_amdgcn_s_setprio(1); _Pragma("unroll") for (int m = 0; m < 4; ++m) _Pragma("unroll") for (int n = 0; n < 2; ++n) _Pragma("unroll") for (int k = 0; k < 2; ++k) \
;         acc[ai][bj][m][n] = __builtin_amdgcn_mfma_f32_16x16x32_bf16(Bt[n][k], At[m][k], acc[ai][bj][m][n], 0, 0, 0); __builtin_amdgcn_s_setprio(0); } while (0)
; #define PG8_WAIT_V(n) asm volatile("s_waitcnt vmcnt(" #n ")" ::: "memory")
; #define PG8_WAIT_L(n) asm volatile("s_waitcnt lgkmcnt(" #n ")" ::: "memory")
; #define PG8_BAR __builtin_amdgcn_s_barrier()
;     DI void operator()(Acc& acc, const Unit& u, int wr, int wc, int fr, int fq, LAS unsigned char* lds) const {
;     ...
;             for (int m = 0; m < 4; ++m) { const int row = u.pm * BM + ai * HALF + wr * 64 + m * 16 + fr; const size_t off = (size_t)row * DM + col0; float ss = 0.f;
; #pragma unroll
;                 for (int bj = 0; bj < 2; ++bj) { const size_t o = off + bj * HALF;
;                     f32x4 b0, b1;
;                     if (BASE_BF16) { const u32x4 w = *(const u32x4*)((const bf16_t*)base + o); b0 = (f32x4){bflo(w.x), bfhi(w.x), bflo(w.y), bfhi(w.y)}; b1 = (f32x4){bflo(w.z), bfhi(w.z), bflo(w.w), bfhi(w.w)}; }
;                     else { b0 = *(const f32x4*)((const float*)base + o); b1 = *(const f32x4*)((const float*)base + o + 4); }
; template <class GEO, class Epi>
; __device__ __forceinline__ void gemm_phase(LAS unsigned char* lds, const Gemm g, const StaticOrder& S, const Epi& E) {
;     ...
;             PG8_LDA(At, 1, 1); PG8_STAGE(PG8_SB(1, 0), b3, voffB); PG8_STAGE(PG8_SB(1, 1), b3 + hstepB, voffB); PG8_STAGE(PG8_SA(1, 0), a3, voffA);
;             PG8_WAIT_V(8); PG8_WAIT_L(0); PG8_BAR; PG8_MMA(1, 0, At, B0); PG8_MMA(1, 1, At, B1); PG8_BAR; PG8_SCHED;
;         }
	s_add_i32 s28, s47, s30
	v_lshl_add_u64 v[214:215], v[214:215], 0, s[8:9]
	s_mov_b32 m0, s28
	ds_read_b128 v[182:185], v153 offset:49152
	ds_read_b128 v[186:189], v153 offset:50176
	ds_read_b128 v[190:193], v153 offset:51200
	ds_read_b128 v[194:197], v153 offset:52224
	ds_read_b128 v[198:201], v153 offset:53248
	ds_read_b128 v[202:205], v153 offset:54272
	ds_read_b128 v[206:209], v153 offset:55296
	ds_read_b128 v[210:213], v153 offset:56320
	global_load_lds_dwordx4 v[214:215], off
	s_add_i32 m0, s28, 0x2000
	s_add_u32 s24, s24, 0x100080
	v_lshl_add_u64 v[214:215], v[216:217], 0, s[8:9]
	s_addc_u32 s25, s25, 0
	s_add_i32 s28, s48, s30
	global_load_lds_dwordx4 v[214:215], off
	v_lshl_add_u64 v[214:215], s[24:25], 0, v[130:131]
	s_mov_b32 m0, s28
	s_nop 0
	global_load_lds_dwordx4 v[214:215], off
	v_lshl_add_u64 v[214:215], s[24:25], 0, v[134:135]
	s_add_i32 m0, s28, 0x2000
	s_nop 0
	global_load_lds_dwordx4 v[214:215], off
	v_lshl_add_u64 v[214:215], v[218:219], 0, s[8:9]
	s_mov_b32 m0, s35
	s_nop 0
	global_load_lds_dwordx4 v[214:215], off
	v_lshl_add_u64 v[214:215], v[220:221], 0, s[8:9]
	s_mov_b32 m0, s36
	s_nop 0
	global_load_lds_dwordx4 v[214:215], off
	s_waitcnt vmcnt(8)
	s_waitcnt lgkmcnt(0)
	s_barrier
	s_waitcnt lgkmcnt(0)
	v_mfma_f32_16x16x32_bf16 v[60:63], v[144:147], v[182:185], v[60:63]
	v_mfma_f32_16x16x32_bf16 v[56:59], v[158:161], v[182:185], v[56:59]
	v_mfma_f32_16x16x32_bf16 v[44:47], v[144:147], v[190:193], v[44:47]
	v_mfma_f32_16x16x32_bf16 v[40:43], v[158:161], v[190:193], v[40:43]
	v_mfma_f32_16x16x32_bf16 v[28:31], v[144:147], v[198:201], v[28:31]
	v_mfma_f32_16x16x32_bf16 v[24:27], v[158:161], v[198:201], v[24:27]
	v_mfma_f32_16x16x32_bf16 v[12:15], v[144:147], v[206:209], v[12:15]
	v_mfma_f32_16x16x32_bf16 v[8:11], v[158:161], v[206:209], v[8:11]
	v_mfma_f32_16x16x32_bf16 v[60:63], v[154:157], v[186:189], v[60:63]
	v_mfma_f32_16x16x32_bf16 v[56:59], v[162:165], v[186:189], v[56:59]
	v_mfma_f32_16x16x32_bf16 v[44:47], v[154:157], v[194:197], v[44:47]
	v_mfma_f32_16x16x32_bf16 v[40:43], v[162:165], v[194:197], v[40:43]
	v_mfma_f32_16x16x32_bf16 v[28:31], v[154:157], v[202:205], v[28:31]
	v_mfma_f32_16x16x32_bf16 v[24:27], v[162:165], v[202:205], v[24:27]
	v_mfma_f32_16x16x32_bf16 v[12:15], v[154:157], v[210:213], v[12:15]
	v_mfma_f32_16x16x32_bf16 v[8:11], v[162:165], v[210:213], v[8:11]
	v_mfma_f32_16x16x32_bf16 v[52:55], v[166:169], v[182:185], v[52:55]
	v_mfma_f32_16x16x32_bf16 v[48:51], v[174:177], v[182:185], v[48:51]
	v_mfma_f32_16x16x32_bf16 v[36:39], v[166:169], v[190:193], v[36:39]
	v_mfma_f32_16x16x32_bf16 v[32:35], v[174:177], v[190:193], v[32:35]
	v_mfma_f32_16x16x32_bf16 v[20:23], v[166:169], v[198:201], v[20:23]
	v_mfma_f32_16x16x32_bf16 v[16:19], v[174:177], v[198:201], v[16:19]
	v_mfma_f32_16x16x32_bf16 v[4:7], v[166:169], v[206:209], v[4:7]
	v_mfma_f32_16x16x32_bf16 v[0:3], v[174:177], v[206:209], v[0:3]
	v_mfma_f32_16x16x32_bf16 v[52:55], v[170:173], v[186:189], v[52:55]
	v_mfma_f32_16x16x32_bf16 v[48:51], v[178:181], v[186:189], v[48:51]
	v_mfma_f32_16x16x32_bf16 v[36:39], v[170:173], v[194:197], v[36:39]
	v_mfma_f32_16x16x32_bf16 v[32:35], v[178:181], v[194:197], v[32:35]
	v_mfma_f32_16x16x32_bf16 v[20:23], v[170:173], v[202:205], v[20:23]
	v_mfma_f32_16x16x32_bf16 v[16:19], v[178:181], v[202:205], v[16:19]
	v_mfma_f32_16x16x32_bf16 v[4:7], v[170:173], v[210:213], v[4:7]
	v_mfma_f32_16x16x32_bf16 v[0:3], v[178:181], v[210:213], v[0:3]
	s_barrier
	s_add_i32 s46, s46, 2
	s_add_u32 s22, s22, 0x100
	s_addc_u32 s23, s23, 0
	s_add_u32 s44, s44, 0x100
	s_addc_u32 s45, s45, 0
	s_cmp_gt_u32 s46, 61
	s_cbranch_scc0 .LBB0_1148
	v_lshl_add_u32 v146, s20, 8, v148
	v_lshl_or_b32 v144, s41, 8, v150
	v_ashrrev_i32_e32 v147, 31, v146
	v_ashrrev_i32_e32 v145, 31, v144
	v_lshlrev_b64 v[154:155], 10, v[146:147]
	v_lshl_add_u64 v[158:159], v[154:155], 0, v[144:145]
	v_lshlrev_b64 v[154:155], 1, v[158:159]
	v_lshl_add_u64 v[154:155], s[26:27], 0, v[154:155]
	v_lshl_add_u64 v[158:159], v[158:159], 2, s[74:75]
	s_mov_b32 s42, 0x8000
	s_mov_b32 s43, 0
	s_mov_b32 s44, 0x40000
	s_mov_b32 s45, 0
	s_mov_b32 s46, 0x10000
	s_mov_b32 s47, 0
	s_mov_b32 s48, 0x80000
	s_mov_b32 s49, 0
	v_lshl_add_u64 v[224:225], v[154:155], 0, s[44:45]
	global_load_dwordx4 v[160:163], v[154:155], off
	global_load_dwordx4 v[164:167], v[154:155], off offset:256
	v_lshl_add_u64 v[156:157], v[154:155], 0, s[42:43]
	global_load_dwordx4 v[168:171], v[156:157], off
	global_load_dwordx4 v[172:175], v[156:157], off offset:256
	v_lshl_add_u64 v[154:155], v[156:157], 0, s[42:43]
	global_load_dwordx4 v[176:179], v[154:155], off
	global_load_dwordx4 v[180:183], v[154:155], off offset:256
	v_lshl_add_u64 v[156:157], v[154:155], 0, s[42:43]
	global_load_dwordx4 v[184:187], v[156:157], off
	global_load_dwordx4 v[188:191], v[156:157], off offset:256
	global_load_dwordx4 v[192:195], v[224:225], off
	global_load_dwordx4 v[196:199], v[224:225], off offset:256
	v_lshl_add_u64 v[156:157], v[224:225], 0, s[42:43]
	global_load_dwordx4 v[200:203], v[156:157], off
	global_load_dwordx4 v[204:207], v[156:157], off offset:256
	v_lshl_add_u64 v[154:155], v[156:157], 0, s[42:43]
	global_load_dwordx4 v[208:211], v[154:155], off
	global_load_dwordx4 v[212:215], v[154:155], off offset:256
	v_lshl_add_u64 v[156:157], v[154:155], 0, s[42:43]
	global_load_dwordx4 v[216:219], v[156:157], off
	global_load_dwordx4 v[220:223], v[156:157], off offset:256
	s_and_b64 vcc, exec, s[12:13]
	s_cbranch_vccz .LBB0_1151
	s_barrier
